# attention unit body rewritten by hand around v_mfma_f32_16x16x32_bf16 (S^T = K Q^T, O^T = V^T P^T): no cross-lane softmax shuffles, row-major swizzled K/V LDS ring filled by HBM->LDS loads, own q-norm
# speedup vs baseline: 1.0921x; 1.0286x over previous
; __device__ __forceinline__ int crow(int r, int hi) { return (r & 3) + 8 * (r >> 2) + 4 * hi; }
; template <typename TQ> ...
;     ...
;   if (hi == 0) li_l[r32] = l_reg; asm volatile("s_waitcnt lgkmcnt(0)" ::: "memory");
;   float rli[16];
; #pragma unroll
;   for (int r = 0; r < 16; ++r) rli[r] = __builtin_amdgcn_rcpf(li_l[crow(r, hi)]);
;   int le = (int)(threadIdx.x & 63u); asm volatile("" : "+v"(le));
;   const int r32e = le & 31, hie = le >> 5;
;   bf16* Ow = Ob + (long)(wid * QBLK) * LDO;
; #pragma unroll
;   for (int r = 0; r < 16; ++r) { int orow = crow(r, hie);
;     for (int d0 = 0; d0 < 4; ++d0) Ow[(long)orow * LDO + d0 * 32 + r32e] = __float2bfloat16(o[d0][r] * rli[r]); }
; __global__ void __launch_bounds__(NTHR, 2) fwd_megakernel(KArgs a) {
;     ...
;     if (IN(9)) {
;         const int G = gridDim.x, bx = blockIdx.x; const int vcu = (G % 8 == 0) ? (bx % 8) * (G / 8) + bx / 8 : bx;
;         const int upb = (512 + G - 1) / G;
;         const att::bf16* Q = (const att::bf16*)(ws + WS_Q); const att::bf16* Kb = (const att::bf16*)(ws + WS_K); const att::bf16* Vb = (const att::bf16*)(ws + WS_V); att::bf16* O = (att::bf16*)(ws + WS_O);
;         float gqm = fmaxf(fabsf(a.g_q[lane]), fabsf(a.g_q[lane + 64])), gkm = fmaxf(fabsf(a.g_k[lane]), fabsf(a.g_k[lane + 64]));
; #pragma unroll
;         for (int o = 1; o < 64; o <<= 1) { gqm = fmaxf(gqm, __shfl_xor(gqm, o)); gkm = fmaxf(gkm, __shfl_xor(gkm, o)); }
;         const float mC = __uint_as_float(__builtin_amdgcn_readfirstlane(__float_as_uint(128.0f * gqm * gkm * (att::SCALE * 1.4426950408889634f))));
;         for (int i = 0; i < upb; ++i) {
;             const int unit = vcu * upb + i; if (unit >= 512) break;
;             const int grp = unit >> 7, rem = unit & 127, gq = rem >> 5, qb = rem & 31, b = grp >> 1, kvh = grp & 1, h = kvh * 4 + gq;
;             const size_t qoff = ((size_t)(b * SEQ + qb * 256)) * DM + h * 128, koff = (size_t)b * SKV * 256 + kvh * 128;
;             att::attn_dense_body<att::bf16>(Q + qoff, Kb + koff, Vb + koff, O + qoff, SKV, (char*)lds_raw, mC, a.g_q, (const float*)(ws + WS_ROPE), (const float*)(ws + WS_ROPE) + 4096, qb * 256);
.LBB0_815:
	v_lshlrev_b32_e32 v1, 2, v198
	global_load_dword v2, v1, s[26:27] offset:256
	global_load_dword v3, v1, s[26:27]
	global_load_dword v4, v1, s[28:29] offset:256
	global_load_dword v5, v1, s[28:29]
	v_mbcnt_lo_u32_b32 v1, -1, 0
	v_mbcnt_hi_u32_b32 v1, -1, v1
	v_and_b32_e32 v7, 64, v1
	v_xor_b32_e32 v8, 1, v1
	v_add_u32_e32 v7, 64, v7
	v_xor_b32_e32 v9, 2, v1
	v_cmp_lt_i32_e32 vcc, v8, v7
	v_xor_b32_e32 v10, 4, v1
	v_xor_b32_e32 v11, 8, v1
	v_cndmask_b32_e32 v8, v1, v8, vcc
	v_cmp_lt_i32_e32 vcc, v9, v7
	v_xor_b32_e32 v12, 16, v1
	v_xor_b32_e32 v13, 32, v1
	v_cndmask_b32_e32 v9, v1, v9, vcc
	v_cmp_lt_i32_e32 vcc, v10, v7
	s_abs_i32 s4, s94
	v_cvt_f32_u32_e32 v6, s4
	v_cndmask_b32_e32 v10, v1, v10, vcc
	v_cmp_lt_i32_e32 vcc, v11, v7
	s_sub_i32 s6, 0, s4
	v_rcp_iflag_f32_e32 v6, v6
	v_cndmask_b32_e32 v11, v1, v11, vcc
	v_cmp_lt_i32_e32 vcc, v12, v7
	s_add_i32 s1, s94, 0x1ff
	v_mul_f32_e32 v6, 0x4f7ffffe, v6
	v_cndmask_b32_e32 v12, v1, v12, vcc
	v_cmp_lt_i32_e32 vcc, v13, v7
	v_lshlrev_b32_e32 v7, 2, v8
	v_lshlrev_b32_e32 v8, 2, v9
	v_lshlrev_b32_e32 v9, 2, v10
	v_lshlrev_b32_e32 v10, 2, v11
	v_cvt_u32_f32_e32 v6, v6
	v_lshlrev_b32_e32 v11, 2, v12
	s_xor_b32 s5, s1, s94
	s_abs_i32 s1, s1
	v_readfirstlane_b32 s7, v6
	s_mul_i32 s6, s6, s7
	s_mul_hi_u32 s6, s7, s6
	s_add_i32 s7, s7, s6
	v_cndmask_b32_e32 v1, v1, v13, vcc
	s_mul_hi_u32 s6, s1, s7
	v_lshlrev_b32_e32 v1, 2, v1
	s_mul_i32 s7, s6, s4
	s_sub_i32 s1, s1, s7
	s_ashr_i32 s5, s5, 31
	s_add_i32 s8, s6, 1
	s_sub_i32 s7, s1, s4
	s_cmp_ge_u32 s1, s4
	s_cselect_b32 s6, s8, s6
	s_cselect_b32 s1, s7, s1
	s_add_i32 s7, s6, 1
	s_cmp_ge_u32 s1, s4
	s_cselect_b32 s1, s7, s6
	s_xor_b32 s1, s1, s5
	s_sub_i32 s66, s1, s5
	s_cmp_lt_i32 s66, 1
	s_waitcnt vmcnt(0)
	v_max_f32_e64 v2, |v2|, |v2|
	v_max_f32_e64 v3, |v3|, |v3|
	v_max_f32_e64 v4, |v4|, |v4|
	v_max_f32_e64 v5, |v5|, |v5|
	v_max_f32_e32 v2, v3, v2
	v_max_f32_e32 v3, v5, v4
	ds_bpermute_b32 v4, v7, v2
	ds_bpermute_b32 v5, v7, v3
	s_waitcnt lgkmcnt(1)
	v_max_f32_e32 v4, v4, v4
	s_waitcnt lgkmcnt(0)
	v_max_f32_e32 v5, v5, v5
	v_max_f32_e32 v2, v2, v4
	v_max_f32_e32 v3, v3, v5
	ds_bpermute_b32 v4, v8, v2
	ds_bpermute_b32 v5, v8, v3
	s_waitcnt lgkmcnt(1)
	v_max_f32_e32 v4, v4, v4
	s_waitcnt lgkmcnt(0)
	v_max_f32_e32 v5, v5, v5
	v_max_f32_e32 v2, v2, v4
	v_max_f32_e32 v3, v3, v5
	ds_bpermute_b32 v4, v9, v2
	ds_bpermute_b32 v5, v9, v3
	s_waitcnt lgkmcnt(1)
	v_max_f32_e32 v4, v4, v4
	s_waitcnt lgkmcnt(0)
	v_max_f32_e32 v5, v5, v5
	v_max_f32_e32 v2, v2, v4
	v_max_f32_e32 v3, v3, v5
	ds_bpermute_b32 v4, v10, v2
	ds_bpermute_b32 v5, v10, v3
	s_waitcnt lgkmcnt(1)
	v_max_f32_e32 v4, v4, v4
	s_waitcnt lgkmcnt(0)
	v_max_f32_e32 v5, v5, v5
	v_max_f32_e32 v2, v2, v4
	v_max_f32_e32 v3, v3, v5
	ds_bpermute_b32 v4, v11, v2
	ds_bpermute_b32 v5, v11, v3
	s_waitcnt lgkmcnt(1)
	v_max_f32_e32 v4, v4, v4
	s_waitcnt lgkmcnt(0)
	v_max_f32_e32 v5, v5, v5
	v_max_f32_e32 v2, v2, v4
	v_max_f32_e32 v3, v3, v5
	ds_bpermute_b32 v4, v1, v2
	ds_bpermute_b32 v5, v1, v3
	s_waitcnt lgkmcnt(1)
	v_max_f32_e32 v4, v4, v4
	s_waitcnt lgkmcnt(0)
	v_max_f32_e32 v5, v5, v5
	v_max_f32_e32 v2, v2, v4
	v_max_f32_e32 v3, v3, v5
	v_mul_f32_e32 v2, 0x43000000, v2
	v_mul_f32_e32 v2, v3, v2
	s_nop 0
	v_readfirstlane_b32 s1, v2
	s_cbranch_scc1 .LBB0_825
	s_add_u32 s67, s58, 0x7700000
	s_addc_u32 s68, s59, 0
	s_add_u32 s69, s58, 0x6e00000
	s_addc_u32 s70, s59, 0
	s_add_u32 s71, s58, 0x8000000
	s_addc_u32 s72, s59, 0
	s_add_u32 s4, s58, 0x180000
	s_addc_u32 s5, s59, 0
	s_add_u32 s6, s58, 0x184000
	s_addc_u32 s7, s59, 0
	v_mov_b32_e32 v2, 0xbe0293ee
	s_mul_i32 s73, s66, s0
	v_mul_f32_e32 v2, s1, v2
	s_add_u32 s8, s58, 0x771c000
	v_mov_b32_e32 v3, v2
	v_mov_b32_e32 v4, v2
	v_mov_b32_e32 v5, v2
	v_mov_b32_e32 v6, v2
	v_mov_b32_e32 v7, v2
	v_mov_b32_e32 v8, v2
	v_mov_b32_e32 v9, v2
	v_mov_b32_e32 v10, v2
	v_mov_b32_e32 v11, v2
	v_mov_b32_e32 v12, v2
	v_mov_b32_e32 v13, v2
	v_mov_b32_e32 v14, v2
	v_mov_b32_e32 v15, v2
	v_mov_b32_e32 v16, v2
	v_mov_b32_e32 v17, v2
	s_addc_u32 s9, s59, 0
	s_mov_b32 s74, 0
	s_movk_i32 s75, 0xffe0
	v_mov_b32_e32 v195, 0
	v_mov_b32_e32 v199, 0x358637bd
	s_mov_b32 s76, 0xf800000
	v_mov_b32_e32 v200, 0x260
	s_mov_b32 s77, 0x3e0293ee
	s_mov_b64 s[10:11], 0x8000
	s_mov_b64 s[24:25], 0xc000
	s_movk_i32 s78, 0x4000
	s_mov_b32 s79, 0xffff4000
	s_movk_i32 s80, 0x8000
	s_mov_b32 s81, 0xff6f4000
	s_mov_b32 s82, 0xff6f8000
	s_movk_i32 s83, 0xc000
	s_mov_b32 s86, 0xff6fc000
	s_mov_b32 s87, 0xff700000
	s_mov_b64 s[28:29], 0x10000
	s_mov_b64 s[30:31], 0x4000
	s_mov_b64 s[36:37], 0x4800
	s_mov_b64 s[38:39], 0x5000
	s_movk_i32 s88, 0x5000
	s_mov_b32 s89, 0x8000
	s_mov_b64 s[40:41], 0x8800
	s_mov_b64 s[42:43], 0x9000
	s_mov_b32 s91, 0x9000
	s_mov_b32 s92, 0xc000
	s_mov_b64 s[44:45], 0xc800
	s_mov_b64 s[46:47], 0xd000
	s_mov_b32 s93, 0xd000
	v_mov_b32_e32 v201, 0x420000
	s_mov_b32 s94, s73
	s_branch .LBB0_819
.LBB0_818:
	s_and_b64 vcc, exec, s[0:1]
	s_cbranch_vccnz .LBB0_824
; __device__ __forceinline__ int v_st(int k, int c) { const int kk = (k & ~0xC) | ((k & 4) << 1) | ((k & 8) >> 1); return ((kk >> 3) * 4 + (c >> 5)) * 512 + ((kk & 7) * 32 + (c & 31)) * 2; }
; __device__ __forceinline__ int v_rd_base(int lane) { return ((lane & 3) << 3) | (((lane >> 2) & 3) << 6) | (((lane >> 4) & 1) << 5) | (((lane >> 5) & 1) << 8); }
; #define SLOAD(i, k0) do { sr_[i].vs0 = St::ld8(&Vh[(long)((k0) + sr) * LDK + sc]); sr_[i].vs1 = St::ld8(&Vh[(long)((k0) + 32 + sr) * LDK + sc]); \
;     sr_[i].ks0 = St::ld8(&Kh[(long)((k0) + sr) * LDK + sc]); sr_[i].ks1 = St::ld8(&Kh[(long)((k0) + 32 + sr) * LDK + sc]); } while (0)
; template <typename TQ> ...
;     ...
;   const int tid = tid_, wid = __builtin_amdgcn_readfirstlane(tid >> 6), lane = tid & 63, r32 = lane & 31, hi = lane >> 5;
;   bf16* V_lds = (bf16*)lds; bf16* K_lds = (bf16*)(lds + 2 * SHM_V);
;   float* ws = (float*)(lds + 2 * SHM_V + 2 * SHM_K) + wid * 64; float* li_l = ws;
;   float l_reg = 0; f32x16 o[4] = {}; bf16x8 qr[8];
;   const TQ* Qw = Qb + (long)(wid * QBLK + r32) * LDQ + hi * 8;
; #pragma unroll
;   for (int d0 = 0; d0 < 8; ++d0) qr[d0] = SQ::tobf(SQ::ld8(Qw + d0 * 16));
;   const int sr = tid >> 4, sc = (tid & 15) * 8, vst0 = v_st(sr, sc), vst1 = v_st(32 + sr, sc);
;   const int vb0 = (int)(uintptr_t)V_lds + v_rd_base(lane);
;   struct { typename St::T vs0, vs1, ks0, ks1; } sr_[SDEPTH];
;     ...
;   constexpr int SE = 0, SO = SDEPTH - 1;
;   SLOAD(SE, 0);
.LBB0_819:
	s_add_i32 s12, s74, s73
	s_cmpk_gt_i32 s12, 0x1ff
	s_mov_b64 s[0:1], -1
	s_cbranch_scc1 .LBB0_818
	s_lshl_b32 s0, s94, 1
	s_ashr_i32 s96, s12, 8
	s_lshl_b32 s1, s12, 8
	s_and_b32 s95, s0, 0x100
	s_lshl_b32 s0, s96, 13
	s_and_b32 s33, s1, 0x1f00
	s_bfe_u32 s15, s12, 0x10007
	s_or_b32 s0, s0, s33
	s_lshl_b32 s12, s12, 2
	s_ashr_i32 s1, s0, 31
	s_lshl_b32 s13, s15, 9
	s_and_b32 s12, s12, 0x180
	s_lshl_b64 s[0:1], s[0:1], 10
	s_or_b32 s12, s13, s12
	s_or_b32 s0, s0, s12
	s_mul_i32 s12, s96, 0x210000
	s_lshl_b32 s15, s15, 7
	s_or_b32 s12, s12, s15
	s_lshl_b64 s[48:49], s[0:1], 1
	s_mul_hi_i32 s13, s96, 0x210000
	s_add_u32 s0, s20, s48
	s_addc_u32 s1, s21, s49
	s_lshl_b64 s[12:13], s[12:13], 1
	s_add_u32 s54, s69, s12
	s_addc_u32 s55, s70, s13
	v_mov_b32_e32 v114, v0
	s_add_u32 s64, s67, s12
	s_addc_u32 s65, s68, s13
	v_readfirstlane_b32 s53, v114
	s_lshr_b32 s15, s53, 6
	s_lshl_b32 s80, s15, 11
	s_add_u32 s79, s80, 0x10000
	s_lshl_b32 s52, s15, 5
	s_lshl_b32 s12, s15, 3
	v_and_b32_e32 v1, 63, v0
	v_and_b32_e32 v16, 15, v1
	v_lshrrev_b32_e32 v17, 4, v1
	v_add_u32_e32 v12, s12, v17
	v_and_b32_e32 v6, 15, v12
	v_xor_b32_e32 v6, v6, v16
	v_lshlrev_b32_e32 v6, 4, v6
	v_lshl_or_b32 v246, v12, 9, v6
	v_and_b32_e32 v6, 7, v12
	v_lshrrev_b32_e32 v7, 1, v16
	v_xor_b32_e32 v6, v6, v7
	v_and_b32_e32 v7, 1, v16
	v_lshl_or_b32 v6, v6, 1, v7
	v_lshlrev_b32_e32 v6, 4, v6
	v_lshl_or_b32 v248, v12, 9, v6
	v_add_u32_e32 v12, s12, v17
	v_add_u32_e32 v12, 4, v12
	v_and_b32_e32 v6, 15, v12
	v_xor_b32_e32 v6, v6, v16
	v_lshlrev_b32_e32 v6, 4, v6
	v_lshl_or_b32 v247, v12, 9, v6
	v_and_b32_e32 v6, 7, v12
	v_lshrrev_b32_e32 v7, 1, v16
	v_xor_b32_e32 v6, v6, v7
	v_and_b32_e32 v7, 1, v16
	v_lshl_or_b32 v6, v6, 1, v7
	v_lshlrev_b32_e32 v6, 4, v6
	v_lshl_or_b32 v249, v12, 9, v6
	s_mov_b32 s98, s54
	s_mov_b32 s99, s55
	s_mov_b32 s100, s64
	s_mov_b32 s101, s65
	s_add_u32 m0, s79, 0
	s_nop 0
	global_load_lds_dwordx4 v246, s[98:99]
	s_add_u32 m0, s79, 1024
	s_nop 0
	global_load_lds_dwordx4 v247, s[98:99]
	s_add_u32 m0, s80, 0
	s_nop 0
	global_load_lds_dwordx4 v248, s[100:101]
	s_add_u32 m0, s80, 1024
	s_nop 0
	global_load_lds_dwordx4 v249, s[100:101]
	s_add_u32 s98, s98, 0x8000
	s_addc_u32 s99, s99, 0
	s_add_u32 s100, s100, 0x8000
	s_addc_u32 s101, s101, 0
	s_add_u32 m0, s79, 16384
	s_nop 0
	global_load_lds_dwordx4 v246, s[98:99]
	s_add_u32 m0, s79, 17408
	s_nop 0
	global_load_lds_dwordx4 v247, s[98:99]
	s_add_u32 m0, s80, 16384
	s_nop 0
	global_load_lds_dwordx4 v248, s[100:101]
	s_add_u32 m0, s80, 17408
	s_nop 0
	global_load_lds_dwordx4 v249, s[100:101]
	s_add_u32 s98, s98, 0x8000
	s_addc_u32 s99, s99, 0
	s_add_u32 s100, s100, 0x8000
	s_addc_u32 s101, s101, 0
	s_add_u32 m0, s79, 32768
	s_nop 0
	global_load_lds_dwordx4 v246, s[98:99]
	s_add_u32 m0, s79, 33792
	s_nop 0
	global_load_lds_dwordx4 v247, s[98:99]
	s_add_u32 m0, s80, 32768
	s_nop 0
	global_load_lds_dwordx4 v248, s[100:101]
	s_add_u32 m0, s80, 33792
	s_nop 0
	global_load_lds_dwordx4 v249, s[100:101]
	s_add_u32 s98, s98, 0x8000
	s_addc_u32 s99, s99, 0
	s_add_u32 m0, s79, 49152
	s_nop 0
	global_load_lds_dwordx4 v246, s[98:99]
	s_add_u32 m0, s79, 50176
	s_nop 0
	global_load_lds_dwordx4 v247, s[98:99]
	v_add_u32_e32 v6, s52, v16
	v_lshlrev_b32_e32 v6, 11, v6
	v_lshl_or_b32 v13, v17, 4, v6
	v_add_u32_e32 v14, 0x8000, v13
	global_load_dwordx4 v[146:149], v13, s[0:1] offset:0
	global_load_dwordx4 v[150:153], v13, s[0:1] offset:64
	global_load_dwordx4 v[154:157], v13, s[0:1] offset:128
	global_load_dwordx4 v[158:161], v13, s[0:1] offset:192
	global_load_dwordx4 v[162:165], v14, s[0:1] offset:0
	global_load_dwordx4 v[166:169], v14, s[0:1] offset:64
	global_load_dwordx4 v[170:173], v14, s[0:1] offset:128
	global_load_dwordx4 v[174:177], v14, s[0:1] offset:192
	v_lshlrev_b32_e32 v15, 5, v17
	global_load_dwordx4 v[18:21], v15, s[26:27] offset:0
	global_load_dwordx4 v[22:25], v15, s[26:27] offset:16
	global_load_dwordx4 v[26:29], v15, s[26:27] offset:128
	global_load_dwordx4 v[30:33], v15, s[26:27] offset:144
	global_load_dwordx4 v[34:37], v15, s[26:27] offset:256
	global_load_dwordx4 v[38:41], v15, s[26:27] offset:272
	global_load_dwordx4 v[42:45], v15, s[26:27] offset:384
	global_load_dwordx4 v[46:49], v15, s[26:27] offset:400
	s_add_u32 s13, s33, s52
	s_lshr_b32 s13, s13, 6
	s_lshl_b32 s13, s13, 7
	v_add_u32_e32 v200, s13, v15
	global_load_dwordx4 v[82:85], v200, s[4:5] offset:0
	global_load_dwordx4 v[90:93], v200, s[6:7] offset:0
	global_load_dwordx4 v[86:89], v200, s[4:5] offset:16
	global_load_dwordx4 v[94:97], v200, s[6:7] offset:16
	v_add_u32_e32 v6, s52, v16
	v_and_b32_e32 v6, 63, v6
	v_lshl_or_b32 v200, v6, 7, v15
	global_load_dwordx4 v[98:101], v200, s[4:5] offset:0
	global_load_dwordx4 v[106:109], v200, s[6:7] offset:0
	global_load_dwordx4 v[102:105], v200, s[4:5] offset:16
	global_load_dwordx4 v[110:113], v200, s[6:7] offset:16
	v_add_u32_e32 v6, s52, v16
	v_add_u32_e32 v6, 16, v6
	v_and_b32_e32 v6, 63, v6
	v_lshl_or_b32 v200, v6, 7, v15
	global_load_dwordx4 v[114:117], v200, s[4:5] offset:0
	global_load_dwordx4 v[122:125], v200, s[6:7] offset:0
	global_load_dwordx4 v[118:121], v200, s[4:5] offset:16
	global_load_dwordx4 v[126:129], v200, s[6:7] offset:16
	v_lshlrev_b32_e32 v7, 8, v16
	v_or_b32_e32 v6, 0, v17
	v_xor_b32_e32 v6, v6, v16
	v_lshl_or_b32 v6, v6, 4, v7
	v_add_u32_e32 v234, 0x10000, v6
	v_or_b32_e32 v6, 4, v17
	v_xor_b32_e32 v6, v6, v16
	v_lshl_or_b32 v6, v6, 4, v7
	v_add_u32_e32 v235, 0x10000, v6
	v_or_b32_e32 v6, 8, v17
	v_xor_b32_e32 v6, v6, v16
	v_lshl_or_b32 v6, v6, 4, v7
	v_add_u32_e32 v236, 0x10000, v6
	v_or_b32_e32 v6, 12, v17
	v_xor_b32_e32 v6, v6, v16
	v_lshl_or_b32 v6, v6, 4, v7
	v_add_u32_e32 v237, 0x10000, v6
	v_bfe_u32 v6, v1, 2, 2
	v_lshl_or_b32 v6, v17, 2, v6
	v_and_b32_e32 v201, 7, v6
	v_and_b32_e32 v7, 3, v1
	v_lshlrev_b32_e32 v7, 3, v7
	v_lshl_or_b32 v7, v6, 8, v7
	v_xor_b32_e32 v12, 0, v201
	v_lshl_or_b32 v238, v12, 5, v7
	v_xor_b32_e32 v12, 1, v201
	v_lshl_or_b32 v239, v12, 5, v7
	v_xor_b32_e32 v12, 2, v201
	v_lshl_or_b32 v240, v12, 5, v7
	v_xor_b32_e32 v12, 3, v201
	v_lshl_or_b32 v241, v12, 5, v7
	v_xor_b32_e32 v12, 4, v201
	v_lshl_or_b32 v242, v12, 5, v7
	v_xor_b32_e32 v12, 5, v201
	v_lshl_or_b32 v243, v12, 5, v7
	v_xor_b32_e32 v12, 6, v201
	v_lshl_or_b32 v244, v12, 5, v7
	v_xor_b32_e32 v12, 7, v201
	v_lshl_or_b32 v245, v12, 5, v7
	s_waitcnt vmcnt(0)
; #define QF(d, e) __uint_as_float(((unsigned)(unsigned short)qr[d][e]) << 16)
; template <typename TQ> ...
;     ...
;   {
;     float ss = 0.f;
;     ...
; #pragma unroll
;     for (int d0 = 0; d0 < 8; ++d0)
; #pragma unroll
;       for (int e = 0; e < 8; ++e) { const float x = QF(d0, e); ss += x * x; }
;     ss += __shfl_xor(ss, 32);
;     const float rn = (SCALE * 1.4426950408889634f) / sqrtf(ss * (1.0f / 128.0f) + 1e-6f);
;     const int t = trow0 + wid * QBLK + r32; const int prow = t >> 6, pcol = t & 63;
; #pragma unroll
;     for (int hf = 0; hf < 2; ++hf)
; #pragma unroll
;       for (int dd = 0; dd < 2; ++dd) {
;         const int dl = 4 * hf + dd, du = dl + 2;
;         const int f0 = 16 * dd + 8 * hi;
;         const float* cp = rc + (hf ? pcol : prow) * 32 + f0; const float* sp = rsn + (hf ? pcol : prow) * 32 + f0;
;         const float* gl = gq + 16 * dl + 8 * hi; const float* gu = gq + 16 * du + 8 * hi;
;         unsigned wl[4], wu[4];
; #pragma unroll
;         for (int e = 0; e < 8; e += 2) {
;           float o1[2], o2[2];
; #pragma unroll
;           for (int k = 0; k < 2; ++k) { const float x1 = QF(dl, e + k) * rn * gl[e + k], x2 = QF(du, e + k) * rn * gu[e + k]; const float c = cp[e + k], sn = sp[e + k];
;             o1[k] = x1 * c - x2 * sn; o2[k] = x2 * c + x1 * sn; }
;           wl[e >> 1] = cvtpk(o1[0], o1[1]); wu[e >> 1] = cvtpk(o2[0], o2[1]);
;         }
;         u32x4 vl = {wl[0], wl[1], wl[2], wl[3]}, vu = {wu[0], wu[1], wu[2], wu[3]};
;         qr[dl] = *reinterpret_cast<bf16x8*>(&vl); qr[du] = *reinterpret_cast<bf16x8*>(&vu);
;       }
	v_lshlrev_b32_e32 v50, 16, v146
	v_and_b32_e32 v51, 0xffff0000, v146
	v_lshlrev_b32_e32 v52, 16, v147
	v_and_b32_e32 v53, 0xffff0000, v147
	v_lshlrev_b32_e32 v54, 16, v148
	v_and_b32_e32 v55, 0xffff0000, v148
	v_lshlrev_b32_e32 v56, 16, v149
	v_and_b32_e32 v57, 0xffff0000, v149
	v_lshlrev_b32_e32 v58, 16, v150
	v_and_b32_e32 v59, 0xffff0000, v150
	v_lshlrev_b32_e32 v60, 16, v151
	v_and_b32_e32 v61, 0xffff0000, v151
	v_lshlrev_b32_e32 v62, 16, v152
	v_and_b32_e32 v63, 0xffff0000, v152
	v_lshlrev_b32_e32 v64, 16, v153
	v_and_b32_e32 v65, 0xffff0000, v153
	v_lshlrev_b32_e32 v66, 16, v154
	v_and_b32_e32 v67, 0xffff0000, v154
	v_lshlrev_b32_e32 v68, 16, v155
	v_and_b32_e32 v69, 0xffff0000, v155
	v_lshlrev_b32_e32 v70, 16, v156
	v_and_b32_e32 v71, 0xffff0000, v156
	v_lshlrev_b32_e32 v72, 16, v157
	v_and_b32_e32 v73, 0xffff0000, v157
	v_lshlrev_b32_e32 v74, 16, v158
	v_and_b32_e32 v75, 0xffff0000, v158
	v_lshlrev_b32_e32 v76, 16, v159
	v_and_b32_e32 v77, 0xffff0000, v159
	v_lshlrev_b32_e32 v78, 16, v160
	v_and_b32_e32 v79, 0xffff0000, v160
	v_lshlrev_b32_e32 v80, 16, v161
	v_and_b32_e32 v81, 0xffff0000, v161
	v_mul_f32_e32 v130, v50, v50
	v_fmac_f32_e32 v130, v51, v51
	v_fmac_f32_e32 v130, v52, v52
	v_fmac_f32_e32 v130, v53, v53
	v_fmac_f32_e32 v130, v54, v54
	v_fmac_f32_e32 v130, v55, v55
	v_fmac_f32_e32 v130, v56, v56
	v_fmac_f32_e32 v130, v57, v57
	v_fmac_f32_e32 v130, v58, v58
	v_fmac_f32_e32 v130, v59, v59
	v_fmac_f32_e32 v130, v60, v60
	v_fmac_f32_e32 v130, v61, v61
	v_fmac_f32_e32 v130, v62, v62
	v_fmac_f32_e32 v130, v63, v63
	v_fmac_f32_e32 v130, v64, v64
	v_fmac_f32_e32 v130, v65, v65
	v_fmac_f32_e32 v130, v66, v66
	v_fmac_f32_e32 v130, v67, v67
	v_fmac_f32_e32 v130, v68, v68
	v_fmac_f32_e32 v130, v69, v69
	v_fmac_f32_e32 v130, v70, v70
	v_fmac_f32_e32 v130, v71, v71
	v_fmac_f32_e32 v130, v72, v72
	v_fmac_f32_e32 v130, v73, v73
	v_fmac_f32_e32 v130, v74, v74
	v_fmac_f32_e32 v130, v75, v75
	v_fmac_f32_e32 v130, v76, v76
	v_fmac_f32_e32 v130, v77, v77
	v_fmac_f32_e32 v130, v78, v78
	v_fmac_f32_e32 v130, v79, v79
	v_fmac_f32_e32 v130, v80, v80
	v_fmac_f32_e32 v130, v81, v81
	ds_swizzle_b32 v132, v130 offset:swizzle(SWAP,16)
	s_waitcnt lgkmcnt(0)
	v_add_f32_e32 v130, v130, v132
	v_mov_b32_e32 v132, v130
	s_nop 1
	v_permlane32_swap_b32_e32 v130, v132
	v_add_f32_e32 v130, v130, v132
	v_fmamk_f32 v130, v130, 0x3c000000, v199
	v_rsq_f32_e32 v130, v130
	s_nop 0
	v_mul_f32_e32 v131, s77, v130
	v_mul_f32_e32 v50, v50, v131
	v_mul_f32_e32 v50, v50, v18
	v_mul_f32_e32 v51, v51, v131
	v_mul_f32_e32 v51, v51, v19
	v_mul_f32_e32 v52, v52, v131
	v_mul_f32_e32 v52, v52, v20
	v_mul_f32_e32 v53, v53, v131
	v_mul_f32_e32 v53, v53, v21
	v_mul_f32_e32 v54, v54, v131
	v_mul_f32_e32 v54, v54, v22
	v_mul_f32_e32 v55, v55, v131
	v_mul_f32_e32 v55, v55, v23
	v_mul_f32_e32 v56, v56, v131
	v_mul_f32_e32 v56, v56, v24
	v_mul_f32_e32 v57, v57, v131
	v_mul_f32_e32 v57, v57, v25
	v_mul_f32_e32 v58, v58, v131
	v_mul_f32_e32 v58, v58, v26
	v_mul_f32_e32 v59, v59, v131
	v_mul_f32_e32 v59, v59, v27
	v_mul_f32_e32 v60, v60, v131
	v_mul_f32_e32 v60, v60, v28
	v_mul_f32_e32 v61, v61, v131
	v_mul_f32_e32 v61, v61, v29
	v_mul_f32_e32 v62, v62, v131
	v_mul_f32_e32 v62, v62, v30
	v_mul_f32_e32 v63, v63, v131
	v_mul_f32_e32 v63, v63, v31
	v_mul_f32_e32 v64, v64, v131
	v_mul_f32_e32 v64, v64, v32
	v_mul_f32_e32 v65, v65, v131
	v_mul_f32_e32 v65, v65, v33
	v_mul_f32_e32 v66, v66, v131
	v_mul_f32_e32 v66, v66, v34
	v_mul_f32_e32 v67, v67, v131
	v_mul_f32_e32 v67, v67, v35
	v_mul_f32_e32 v68, v68, v131
	v_mul_f32_e32 v68, v68, v36
	v_mul_f32_e32 v69, v69, v131
	v_mul_f32_e32 v69, v69, v37
	v_mul_f32_e32 v70, v70, v131
	v_mul_f32_e32 v70, v70, v38
	v_mul_f32_e32 v71, v71, v131
	v_mul_f32_e32 v71, v71, v39
	v_mul_f32_e32 v72, v72, v131
	v_mul_f32_e32 v72, v72, v40
	v_mul_f32_e32 v73, v73, v131
	v_mul_f32_e32 v73, v73, v41
	v_mul_f32_e32 v74, v74, v131
	v_mul_f32_e32 v74, v74, v42
	v_mul_f32_e32 v75, v75, v131
	v_mul_f32_e32 v75, v75, v43
	v_mul_f32_e32 v76, v76, v131
	v_mul_f32_e32 v76, v76, v44
	v_mul_f32_e32 v77, v77, v131
	v_mul_f32_e32 v77, v77, v45
	v_mul_f32_e32 v78, v78, v131
	v_mul_f32_e32 v78, v78, v46
	v_mul_f32_e32 v79, v79, v131
	v_mul_f32_e32 v79, v79, v47
	v_mul_f32_e32 v80, v80, v131
	v_mul_f32_e32 v80, v80, v48
	v_mul_f32_e32 v81, v81, v131
	v_mul_f32_e32 v81, v81, v49
	v_mul_f32_e32 v133, v58, v90
	v_mul_f32_e32 v134, v50, v90
	v_fma_f32 v50, v50, v82, -v133
	v_fma_f32 v58, v58, v82, v134
	v_mul_f32_e32 v133, v59, v91
	v_mul_f32_e32 v134, v51, v91
	v_fma_f32 v51, v51, v83, -v133
	v_fma_f32 v59, v59, v83, v134
	v_mul_f32_e32 v133, v60, v92
	v_mul_f32_e32 v134, v52, v92
	v_fma_f32 v52, v52, v84, -v133
	v_fma_f32 v60, v60, v84, v134
	v_mul_f32_e32 v133, v61, v93
	v_mul_f32_e32 v134, v53, v93
	v_fma_f32 v53, v53, v85, -v133
	v_fma_f32 v61, v61, v85, v134
	v_mul_f32_e32 v133, v62, v94
	v_mul_f32_e32 v134, v54, v94
	v_fma_f32 v54, v54, v86, -v133
	v_fma_f32 v62, v62, v86, v134
	v_mul_f32_e32 v133, v63, v95
	v_mul_f32_e32 v134, v55, v95
	v_fma_f32 v55, v55, v87, -v133
	v_fma_f32 v63, v63, v87, v134
	v_mul_f32_e32 v133, v64, v96
	v_mul_f32_e32 v134, v56, v96
	v_fma_f32 v56, v56, v88, -v133
	v_fma_f32 v64, v64, v88, v134
	v_mul_f32_e32 v133, v65, v97
	v_mul_f32_e32 v134, v57, v97
	v_fma_f32 v57, v57, v89, -v133
	v_fma_f32 v65, v65, v89, v134
	v_mul_f32_e32 v133, v74, v106
	v_mul_f32_e32 v134, v66, v106
	v_fma_f32 v66, v66, v98, -v133
	v_fma_f32 v74, v74, v98, v134
	v_mul_f32_e32 v133, v75, v107
	v_mul_f32_e32 v134, v67, v107
	v_fma_f32 v67, v67, v99, -v133
	v_fma_f32 v75, v75, v99, v134
	v_mul_f32_e32 v133, v76, v108
	v_mul_f32_e32 v134, v68, v108
	v_fma_f32 v68, v68, v100, -v133
; #define QF(d, e) __uint_as_float(((unsigned)(unsigned short)qr[d][e]) << 16)
; template <typename TQ> ...
;     ...
;     float ss = 0.f;
;     ...
; #pragma unroll
;     for (int d0 = 0; d0 < 8; ++d0)
; #pragma unroll
;       for (int e = 0; e < 8; ++e) { const float x = QF(d0, e); ss += x * x; }
;     ss += __shfl_xor(ss, 32);
;     const float rn = (SCALE * 1.4426950408889634f) / sqrtf(ss * (1.0f / 128.0f) + 1e-6f);
;     const int t = trow0 + wid * QBLK + r32; const int prow = t >> 6, pcol = t & 63;
; #pragma unroll
;     for (int hf = 0; hf < 2; ++hf)
; #pragma unroll
;       for (int dd = 0; dd < 2; ++dd) {
;         const int dl = 4 * hf + dd, du = dl + 2;
;         const int f0 = 16 * dd + 8 * hi;
;         const float* cp = rc + (hf ? pcol : prow) * 32 + f0; const float* sp = rsn + (hf ? pcol : prow) * 32 + f0;
;         const float* gl = gq + 16 * dl + 8 * hi; const float* gu = gq + 16 * du + 8 * hi;
;         unsigned wl[4], wu[4];
; #pragma unroll
;         for (int e = 0; e < 8; e += 2) {
;           float o1[2], o2[2];
; #pragma unroll
;           for (int k = 0; k < 2; ++k) { const float x1 = QF(dl, e + k) * rn * gl[e + k], x2 = QF(du, e + k) * rn * gu[e + k]; const float c = cp[e + k], sn = sp[e + k];
;             o1[k] = x1 * c - x2 * sn; o2[k] = x2 * c + x1 * sn; }
;           wl[e >> 1] = cvtpk(o1[0], o1[1]); wu[e >> 1] = cvtpk(o2[0], o2[1]);
;         }
;         u32x4 vl = {wl[0], wl[1], wl[2], wl[3]}, vu = {wu[0], wu[1], wu[2], wu[3]};
;         qr[dl] = *reinterpret_cast<bf16x8*>(&vl); qr[du] = *reinterpret_cast<bf16x8*>(&vu);
	v_fma_f32 v76, v76, v100, v134
	v_mul_f32_e32 v133, v77, v109
	v_mul_f32_e32 v134, v69, v109
	v_fma_f32 v69, v69, v101, -v133
	v_fma_f32 v77, v77, v101, v134
	v_mul_f32_e32 v133, v78, v110
	v_mul_f32_e32 v134, v70, v110
	v_fma_f32 v70, v70, v102, -v133
	v_fma_f32 v78, v78, v102, v134
	v_mul_f32_e32 v133, v79, v111
	v_mul_f32_e32 v134, v71, v111
	v_fma_f32 v71, v71, v103, -v133
	v_fma_f32 v79, v79, v103, v134
	v_mul_f32_e32 v133, v80, v112
	v_mul_f32_e32 v134, v72, v112
	v_fma_f32 v72, v72, v104, -v133
	v_fma_f32 v80, v80, v104, v134
	v_mul_f32_e32 v133, v81, v113
	v_mul_f32_e32 v134, v73, v113
	v_fma_f32 v73, v73, v105, -v133
	v_fma_f32 v81, v81, v105, v134
	v_cvt_pk_bf16_f32 v146, v50, v51
	v_cvt_pk_bf16_f32 v147, v52, v53
	v_cvt_pk_bf16_f32 v148, v54, v55
	v_cvt_pk_bf16_f32 v149, v56, v57
	v_cvt_pk_bf16_f32 v150, v58, v59
	v_cvt_pk_bf16_f32 v151, v60, v61
	v_cvt_pk_bf16_f32 v152, v62, v63
	v_cvt_pk_bf16_f32 v153, v64, v65
	v_cvt_pk_bf16_f32 v154, v66, v67
	v_cvt_pk_bf16_f32 v155, v68, v69
	v_cvt_pk_bf16_f32 v156, v70, v71
	v_cvt_pk_bf16_f32 v157, v72, v73
	v_cvt_pk_bf16_f32 v158, v74, v75
	v_cvt_pk_bf16_f32 v159, v76, v77
	v_cvt_pk_bf16_f32 v160, v78, v79
	v_cvt_pk_bf16_f32 v161, v80, v81
	v_lshlrev_b32_e32 v50, 16, v162
	v_and_b32_e32 v51, 0xffff0000, v162
	v_lshlrev_b32_e32 v52, 16, v163
	v_and_b32_e32 v53, 0xffff0000, v163
	v_lshlrev_b32_e32 v54, 16, v164
	v_and_b32_e32 v55, 0xffff0000, v164
	v_lshlrev_b32_e32 v56, 16, v165
	v_and_b32_e32 v57, 0xffff0000, v165
	v_lshlrev_b32_e32 v58, 16, v166
	v_and_b32_e32 v59, 0xffff0000, v166
	v_lshlrev_b32_e32 v60, 16, v167
	v_and_b32_e32 v61, 0xffff0000, v167
	v_lshlrev_b32_e32 v62, 16, v168
	v_and_b32_e32 v63, 0xffff0000, v168
	v_lshlrev_b32_e32 v64, 16, v169
	v_and_b32_e32 v65, 0xffff0000, v169
	v_lshlrev_b32_e32 v66, 16, v170
	v_and_b32_e32 v67, 0xffff0000, v170
	v_lshlrev_b32_e32 v68, 16, v171
	v_and_b32_e32 v69, 0xffff0000, v171
	v_lshlrev_b32_e32 v70, 16, v172
	v_and_b32_e32 v71, 0xffff0000, v172
	v_lshlrev_b32_e32 v72, 16, v173
	v_and_b32_e32 v73, 0xffff0000, v173
	v_lshlrev_b32_e32 v74, 16, v174
	v_and_b32_e32 v75, 0xffff0000, v174
	v_lshlrev_b32_e32 v76, 16, v175
	v_and_b32_e32 v77, 0xffff0000, v175
	v_lshlrev_b32_e32 v78, 16, v176
	v_and_b32_e32 v79, 0xffff0000, v176
	v_lshlrev_b32_e32 v80, 16, v177
	v_and_b32_e32 v81, 0xffff0000, v177
	v_mul_f32_e32 v130, v50, v50
	v_fmac_f32_e32 v130, v51, v51
	v_fmac_f32_e32 v130, v52, v52
	v_fmac_f32_e32 v130, v53, v53
	v_fmac_f32_e32 v130, v54, v54
	v_fmac_f32_e32 v130, v55, v55
	v_fmac_f32_e32 v130, v56, v56
	v_fmac_f32_e32 v130, v57, v57
	v_fmac_f32_e32 v130, v58, v58
	v_fmac_f32_e32 v130, v59, v59
	v_fmac_f32_e32 v130, v60, v60
	v_fmac_f32_e32 v130, v61, v61
	v_fmac_f32_e32 v130, v62, v62
	v_fmac_f32_e32 v130, v63, v63
	v_fmac_f32_e32 v130, v64, v64
	v_fmac_f32_e32 v130, v65, v65
	v_fmac_f32_e32 v130, v66, v66
	v_fmac_f32_e32 v130, v67, v67
	v_fmac_f32_e32 v130, v68, v68
	v_fmac_f32_e32 v130, v69, v69
	v_fmac_f32_e32 v130, v70, v70
	v_fmac_f32_e32 v130, v71, v71
	v_fmac_f32_e32 v130, v72, v72
	v_fmac_f32_e32 v130, v73, v73
	v_fmac_f32_e32 v130, v74, v74
	v_fmac_f32_e32 v130, v75, v75
	v_fmac_f32_e32 v130, v76, v76
	v_fmac_f32_e32 v130, v77, v77
	v_fmac_f32_e32 v130, v78, v78
	v_fmac_f32_e32 v130, v79, v79
	v_fmac_f32_e32 v130, v80, v80
	v_fmac_f32_e32 v130, v81, v81
	ds_swizzle_b32 v132, v130 offset:swizzle(SWAP,16)
	s_waitcnt lgkmcnt(0)
	v_add_f32_e32 v130, v130, v132
	v_mov_b32_e32 v132, v130
	s_nop 1
	v_permlane32_swap_b32_e32 v130, v132
	v_add_f32_e32 v130, v130, v132
	v_fmamk_f32 v130, v130, 0x3c000000, v199
	v_rsq_f32_e32 v130, v130
	s_nop 0
	v_mul_f32_e32 v131, s77, v130
	v_mul_f32_e32 v50, v50, v131
	v_mul_f32_e32 v50, v50, v18
	v_mul_f32_e32 v51, v51, v131
	v_mul_f32_e32 v51, v51, v19
	v_mul_f32_e32 v52, v52, v131
	v_mul_f32_e32 v52, v52, v20
	v_mul_f32_e32 v53, v53, v131
	v_mul_f32_e32 v53, v53, v21
	v_mul_f32_e32 v54, v54, v131
	v_mul_f32_e32 v54, v54, v22
	v_mul_f32_e32 v55, v55, v131
	v_mul_f32_e32 v55, v55, v23
	v_mul_f32_e32 v56, v56, v131
	v_mul_f32_e32 v56, v56, v24
	v_mul_f32_e32 v57, v57, v131
	v_mul_f32_e32 v57, v57, v25
	v_mul_f32_e32 v58, v58, v131
	v_mul_f32_e32 v58, v58, v26
	v_mul_f32_e32 v59, v59, v131
	v_mul_f32_e32 v59, v59, v27
	v_mul_f32_e32 v60, v60, v131
	v_mul_f32_e32 v60, v60, v28
	v_mul_f32_e32 v61, v61, v131
	v_mul_f32_e32 v61, v61, v29
	v_mul_f32_e32 v62, v62, v131
	v_mul_f32_e32 v62, v62, v30
	v_mul_f32_e32 v63, v63, v131
	v_mul_f32_e32 v63, v63, v31
	v_mul_f32_e32 v64, v64, v131
	v_mul_f32_e32 v64, v64, v32
	v_mul_f32_e32 v65, v65, v131
	v_mul_f32_e32 v65, v65, v33
	v_mul_f32_e32 v66, v66, v131
	v_mul_f32_e32 v66, v66, v34
	v_mul_f32_e32 v67, v67, v131
	v_mul_f32_e32 v67, v67, v35
	v_mul_f32_e32 v68, v68, v131
	v_mul_f32_e32 v68, v68, v36
	v_mul_f32_e32 v69, v69, v131
	v_mul_f32_e32 v69, v69, v37
	v_mul_f32_e32 v70, v70, v131
	v_mul_f32_e32 v70, v70, v38
	v_mul_f32_e32 v71, v71, v131
	v_mul_f32_e32 v71, v71, v39
	v_mul_f32_e32 v72, v72, v131
	v_mul_f32_e32 v72, v72, v40
	v_mul_f32_e32 v73, v73, v131
	v_mul_f32_e32 v73, v73, v41
	v_mul_f32_e32 v74, v74, v131
	v_mul_f32_e32 v74, v74, v42
	v_mul_f32_e32 v75, v75, v131
	v_mul_f32_e32 v75, v75, v43
	v_mul_f32_e32 v76, v76, v131
	v_mul_f32_e32 v76, v76, v44
	v_mul_f32_e32 v77, v77, v131
	v_mul_f32_e32 v77, v77, v45
	v_mul_f32_e32 v78, v78, v131
	v_mul_f32_e32 v78, v78, v46
	v_mul_f32_e32 v79, v79, v131
	v_mul_f32_e32 v79, v79, v47
	v_mul_f32_e32 v80, v80, v131
	v_mul_f32_e32 v80, v80, v48
	v_mul_f32_e32 v81, v81, v131
	v_mul_f32_e32 v81, v81, v49
	v_mul_f32_e32 v133, v58, v90
	v_mul_f32_e32 v134, v50, v90
	v_fma_f32 v50, v50, v82, -v133
	v_fma_f32 v58, v58, v82, v134
; #define SBAR() __builtin_amdgcn_sched_barrier(0)
; #define QF(d, e) __uint_as_float(((unsigned)(unsigned short)qr[d][e]) << 16)
; template <typename TQ> ...
;     ...
;           for (int k = 0; k < 2; ++k) { const float x1 = QF(dl, e + k) * rn * gl[e + k], x2 = QF(du, e + k) * rn * gu[e + k]; const float c = cp[e + k], sn = sp[e + k];
;             o1[k] = x1 * c - x2 * sn; o2[k] = x2 * c + x1 * sn; }
;           wl[e >> 1] = cvtpk(o1[0], o1[1]); wu[e >> 1] = cvtpk(o2[0], o2[1]);
;         }
;         u32x4 vl = {wl[0], wl[1], wl[2], wl[3]}, vu = {wu[0], wu[1], wu[2], wu[3]};
;         qr[dl] = *reinterpret_cast<bf16x8*>(&vl); qr[du] = *reinterpret_cast<bf16x8*>(&vu);
;       }
;   }
;     ...
;   SBAR();
;   f32x16 pA0, pA1, pB0, pB1; bf16x8 pa0, pa1, pa2, pa3; const int NT = seq / KVBLK;
;   f32x16 negm;
; #pragma unroll
;   for (int r = 0; r < 16; ++r) negm[r] = -mC;
;   asm volatile("" : "+v"(negm));
;   asm volatile("s_waitcnt vmcnt(0)" ::: "memory"); SWRITE(0, SE); __syncthreads();
;   qkt(pA0, pA1, K_lds, qr, r32, hi, negm); partialSM(pA0, pA1, mC);
	v_mul_f32_e32 v133, v59, v91
	v_mul_f32_e32 v134, v51, v91
	v_fma_f32 v51, v51, v83, -v133
	v_fma_f32 v59, v59, v83, v134
	v_mul_f32_e32 v133, v60, v92
	v_mul_f32_e32 v134, v52, v92
	v_fma_f32 v52, v52, v84, -v133
	v_fma_f32 v60, v60, v84, v134
	v_mul_f32_e32 v133, v61, v93
	v_mul_f32_e32 v134, v53, v93
	v_fma_f32 v53, v53, v85, -v133
	v_fma_f32 v61, v61, v85, v134
	v_mul_f32_e32 v133, v62, v94
	v_mul_f32_e32 v134, v54, v94
	v_fma_f32 v54, v54, v86, -v133
	v_fma_f32 v62, v62, v86, v134
	v_mul_f32_e32 v133, v63, v95
	v_mul_f32_e32 v134, v55, v95
	v_fma_f32 v55, v55, v87, -v133
	v_fma_f32 v63, v63, v87, v134
	v_mul_f32_e32 v133, v64, v96
	v_mul_f32_e32 v134, v56, v96
	v_fma_f32 v56, v56, v88, -v133
	v_fma_f32 v64, v64, v88, v134
	v_mul_f32_e32 v133, v65, v97
	v_mul_f32_e32 v134, v57, v97
	v_fma_f32 v57, v57, v89, -v133
	v_fma_f32 v65, v65, v89, v134
	v_mul_f32_e32 v133, v74, v122
	v_mul_f32_e32 v134, v66, v122
	v_fma_f32 v66, v66, v114, -v133
	v_fma_f32 v74, v74, v114, v134
	v_mul_f32_e32 v133, v75, v123
	v_mul_f32_e32 v134, v67, v123
	v_fma_f32 v67, v67, v115, -v133
	v_fma_f32 v75, v75, v115, v134
	v_mul_f32_e32 v133, v76, v124
	v_mul_f32_e32 v134, v68, v124
	v_fma_f32 v68, v68, v116, -v133
	v_fma_f32 v76, v76, v116, v134
	v_mul_f32_e32 v133, v77, v125
	v_mul_f32_e32 v134, v69, v125
	v_fma_f32 v69, v69, v117, -v133
	v_fma_f32 v77, v77, v117, v134
	v_mul_f32_e32 v133, v78, v126
	v_mul_f32_e32 v134, v70, v126
	v_fma_f32 v70, v70, v118, -v133
	v_fma_f32 v78, v78, v118, v134
	v_mul_f32_e32 v133, v79, v127
	v_mul_f32_e32 v134, v71, v127
	v_fma_f32 v71, v71, v119, -v133
	v_fma_f32 v79, v79, v119, v134
	v_mul_f32_e32 v133, v80, v128
	v_mul_f32_e32 v134, v72, v128
	v_fma_f32 v72, v72, v120, -v133
	v_fma_f32 v80, v80, v120, v134
	v_mul_f32_e32 v133, v81, v129
	v_mul_f32_e32 v134, v73, v129
	v_fma_f32 v73, v73, v121, -v133
	v_fma_f32 v81, v81, v121, v134
	v_cvt_pk_bf16_f32 v162, v50, v51
	v_cvt_pk_bf16_f32 v163, v52, v53
	v_cvt_pk_bf16_f32 v164, v54, v55
	v_cvt_pk_bf16_f32 v165, v56, v57
	v_cvt_pk_bf16_f32 v166, v58, v59
	v_cvt_pk_bf16_f32 v167, v60, v61
	v_cvt_pk_bf16_f32 v168, v62, v63
	v_cvt_pk_bf16_f32 v169, v64, v65
	v_cvt_pk_bf16_f32 v170, v66, v67
	v_cvt_pk_bf16_f32 v171, v68, v69
	v_cvt_pk_bf16_f32 v172, v70, v71
	v_cvt_pk_bf16_f32 v173, v72, v73
	v_cvt_pk_bf16_f32 v174, v74, v75
	v_cvt_pk_bf16_f32 v175, v76, v77
	v_cvt_pk_bf16_f32 v176, v78, v79
	v_cvt_pk_bf16_f32 v177, v80, v81
	v_mov_b32_e32 v18, 0
	v_mov_b32_e32 v19, 0
	v_mov_b32_e32 v20, 0
	v_mov_b32_e32 v21, 0
	v_mov_b32_e32 v22, 0
	v_mov_b32_e32 v23, 0
	v_mov_b32_e32 v24, 0
	v_mov_b32_e32 v25, 0
	v_mov_b32_e32 v26, 0
	v_mov_b32_e32 v27, 0
	v_mov_b32_e32 v28, 0
	v_mov_b32_e32 v29, 0
	v_mov_b32_e32 v30, 0
	v_mov_b32_e32 v31, 0
	v_mov_b32_e32 v32, 0
	v_mov_b32_e32 v33, 0
	v_mov_b32_e32 v34, 0
	v_mov_b32_e32 v35, 0
	v_mov_b32_e32 v36, 0
	v_mov_b32_e32 v37, 0
	v_mov_b32_e32 v38, 0
	v_mov_b32_e32 v39, 0
	v_mov_b32_e32 v40, 0
	v_mov_b32_e32 v41, 0
	v_mov_b32_e32 v42, 0
	v_mov_b32_e32 v43, 0
	v_mov_b32_e32 v44, 0
	v_mov_b32_e32 v45, 0
	v_mov_b32_e32 v46, 0
	v_mov_b32_e32 v47, 0
	v_mov_b32_e32 v48, 0
	v_mov_b32_e32 v49, 0
	v_mov_b32_e32 v50, 0
	v_mov_b32_e32 v51, 0
	v_mov_b32_e32 v52, 0
	v_mov_b32_e32 v53, 0
	v_mov_b32_e32 v54, 0
	v_mov_b32_e32 v55, 0
	v_mov_b32_e32 v56, 0
	v_mov_b32_e32 v57, 0
	v_mov_b32_e32 v58, 0
	v_mov_b32_e32 v59, 0
	v_mov_b32_e32 v60, 0
	v_mov_b32_e32 v61, 0
	v_mov_b32_e32 v62, 0
	v_mov_b32_e32 v63, 0
	v_mov_b32_e32 v64, 0
	v_mov_b32_e32 v65, 0
	v_mov_b32_e32 v66, 0
	v_mov_b32_e32 v67, 0
	v_mov_b32_e32 v68, 0
	v_mov_b32_e32 v69, 0
	v_mov_b32_e32 v70, 0
	v_mov_b32_e32 v71, 0
	v_mov_b32_e32 v72, 0
	v_mov_b32_e32 v73, 0
	v_mov_b32_e32 v74, 0
	v_mov_b32_e32 v75, 0
	v_mov_b32_e32 v76, 0
	v_mov_b32_e32 v77, 0
	v_mov_b32_e32 v78, 0
	v_mov_b32_e32 v79, 0
	v_mov_b32_e32 v80, 0
	v_mov_b32_e32 v81, 0
	v_mov_b32_e32 v250, 0
	v_mov_b32_e32 v251, 0
	s_barrier
	ds_read_b128 v[178:181], v234 offset:0
	ds_read_b128 v[182:185], v234 offset:4096
	ds_read_b128 v[186:189], v234 offset:8192
	ds_read_b128 v[190:193], v234 offset:12288
	s_waitcnt lgkmcnt(3)
	v_mfma_f32_16x16x32_bf16 v[82:85], v[178:181], v[146:149], v[2:5]
	v_mfma_f32_16x16x32_bf16 v[86:89], v[178:181], v[162:165], v[2:5]
	ds_read_b128 v[178:181], v235 offset:0
	s_waitcnt lgkmcnt(3)
	v_mfma_f32_16x16x32_bf16 v[90:93], v[182:185], v[146:149], v[2:5]
	v_mfma_f32_16x16x32_bf16 v[94:97], v[182:185], v[162:165], v[2:5]
	ds_read_b128 v[182:185], v235 offset:4096
	s_waitcnt lgkmcnt(3)
	v_mfma_f32_16x16x32_bf16 v[98:101], v[186:189], v[146:149], v[2:5]
	v_mfma_f32_16x16x32_bf16 v[102:105], v[186:189], v[162:165], v[2:5]
	ds_read_b128 v[186:189], v235 offset:8192
	s_waitcnt lgkmcnt(3)
	v_mfma_f32_16x16x32_bf16 v[106:109], v[190:193], v[146:149], v[2:5]
	v_mfma_f32_16x16x32_bf16 v[110:113], v[190:193], v[162:165], v[2:5]
	ds_read_b128 v[190:193], v235 offset:12288
	s_waitcnt lgkmcnt(3)
	v_mfma_f32_16x16x32_bf16 v[82:85], v[178:181], v[150:153], v[82:85]
	v_mfma_f32_16x16x32_bf16 v[86:89], v[178:181], v[166:169], v[86:89]
	ds_read_b128 v[178:181], v236 offset:0
	s_waitcnt lgkmcnt(3)
	v_mfma_f32_16x16x32_bf16 v[90:93], v[182:185], v[150:153], v[90:93]
	v_mfma_f32_16x16x32_bf16 v[94:97], v[182:185], v[166:169], v[94:97]
	ds_read_b128 v[182:185], v236 offset:4096
	s_waitcnt lgkmcnt(3)
	v_mfma_f32_16x16x32_bf16 v[98:101], v[186:189], v[150:153], v[98:101]
	v_mfma_f32_16x16x32_bf16 v[102:105], v[186:189], v[166:169], v[102:105]
	ds_read_b128 v[186:189], v236 offset:8192
	s_waitcnt lgkmcnt(3)
	v_mfma_f32_16x16x32_bf16 v[106:109], v[190:193], v[150:153], v[106:109]
	v_mfma_f32_16x16x32_bf16 v[110:113], v[190:193], v[166:169], v[110:113]
	ds_read_b128 v[190:193], v236 offset:12288
	s_waitcnt lgkmcnt(3)
; #define SBAR() __builtin_amdgcn_sched_barrier(0)
; #define SLOAD(i, k0) do { sr_[i].vs0 = St::ld8(&Vh[(long)((k0) + sr) * LDK + sc]); sr_[i].vs1 = St::ld8(&Vh[(long)((k0) + 32 + sr) * LDK + sc]); \
;     sr_[i].ks0 = St::ld8(&Kh[(long)((k0) + sr) * LDK + sc]); sr_[i].ks1 = St::ld8(&Kh[(long)((k0) + 32 + sr) * LDK + sc]); } while (0)
; __device__ __forceinline__ void partialSM(f32x16& p0, f32x16& p1, float mC) {
;     ...
;   for (int r = 0; r < 16; ++r) p0[r] = __builtin_amdgcn_exp2f(p0[r]);
; }
; __device__ __forceinline__ void finishSM(f32x16& p0, f32x16& p1, float& l_reg, bf16x8& pa0, bf16x8& pa1, bf16x8& pa2, bf16x8& pa3) {
;   for (int r = 0; r < 16; ++r) p1[r] = __builtin_amdgcn_exp2f(p1[r]);
;   float ps = 0; for (int r = 0; r < 16; ++r) ps += p0[r]; for (int r = 0; r < 16; ++r) ps += p1[r];
;   { auto rr = __builtin_amdgcn_permlane32_swap(__float_as_uint(ps), __float_as_uint(ps), false, false);
;     ps = __uint_as_float(rr[0]) + __uint_as_float(rr[1]); }
;   l_reg += ps;
;     ...
;   PK4(p0, 0, pa0); PK4(p0, 8, pa1); PK4(p1, 0, pa2); PK4(p1, 8, pa3);
;     ...
; }
; __device__ __forceinline__ void qkt(f32x16& p0, f32x16& p1, const bf16* Ks, const bf16x8* qr, int r32, int hi, const f32x16& negm) {
; #pragma unroll
;   for (int d0 = 0; d0 < 8; ++d0) { int cb = (d0 * 16 + hi * 8) * 2;
;     bf16x8 b0 = *reinterpret_cast<const bf16x8*>((const char*)Ks + KSWZ(r32, cb));
;     bf16x8 b1 = *reinterpret_cast<const bf16x8*>((const char*)Ks + KSWZ(32 + r32, cb));
;     if (d0 == 0) { p0 = __builtin_amdgcn_mfma_f32_32x32x16_bf16(b0, qr[0], negm, 0, 0, 0); p1 = __builtin_amdgcn_mfma_f32_32x32x16_bf16(b1, qr[0], negm, 0, 0, 0); }
;     else { p0 = __builtin_amdgcn_mfma_f32_32x32x16_bf16(b0, qr[d0], p0, 0, 0, 0); p1 = __builtin_amdgcn_mfma_f32_32x32x16_bf16(b1, qr[d0], p1, 0, 0, 0); } }
; }
; template <typename TQ> ...
;     ...
;   for (int j = 1; j + 1 < NT; j += 2) {
;     SBAR(); SLOAD(SO, (j + SDEPTH) * KVBLK); SBAR();
;     qkt(pB0, pB1, (bf16*)((char*)K_lds + SHM_K), qr, r32, hi, negm);
;     finishSM(pA0, pA1, l_reg, pa0, pa1, pa2, pa3); SBAR();
;     pv_d0(o, vb0, pa0, pa1, pa2, pa3); partialSM(pB0, pB1, mC);
	v_mfma_f32_16x16x32_bf16 v[82:85], v[178:181], v[154:157], v[82:85]
	v_mfma_f32_16x16x32_bf16 v[86:89], v[178:181], v[170:173], v[86:89]
	ds_read_b128 v[178:181], v237 offset:0
	s_waitcnt lgkmcnt(3)
	v_mfma_f32_16x16x32_bf16 v[90:93], v[182:185], v[154:157], v[90:93]
	v_mfma_f32_16x16x32_bf16 v[94:97], v[182:185], v[170:173], v[94:97]
	ds_read_b128 v[182:185], v237 offset:4096
	s_waitcnt lgkmcnt(3)
	v_mfma_f32_16x16x32_bf16 v[98:101], v[186:189], v[154:157], v[98:101]
	v_mfma_f32_16x16x32_bf16 v[102:105], v[186:189], v[170:173], v[102:105]
	ds_read_b128 v[186:189], v237 offset:8192
	s_waitcnt lgkmcnt(3)
	v_mfma_f32_16x16x32_bf16 v[106:109], v[190:193], v[154:157], v[106:109]
	v_mfma_f32_16x16x32_bf16 v[110:113], v[190:193], v[170:173], v[110:113]
	ds_read_b128 v[190:193], v237 offset:12288
	s_waitcnt lgkmcnt(3)
	v_mfma_f32_16x16x32_bf16 v[82:85], v[178:181], v[158:161], v[82:85]
	v_mfma_f32_16x16x32_bf16 v[86:89], v[178:181], v[174:177], v[86:89]
	s_waitcnt lgkmcnt(2)
	v_mfma_f32_16x16x32_bf16 v[90:93], v[182:185], v[158:161], v[90:93]
	v_mfma_f32_16x16x32_bf16 v[94:97], v[182:185], v[174:177], v[94:97]
	s_waitcnt lgkmcnt(1)
	v_mfma_f32_16x16x32_bf16 v[98:101], v[186:189], v[158:161], v[98:101]
	v_mfma_f32_16x16x32_bf16 v[102:105], v[186:189], v[174:177], v[102:105]
	s_waitcnt lgkmcnt(0)
	v_mfma_f32_16x16x32_bf16 v[106:109], v[190:193], v[158:161], v[106:109]
	v_mfma_f32_16x16x32_bf16 v[110:113], v[190:193], v[174:177], v[110:113]
	s_nop 7
	v_exp_f32_e32 v82, v82
	v_exp_f32_e32 v83, v83
	v_exp_f32_e32 v84, v84
	v_exp_f32_e32 v85, v85
	v_exp_f32_e32 v86, v86
	v_exp_f32_e32 v87, v87
	v_exp_f32_e32 v88, v88
	v_exp_f32_e32 v89, v89
	v_exp_f32_e32 v90, v90
	v_exp_f32_e32 v91, v91
	v_exp_f32_e32 v92, v92
	v_exp_f32_e32 v93, v93
	v_exp_f32_e32 v94, v94
	v_exp_f32_e32 v95, v95
	v_exp_f32_e32 v96, v96
	v_exp_f32_e32 v97, v97
	v_exp_f32_e32 v98, v98
	v_exp_f32_e32 v99, v99
	v_exp_f32_e32 v100, v100
	v_exp_f32_e32 v101, v101
	v_exp_f32_e32 v102, v102
	v_exp_f32_e32 v103, v103
	v_exp_f32_e32 v104, v104
	v_exp_f32_e32 v105, v105
	v_exp_f32_e32 v106, v106
	v_exp_f32_e32 v107, v107
	v_exp_f32_e32 v108, v108
	v_exp_f32_e32 v109, v109
	v_exp_f32_e32 v110, v110
	v_exp_f32_e32 v111, v111
	v_exp_f32_e32 v112, v112
	v_exp_f32_e32 v113, v113
	ds_read_b128 v[178:181], v234 offset:16384
	ds_read_b128 v[182:185], v234 offset:20480
	ds_read_b128 v[186:189], v234 offset:24576
	ds_read_b128 v[190:193], v234 offset:28672
	s_mov_b32 s15, 0
.Lattn_loop:
	s_barrier
	s_waitcnt lgkmcnt(3)
	v_mfma_f32_16x16x32_bf16 v[114:117], v[178:181], v[146:149], v[2:5]
	v_add_f32_e32 v250, v82, v250
	s_add_u32 s98, s98, 0x8000
	s_addc_u32 s99, s99, 0
	s_add_u32 s100, s100, 0x8000
	s_addc_u32 s101, s101, 0
	v_mfma_f32_16x16x32_bf16 v[118:121], v[178:181], v[162:165], v[2:5]
	ds_read_b128 v[178:181], v235 offset:16384
	v_add_f32_e32 v250, v83, v250
	v_add_f32_e32 v250, v84, v250
	s_waitcnt lgkmcnt(3)
	v_mfma_f32_16x16x32_bf16 v[122:125], v[182:185], v[146:149], v[2:5]
	v_add_f32_e32 v250, v85, v250
	s_add_u32 m0, s79, 0
	s_nop 0
	global_load_lds_dwordx4 v246, s[98:99]
	v_mfma_f32_16x16x32_bf16 v[126:129], v[182:185], v[162:165], v[2:5]
	ds_read_b128 v[182:185], v235 offset:20480
	v_add_f32_e32 v250, v90, v250
	v_add_f32_e32 v250, v91, v250
	s_waitcnt lgkmcnt(3)
	v_mfma_f32_16x16x32_bf16 v[130:133], v[186:189], v[146:149], v[2:5]
	v_add_f32_e32 v250, v92, v250
	v_mfma_f32_16x16x32_bf16 v[134:137], v[186:189], v[162:165], v[2:5]
	ds_read_b128 v[186:189], v235 offset:24576
	v_add_f32_e32 v250, v93, v250
	v_cvt_pk_bf16_f32 v82, v82, v83
	s_waitcnt lgkmcnt(3)
	v_mfma_f32_16x16x32_bf16 v[138:141], v[190:193], v[146:149], v[2:5]
	v_cvt_pk_bf16_f32 v83, v84, v85
	s_add_u32 m0, s79, 1024
	s_nop 0
	global_load_lds_dwordx4 v247, s[98:99]
	v_mfma_f32_16x16x32_bf16 v[142:145], v[190:193], v[162:165], v[2:5]
	ds_read_b128 v[190:193], v235 offset:28672
	v_cvt_pk_bf16_f32 v84, v90, v91
	v_cvt_pk_bf16_f32 v85, v92, v93
	s_waitcnt lgkmcnt(3)
	v_mfma_f32_16x16x32_bf16 v[114:117], v[178:181], v[150:153], v[114:117]
	v_add_f32_e32 v251, v86, v251
	v_mfma_f32_16x16x32_bf16 v[118:121], v[178:181], v[166:169], v[118:121]
	ds_read_b128 v[178:181], v236 offset:16384
	v_add_f32_e32 v251, v87, v251
	v_add_f32_e32 v251, v88, v251
	s_waitcnt lgkmcnt(3)
	v_mfma_f32_16x16x32_bf16 v[122:125], v[182:185], v[150:153], v[122:125]
	v_add_f32_e32 v251, v89, v251
	s_add_u32 m0, s80, 49152
	s_nop 0
	global_load_lds_dwordx4 v248, s[100:101]
	v_mfma_f32_16x16x32_bf16 v[126:129], v[182:185], v[166:169], v[126:129]
	ds_read_b128 v[182:185], v236 offset:20480
	v_add_f32_e32 v251, v94, v251
	v_add_f32_e32 v251, v95, v251
	s_waitcnt lgkmcnt(3)
	v_mfma_f32_16x16x32_bf16 v[130:133], v[186:189], v[150:153], v[130:133]
	v_add_f32_e32 v251, v96, v251
	v_mfma_f32_16x16x32_bf16 v[134:137], v[186:189], v[166:169], v[134:137]
	ds_read_b128 v[186:189], v236 offset:24576
	v_add_f32_e32 v251, v97, v251
	v_cvt_pk_bf16_f32 v86, v86, v87
	s_waitcnt lgkmcnt(3)
	v_mfma_f32_16x16x32_bf16 v[138:141], v[190:193], v[150:153], v[138:141]
	v_cvt_pk_bf16_f32 v87, v88, v89
	s_add_u32 m0, s80, 50176
	s_nop 0
	global_load_lds_dwordx4 v249, s[100:101]
	v_mfma_f32_16x16x32_bf16 v[142:145], v[190:193], v[166:169], v[142:145]
	ds_read_b128 v[190:193], v236 offset:28672
	v_cvt_pk_bf16_f32 v88, v94, v95
	v_cvt_pk_bf16_f32 v89, v96, v97
	s_waitcnt lgkmcnt(3)
	v_mfma_f32_16x16x32_bf16 v[114:117], v[178:181], v[154:157], v[114:117]
	v_add_f32_e32 v250, v98, v250
	v_mfma_f32_16x16x32_bf16 v[118:121], v[178:181], v[170:173], v[118:121]
	ds_read_b128 v[178:181], v237 offset:16384
	v_add_f32_e32 v250, v99, v250
	v_add_f32_e32 v250, v100, v250
	s_waitcnt lgkmcnt(3)
; __device__ __forceinline__ void finishSM(f32x16& p0, f32x16& p1, float& l_reg, bf16x8& pa0, bf16x8& pa1, bf16x8& pa2, bf16x8& pa3) {
;   for (int r = 0; r < 16; ++r) p1[r] = __builtin_amdgcn_exp2f(p1[r]);
;   float ps = 0; for (int r = 0; r < 16; ++r) ps += p0[r]; for (int r = 0; r < 16; ++r) ps += p1[r];
;   { auto rr = __builtin_amdgcn_permlane32_swap(__float_as_uint(ps), __float_as_uint(ps), false, false);
;     ps = __uint_as_float(rr[0]) + __uint_as_float(rr[1]); }
;   l_reg += ps;
;     ...
;   PK4(p0, 0, pa0); PK4(p0, 8, pa1); PK4(p1, 0, pa2); PK4(p1, 8, pa3);
;     ...
; }
; __device__ __forceinline__ void qkt(f32x16& p0, f32x16& p1, const bf16* Ks, const bf16x8* qr, int r32, int hi, const f32x16& negm) {
; #pragma unroll
;   for (int d0 = 0; d0 < 8; ++d0) { int cb = (d0 * 16 + hi * 8) * 2;
;     bf16x8 b0 = *reinterpret_cast<const bf16x8*>((const char*)Ks + KSWZ(r32, cb));
;     bf16x8 b1 = *reinterpret_cast<const bf16x8*>((const char*)Ks + KSWZ(32 + r32, cb));
;     if (d0 == 0) { p0 = __builtin_amdgcn_mfma_f32_32x32x16_bf16(b0, qr[0], negm, 0, 0, 0); p1 = __builtin_amdgcn_mfma_f32_32x32x16_bf16(b1, qr[0], negm, 0, 0, 0); }
;     else { p0 = __builtin_amdgcn_mfma_f32_32x32x16_bf16(b0, qr[d0], p0, 0, 0, 0); p1 = __builtin_amdgcn_mfma_f32_32x32x16_bf16(b1, qr[d0], p1, 0, 0, 0); } }
; }
; __device__ __forceinline__ int v_st(int k, int c) { const int kk = (k & ~0xC) | ((k & 4) << 1) | ((k & 8) >> 1); return ((kk >> 3) * 4 + (c >> 5)) * 512 + ((kk & 7) * 32 + (c & 31)) * 2; }
; __device__ __forceinline__ int v_rd_base(int lane) { return ((lane & 3) << 3) | (((lane >> 2) & 3) << 6) | (((lane >> 4) & 1) << 5) | (((lane >> 5) & 1) << 8); }
; template <int OFF> __device__ __forceinline__ s16x4 tr_read(int vb) {
;   s16x4 r; asm volatile("ds_read_b64_tr_b16 %0, %1 offset:%2" : "=&v"(r) : "v"(vb), "i"(OFF) : "memory"); return r;
; }
; template <int D0> __device__ __forceinline__ void pv_one(f32x16& od, int vb, bf16x8 pa0, bf16x8 pa1, bf16x8 pa2, bf16x8 pa3) {
;   const s16x4 l0 = tr_read<v_rd_off(D0, 0, 0)>(vb), h0 = tr_read<v_rd_off(D0, 0, 1)>(vb), l1 = tr_read<v_rd_off(D0, 1, 0)>(vb), h1 = tr_read<v_rd_off(D0, 1, 1)>(vb);
;   const s16x4 l2 = tr_read<v_rd_off(D0, 2, 0)>(vb), h2 = tr_read<v_rd_off(D0, 2, 1)>(vb), l3 = tr_read<v_rd_off(D0, 3, 0)>(vb), h3 = tr_read<v_rd_off(D0, 3, 1)>(vb);
;   asm volatile("s_waitcnt lgkmcnt(0)" ::: "memory"); SBAR();
	v_mfma_f32_16x16x32_bf16 v[122:125], v[182:185], v[154:157], v[122:125]
	v_add_f32_e32 v250, v101, v250
	v_mfma_f32_16x16x32_bf16 v[126:129], v[182:185], v[170:173], v[126:129]
	ds_read_b128 v[182:185], v237 offset:20480
	v_add_f32_e32 v250, v106, v250
	v_add_f32_e32 v250, v107, v250
	s_waitcnt lgkmcnt(3)
	v_mfma_f32_16x16x32_bf16 v[130:133], v[186:189], v[154:157], v[130:133]
	v_add_f32_e32 v250, v108, v250
	ds_read_b64_tr_b16 v[202:203], v238 offset:0
	ds_read_b64_tr_b16 v[204:205], v238 offset:4096
	v_mfma_f32_16x16x32_bf16 v[134:137], v[186:189], v[170:173], v[134:137]
	ds_read_b128 v[186:189], v237 offset:24576
	v_add_f32_e32 v250, v109, v250
	v_cvt_pk_bf16_f32 v98, v98, v99
	s_waitcnt lgkmcnt(5)
	v_mfma_f32_16x16x32_bf16 v[138:141], v[190:193], v[154:157], v[138:141]
	v_cvt_pk_bf16_f32 v99, v100, v101
	ds_read_b64_tr_b16 v[206:207], v239 offset:0
	ds_read_b64_tr_b16 v[208:209], v239 offset:4096
	v_mfma_f32_16x16x32_bf16 v[142:145], v[190:193], v[170:173], v[142:145]
	ds_read_b128 v[190:193], v237 offset:28672
	v_cvt_pk_bf16_f32 v100, v106, v107
	v_cvt_pk_bf16_f32 v101, v108, v109
	s_waitcnt lgkmcnt(7)
	v_mfma_f32_16x16x32_bf16 v[114:117], v[178:181], v[158:161], v[114:117]
	v_add_f32_e32 v251, v102, v251
	ds_read_b64_tr_b16 v[210:211], v240 offset:0
	ds_read_b64_tr_b16 v[212:213], v240 offset:4096
	v_mfma_f32_16x16x32_bf16 v[118:121], v[178:181], v[174:177], v[118:121]
	v_add_f32_e32 v251, v103, v251
	v_add_f32_e32 v251, v104, v251
	s_waitcnt lgkmcnt(8)
	v_mfma_f32_16x16x32_bf16 v[122:125], v[182:185], v[158:161], v[122:125]
	v_add_f32_e32 v251, v105, v251
	ds_read_b64_tr_b16 v[214:215], v241 offset:0
	ds_read_b64_tr_b16 v[216:217], v241 offset:4096
	v_mfma_f32_16x16x32_bf16 v[126:129], v[182:185], v[174:177], v[126:129]
	v_add_f32_e32 v251, v110, v251
	v_add_f32_e32 v251, v111, v251
	s_waitcnt lgkmcnt(7)
	v_mfma_f32_16x16x32_bf16 v[130:133], v[186:189], v[158:161], v[130:133]
	v_add_f32_e32 v251, v112, v251
	ds_read_b64_tr_b16 v[218:219], v242 offset:0
	ds_read_b64_tr_b16 v[220:221], v242 offset:4096
	v_mfma_f32_16x16x32_bf16 v[134:137], v[186:189], v[174:177], v[134:137]
	v_add_f32_e32 v251, v113, v251
	v_cvt_pk_bf16_f32 v102, v102, v103
	s_waitcnt lgkmcnt(6)
	v_mfma_f32_16x16x32_bf16 v[138:141], v[190:193], v[158:161], v[138:141]
	v_cvt_pk_bf16_f32 v103, v104, v105
	ds_read_b64_tr_b16 v[222:223], v243 offset:0
	ds_read_b64_tr_b16 v[224:225], v243 offset:4096
	v_mfma_f32_16x16x32_bf16 v[142:145], v[190:193], v[174:177], v[142:145]
	v_cvt_pk_bf16_f32 v104, v110, v111
	v_cvt_pk_bf16_f32 v105, v112, v113
	v_mfma_f32_16x16x32_bf16 v[18:21], v[202:205], v[82:85], v[18:21]
	v_exp_f32_e32 v114, v114
	v_mfma_f32_16x16x32_bf16 v[22:25], v[202:205], v[86:89], v[22:25]
	ds_read_b64_tr_b16 v[202:203], v244 offset:0
	ds_read_b64_tr_b16 v[204:205], v244 offset:4096
	v_exp_f32_e32 v115, v115
	v_mfma_f32_16x16x32_bf16 v[26:29], v[206:209], v[82:85], v[26:29]
	v_exp_f32_e32 v116, v116
	v_mfma_f32_16x16x32_bf16 v[30:33], v[206:209], v[86:89], v[30:33]
	ds_read_b64_tr_b16 v[206:207], v245 offset:0
	ds_read_b64_tr_b16 v[208:209], v245 offset:4096
	v_exp_f32_e32 v117, v117
	s_waitcnt lgkmcnt(10)
	v_mfma_f32_16x16x32_bf16 v[34:37], v[210:213], v[82:85], v[34:37]
	v_exp_f32_e32 v118, v118
	v_mfma_f32_16x16x32_bf16 v[38:41], v[210:213], v[86:89], v[38:41]
	ds_read_b64_tr_b16 v[210:211], v238 offset:8192
	ds_read_b64_tr_b16 v[212:213], v238 offset:12288
	v_exp_f32_e32 v119, v119
	s_waitcnt lgkmcnt(10)
	v_mfma_f32_16x16x32_bf16 v[42:45], v[214:217], v[82:85], v[42:45]
	v_exp_f32_e32 v120, v120
	v_mfma_f32_16x16x32_bf16 v[46:49], v[214:217], v[86:89], v[46:49]
	ds_read_b64_tr_b16 v[214:215], v239 offset:8192
	ds_read_b64_tr_b16 v[216:217], v239 offset:12288
	v_exp_f32_e32 v121, v121
	s_waitcnt lgkmcnt(10)
	v_mfma_f32_16x16x32_bf16 v[50:53], v[218:221], v[82:85], v[50:53]
	v_exp_f32_e32 v122, v122
	v_mfma_f32_16x16x32_bf16 v[54:57], v[218:221], v[86:89], v[54:57]
	ds_read_b64_tr_b16 v[218:219], v240 offset:8192
	ds_read_b64_tr_b16 v[220:221], v240 offset:12288
	v_exp_f32_e32 v123, v123
	s_waitcnt lgkmcnt(10)
	v_mfma_f32_16x16x32_bf16 v[58:61], v[222:225], v[82:85], v[58:61]
	v_exp_f32_e32 v124, v124
	v_mfma_f32_16x16x32_bf16 v[62:65], v[222:225], v[86:89], v[62:65]
	ds_read_b64_tr_b16 v[222:223], v241 offset:8192
	ds_read_b64_tr_b16 v[224:225], v241 offset:12288
	v_exp_f32_e32 v125, v125
	s_waitcnt lgkmcnt(10)
	v_mfma_f32_16x16x32_bf16 v[66:69], v[202:205], v[82:85], v[66:69]
	v_exp_f32_e32 v126, v126
	v_mfma_f32_16x16x32_bf16 v[70:73], v[202:205], v[86:89], v[70:73]
	ds_read_b64_tr_b16 v[202:203], v242 offset:8192
	ds_read_b64_tr_b16 v[204:205], v242 offset:12288
	v_exp_f32_e32 v127, v127
	s_waitcnt lgkmcnt(10)
	v_mfma_f32_16x16x32_bf16 v[74:77], v[206:209], v[82:85], v[74:77]
	v_exp_f32_e32 v128, v128
	v_mfma_f32_16x16x32_bf16 v[78:81], v[206:209], v[86:89], v[78:81]
	ds_read_b64_tr_b16 v[206:207], v243 offset:8192
	ds_read_b64_tr_b16 v[208:209], v243 offset:12288
	v_exp_f32_e32 v129, v129
	s_waitcnt lgkmcnt(10)
	v_mfma_f32_16x16x32_bf16 v[18:21], v[210:213], v[98:101], v[18:21]
	v_exp_f32_e32 v130, v130
	v_mfma_f32_16x16x32_bf16 v[22:25], v[210:213], v[102:105], v[22:25]
	ds_read_b64_tr_b16 v[210:211], v244 offset:8192
	ds_read_b64_tr_b16 v[212:213], v244 offset:12288
	v_exp_f32_e32 v131, v131
	s_waitcnt lgkmcnt(10)
	v_mfma_f32_16x16x32_bf16 v[26:29], v[214:217], v[98:101], v[26:29]
	v_exp_f32_e32 v132, v132
	v_mfma_f32_16x16x32_bf16 v[30:33], v[214:217], v[102:105], v[30:33]
	ds_read_b64_tr_b16 v[214:215], v245 offset:8192
	ds_read_b64_tr_b16 v[216:217], v245 offset:12288
	v_exp_f32_e32 v133, v133
	s_waitcnt lgkmcnt(10)
; #define SBAR() __builtin_amdgcn_sched_barrier(0)
; #define SLOAD(i, k0) do { sr_[i].vs0 = St::ld8(&Vh[(long)((k0) + sr) * LDK + sc]); sr_[i].vs1 = St::ld8(&Vh[(long)((k0) + 32 + sr) * LDK + sc]); \
;     sr_[i].ks0 = St::ld8(&Kh[(long)((k0) + sr) * LDK + sc]); sr_[i].ks1 = St::ld8(&Kh[(long)((k0) + 32 + sr) * LDK + sc]); } while (0)
; #define SWAIT() do { if constexpr (SDEPTH == 2) asm volatile("s_waitcnt vmcnt(4)" ::: "memory"); else asm volatile("s_waitcnt vmcnt(0)" ::: "memory"); } while (0)
; template <typename TQ> ...
;     ...
;   for (int j = 1; j + 1 < NT; j += 2) {
;     SBAR(); SLOAD(SO, (j + SDEPTH) * KVBLK); SBAR();
;     qkt(pB0, pB1, (bf16*)((char*)K_lds + SHM_K), qr, r32, hi, negm);
;     finishSM(pA0, pA1, l_reg, pa0, pa1, pa2, pa3); SBAR();
;     pv_d0(o, vb0, pa0, pa1, pa2, pa3); partialSM(pB0, pB1, mC);
;     __syncthreads(); SWAIT(); SWRITE(0, SE);
;     __syncthreads();
;     SBAR(); if (SDEPTH == 1 || j + 3 < NT) SLOAD(SE, (j + 1 + SDEPTH) * KVBLK); SBAR();
;     qkt(pA0, pA1, K_lds, qr, r32, hi, negm);
;     finishSM(pB0, pB1, l_reg, pa0, pa1, pa2, pa3); SBAR();
;     pv_d0(o, vb0 + (int)SHM_V, pa0, pa1, pa2, pa3); partialSM(pA0, pA1, mC);
	v_mfma_f32_16x16x32_bf16 v[34:37], v[218:221], v[98:101], v[34:37]
	v_exp_f32_e32 v134, v134
	v_mfma_f32_16x16x32_bf16 v[38:41], v[218:221], v[102:105], v[38:41]
	v_exp_f32_e32 v135, v135
	s_waitcnt lgkmcnt(8)
	v_mfma_f32_16x16x32_bf16 v[42:45], v[222:225], v[98:101], v[42:45]
	v_exp_f32_e32 v136, v136
	v_mfma_f32_16x16x32_bf16 v[46:49], v[222:225], v[102:105], v[46:49]
	v_exp_f32_e32 v137, v137
	s_waitcnt lgkmcnt(6)
	v_mfma_f32_16x16x32_bf16 v[50:53], v[202:205], v[98:101], v[50:53]
	v_exp_f32_e32 v138, v138
	ds_read_b128 v[178:181], v234 offset:32768
	v_mfma_f32_16x16x32_bf16 v[54:57], v[202:205], v[102:105], v[54:57]
	v_exp_f32_e32 v139, v139
	s_waitcnt lgkmcnt(5)
	v_mfma_f32_16x16x32_bf16 v[58:61], v[206:209], v[98:101], v[58:61]
	v_exp_f32_e32 v140, v140
	ds_read_b128 v[182:185], v234 offset:36864
	v_mfma_f32_16x16x32_bf16 v[62:65], v[206:209], v[102:105], v[62:65]
	v_exp_f32_e32 v141, v141
	s_waitcnt lgkmcnt(4)
	v_mfma_f32_16x16x32_bf16 v[66:69], v[210:213], v[98:101], v[66:69]
	v_exp_f32_e32 v142, v142
	ds_read_b128 v[186:189], v234 offset:40960
	v_mfma_f32_16x16x32_bf16 v[70:73], v[210:213], v[102:105], v[70:73]
	v_exp_f32_e32 v143, v143
	s_waitcnt lgkmcnt(3)
	v_mfma_f32_16x16x32_bf16 v[74:77], v[214:217], v[98:101], v[74:77]
	v_exp_f32_e32 v144, v144
	ds_read_b128 v[190:193], v234 offset:45056
	v_mfma_f32_16x16x32_bf16 v[78:81], v[214:217], v[102:105], v[78:81]
	v_exp_f32_e32 v145, v145
	s_waitcnt vmcnt(4)
	s_barrier
	s_waitcnt lgkmcnt(3)
	v_mfma_f32_16x16x32_bf16 v[82:85], v[178:181], v[146:149], v[2:5]
	v_add_f32_e32 v250, v114, v250
	s_add_u32 s98, s98, 0x8000
	s_addc_u32 s99, s99, 0
	s_add_u32 s100, s100, 0x8000
	s_addc_u32 s101, s101, 0
	v_mfma_f32_16x16x32_bf16 v[86:89], v[178:181], v[162:165], v[2:5]
	ds_read_b128 v[178:181], v235 offset:32768
	v_add_f32_e32 v250, v115, v250
	v_add_f32_e32 v250, v116, v250
	s_waitcnt lgkmcnt(3)
	v_mfma_f32_16x16x32_bf16 v[90:93], v[182:185], v[146:149], v[2:5]
	v_add_f32_e32 v250, v117, v250
	s_add_u32 m0, s79, 16384
	s_nop 0
	global_load_lds_dwordx4 v246, s[98:99]
	v_mfma_f32_16x16x32_bf16 v[94:97], v[182:185], v[162:165], v[2:5]
	ds_read_b128 v[182:185], v235 offset:36864
	v_add_f32_e32 v250, v122, v250
	v_add_f32_e32 v250, v123, v250
	s_waitcnt lgkmcnt(3)
	v_mfma_f32_16x16x32_bf16 v[98:101], v[186:189], v[146:149], v[2:5]
	v_add_f32_e32 v250, v124, v250
	v_mfma_f32_16x16x32_bf16 v[102:105], v[186:189], v[162:165], v[2:5]
	ds_read_b128 v[186:189], v235 offset:40960
	v_add_f32_e32 v250, v125, v250
	v_cvt_pk_bf16_f32 v114, v114, v115
	s_waitcnt lgkmcnt(3)
	v_mfma_f32_16x16x32_bf16 v[106:109], v[190:193], v[146:149], v[2:5]
	v_cvt_pk_bf16_f32 v115, v116, v117
	s_add_u32 m0, s79, 17408
	s_nop 0
	global_load_lds_dwordx4 v247, s[98:99]
	v_mfma_f32_16x16x32_bf16 v[110:113], v[190:193], v[162:165], v[2:5]
	ds_read_b128 v[190:193], v235 offset:45056
	v_cvt_pk_bf16_f32 v116, v122, v123
	v_cvt_pk_bf16_f32 v117, v124, v125
	s_waitcnt lgkmcnt(3)
	v_mfma_f32_16x16x32_bf16 v[82:85], v[178:181], v[150:153], v[82:85]
	v_add_f32_e32 v251, v118, v251
	v_mfma_f32_16x16x32_bf16 v[86:89], v[178:181], v[166:169], v[86:89]
	ds_read_b128 v[178:181], v236 offset:32768
	v_add_f32_e32 v251, v119, v251
	v_add_f32_e32 v251, v120, v251
	s_waitcnt lgkmcnt(3)
	v_mfma_f32_16x16x32_bf16 v[90:93], v[182:185], v[150:153], v[90:93]
	v_add_f32_e32 v251, v121, v251
	s_add_u32 m0, s80, 0
	s_nop 0
	global_load_lds_dwordx4 v248, s[100:101]
	v_mfma_f32_16x16x32_bf16 v[94:97], v[182:185], v[166:169], v[94:97]
	ds_read_b128 v[182:185], v236 offset:36864
	v_add_f32_e32 v251, v126, v251
	v_add_f32_e32 v251, v127, v251
	s_waitcnt lgkmcnt(3)
	v_mfma_f32_16x16x32_bf16 v[98:101], v[186:189], v[150:153], v[98:101]
	v_add_f32_e32 v251, v128, v251
	v_mfma_f32_16x16x32_bf16 v[102:105], v[186:189], v[166:169], v[102:105]
	ds_read_b128 v[186:189], v236 offset:40960
	v_add_f32_e32 v251, v129, v251
	v_cvt_pk_bf16_f32 v118, v118, v119
	s_waitcnt lgkmcnt(3)
	v_mfma_f32_16x16x32_bf16 v[106:109], v[190:193], v[150:153], v[106:109]
	v_cvt_pk_bf16_f32 v119, v120, v121
	s_add_u32 m0, s80, 1024
	s_nop 0
	global_load_lds_dwordx4 v249, s[100:101]
	v_mfma_f32_16x16x32_bf16 v[110:113], v[190:193], v[166:169], v[110:113]
	ds_read_b128 v[190:193], v236 offset:45056
	v_cvt_pk_bf16_f32 v120, v126, v127
	v_cvt_pk_bf16_f32 v121, v128, v129
	s_waitcnt lgkmcnt(3)
	v_mfma_f32_16x16x32_bf16 v[82:85], v[178:181], v[154:157], v[82:85]
	v_add_f32_e32 v250, v130, v250
	v_mfma_f32_16x16x32_bf16 v[86:89], v[178:181], v[170:173], v[86:89]
	ds_read_b128 v[178:181], v237 offset:32768
	v_add_f32_e32 v250, v131, v250
	v_add_f32_e32 v250, v132, v250
	s_waitcnt lgkmcnt(3)
	v_mfma_f32_16x16x32_bf16 v[90:93], v[182:185], v[154:157], v[90:93]
	v_add_f32_e32 v250, v133, v250
	v_mfma_f32_16x16x32_bf16 v[94:97], v[182:185], v[170:173], v[94:97]
	ds_read_b128 v[182:185], v237 offset:36864
	v_add_f32_e32 v250, v138, v250
	v_add_f32_e32 v250, v139, v250
	s_waitcnt lgkmcnt(3)
	v_mfma_f32_16x16x32_bf16 v[98:101], v[186:189], v[154:157], v[98:101]
	v_add_f32_e32 v250, v140, v250
	ds_read_b64_tr_b16 v[202:203], v238 offset:16384
	ds_read_b64_tr_b16 v[204:205], v238 offset:20480
	v_mfma_f32_16x16x32_bf16 v[102:105], v[186:189], v[170:173], v[102:105]
	ds_read_b128 v[186:189], v237 offset:40960
	v_add_f32_e32 v250, v141, v250
	v_cvt_pk_bf16_f32 v130, v130, v131
	s_waitcnt lgkmcnt(5)
	v_mfma_f32_16x16x32_bf16 v[106:109], v[190:193], v[154:157], v[106:109]
	v_cvt_pk_bf16_f32 v131, v132, v133
	ds_read_b64_tr_b16 v[206:207], v239 offset:16384
	ds_read_b64_tr_b16 v[208:209], v239 offset:20480
	v_mfma_f32_16x16x32_bf16 v[110:113], v[190:193], v[170:173], v[110:113]
	ds_read_b128 v[190:193], v237 offset:45056
	v_cvt_pk_bf16_f32 v132, v138, v139
	v_cvt_pk_bf16_f32 v133, v140, v141
	s_waitcnt lgkmcnt(7)
; __device__ __forceinline__ void finishSM(f32x16& p0, f32x16& p1, float& l_reg, bf16x8& pa0, bf16x8& pa1, bf16x8& pa2, bf16x8& pa3) {
;   for (int r = 0; r < 16; ++r) p1[r] = __builtin_amdgcn_exp2f(p1[r]);
;   float ps = 0; for (int r = 0; r < 16; ++r) ps += p0[r]; for (int r = 0; r < 16; ++r) ps += p1[r];
;   { auto rr = __builtin_amdgcn_permlane32_swap(__float_as_uint(ps), __float_as_uint(ps), false, false);
;     ps = __uint_as_float(rr[0]) + __uint_as_float(rr[1]); }
;   l_reg += ps;
;     ...
;   PK4(p0, 0, pa0); PK4(p0, 8, pa1); PK4(p1, 0, pa2); PK4(p1, 8, pa3);
;     ...
; }
; __device__ __forceinline__ void qkt(f32x16& p0, f32x16& p1, const bf16* Ks, const bf16x8* qr, int r32, int hi, const f32x16& negm) {
; #pragma unroll
;   for (int d0 = 0; d0 < 8; ++d0) { int cb = (d0 * 16 + hi * 8) * 2;
;     bf16x8 b0 = *reinterpret_cast<const bf16x8*>((const char*)Ks + KSWZ(r32, cb));
;     bf16x8 b1 = *reinterpret_cast<const bf16x8*>((const char*)Ks + KSWZ(32 + r32, cb));
;     if (d0 == 0) { p0 = __builtin_amdgcn_mfma_f32_32x32x16_bf16(b0, qr[0], negm, 0, 0, 0); p1 = __builtin_amdgcn_mfma_f32_32x32x16_bf16(b1, qr[0], negm, 0, 0, 0); }
;     else { p0 = __builtin_amdgcn_mfma_f32_32x32x16_bf16(b0, qr[d0], p0, 0, 0, 0); p1 = __builtin_amdgcn_mfma_f32_32x32x16_bf16(b1, qr[d0], p1, 0, 0, 0); } }
; }
; __device__ __forceinline__ int v_st(int k, int c) { const int kk = (k & ~0xC) | ((k & 4) << 1) | ((k & 8) >> 1); return ((kk >> 3) * 4 + (c >> 5)) * 512 + ((kk & 7) * 32 + (c & 31)) * 2; }
; __device__ __forceinline__ int v_rd_base(int lane) { return ((lane & 3) << 3) | (((lane >> 2) & 3) << 6) | (((lane >> 4) & 1) << 5) | (((lane >> 5) & 1) << 8); }
; template <int OFF> __device__ __forceinline__ s16x4 tr_read(int vb) {
;   s16x4 r; asm volatile("ds_read_b64_tr_b16 %0, %1 offset:%2" : "=&v"(r) : "v"(vb), "i"(OFF) : "memory"); return r;
; }
; template <int D0> __device__ __forceinline__ void pv_one(f32x16& od, int vb, bf16x8 pa0, bf16x8 pa1, bf16x8 pa2, bf16x8 pa3) {
;   const s16x4 l0 = tr_read<v_rd_off(D0, 0, 0)>(vb), h0 = tr_read<v_rd_off(D0, 0, 1)>(vb), l1 = tr_read<v_rd_off(D0, 1, 0)>(vb), h1 = tr_read<v_rd_off(D0, 1, 1)>(vb);
;   const s16x4 l2 = tr_read<v_rd_off(D0, 2, 0)>(vb), h2 = tr_read<v_rd_off(D0, 2, 1)>(vb), l3 = tr_read<v_rd_off(D0, 3, 0)>(vb), h3 = tr_read<v_rd_off(D0, 3, 1)>(vb);
;   asm volatile("s_waitcnt lgkmcnt(0)" ::: "memory"); SBAR();
	v_mfma_f32_16x16x32_bf16 v[82:85], v[178:181], v[158:161], v[82:85]
	v_add_f32_e32 v251, v134, v251
	ds_read_b64_tr_b16 v[210:211], v240 offset:16384
	ds_read_b64_tr_b16 v[212:213], v240 offset:20480
	v_mfma_f32_16x16x32_bf16 v[86:89], v[178:181], v[174:177], v[86:89]
	v_add_f32_e32 v251, v135, v251
	v_add_f32_e32 v251, v136, v251
	s_waitcnt lgkmcnt(8)
	v_mfma_f32_16x16x32_bf16 v[90:93], v[182:185], v[158:161], v[90:93]
	v_add_f32_e32 v251, v137, v251
	ds_read_b64_tr_b16 v[214:215], v241 offset:16384
	ds_read_b64_tr_b16 v[216:217], v241 offset:20480
	v_mfma_f32_16x16x32_bf16 v[94:97], v[182:185], v[174:177], v[94:97]
	v_add_f32_e32 v251, v142, v251
	v_add_f32_e32 v251, v143, v251
	s_waitcnt lgkmcnt(7)
	v_mfma_f32_16x16x32_bf16 v[98:101], v[186:189], v[158:161], v[98:101]
	v_add_f32_e32 v251, v144, v251
	ds_read_b64_tr_b16 v[218:219], v242 offset:16384
	ds_read_b64_tr_b16 v[220:221], v242 offset:20480
	v_mfma_f32_16x16x32_bf16 v[102:105], v[186:189], v[174:177], v[102:105]
	v_add_f32_e32 v251, v145, v251
	v_cvt_pk_bf16_f32 v134, v134, v135
	s_waitcnt lgkmcnt(6)
	v_mfma_f32_16x16x32_bf16 v[106:109], v[190:193], v[158:161], v[106:109]
	v_cvt_pk_bf16_f32 v135, v136, v137
	ds_read_b64_tr_b16 v[222:223], v243 offset:16384
	ds_read_b64_tr_b16 v[224:225], v243 offset:20480
	v_mfma_f32_16x16x32_bf16 v[110:113], v[190:193], v[174:177], v[110:113]
	v_cvt_pk_bf16_f32 v136, v142, v143
	v_cvt_pk_bf16_f32 v137, v144, v145
	v_mfma_f32_16x16x32_bf16 v[18:21], v[202:205], v[114:117], v[18:21]
	v_exp_f32_e32 v82, v82
	v_mfma_f32_16x16x32_bf16 v[22:25], v[202:205], v[118:121], v[22:25]
	ds_read_b64_tr_b16 v[202:203], v244 offset:16384
	ds_read_b64_tr_b16 v[204:205], v244 offset:20480
	v_exp_f32_e32 v83, v83
	v_mfma_f32_16x16x32_bf16 v[26:29], v[206:209], v[114:117], v[26:29]
	v_exp_f32_e32 v84, v84
	v_mfma_f32_16x16x32_bf16 v[30:33], v[206:209], v[118:121], v[30:33]
	ds_read_b64_tr_b16 v[206:207], v245 offset:16384
	ds_read_b64_tr_b16 v[208:209], v245 offset:20480
	v_exp_f32_e32 v85, v85
	s_waitcnt lgkmcnt(10)
	v_mfma_f32_16x16x32_bf16 v[34:37], v[210:213], v[114:117], v[34:37]
	v_exp_f32_e32 v86, v86
	v_mfma_f32_16x16x32_bf16 v[38:41], v[210:213], v[118:121], v[38:41]
	ds_read_b64_tr_b16 v[210:211], v238 offset:24576
	ds_read_b64_tr_b16 v[212:213], v238 offset:28672
	v_exp_f32_e32 v87, v87
	s_waitcnt lgkmcnt(10)
	v_mfma_f32_16x16x32_bf16 v[42:45], v[214:217], v[114:117], v[42:45]
	v_exp_f32_e32 v88, v88
	v_mfma_f32_16x16x32_bf16 v[46:49], v[214:217], v[118:121], v[46:49]
	ds_read_b64_tr_b16 v[214:215], v239 offset:24576
	ds_read_b64_tr_b16 v[216:217], v239 offset:28672
	v_exp_f32_e32 v89, v89
	s_waitcnt lgkmcnt(10)
	v_mfma_f32_16x16x32_bf16 v[50:53], v[218:221], v[114:117], v[50:53]
	v_exp_f32_e32 v90, v90
	v_mfma_f32_16x16x32_bf16 v[54:57], v[218:221], v[118:121], v[54:57]
	ds_read_b64_tr_b16 v[218:219], v240 offset:24576
	ds_read_b64_tr_b16 v[220:221], v240 offset:28672
	v_exp_f32_e32 v91, v91
	s_waitcnt lgkmcnt(10)
	v_mfma_f32_16x16x32_bf16 v[58:61], v[222:225], v[114:117], v[58:61]
	v_exp_f32_e32 v92, v92
	v_mfma_f32_16x16x32_bf16 v[62:65], v[222:225], v[118:121], v[62:65]
	ds_read_b64_tr_b16 v[222:223], v241 offset:24576
	ds_read_b64_tr_b16 v[224:225], v241 offset:28672
	v_exp_f32_e32 v93, v93
	s_waitcnt lgkmcnt(10)
	v_mfma_f32_16x16x32_bf16 v[66:69], v[202:205], v[114:117], v[66:69]
	v_exp_f32_e32 v94, v94
	v_mfma_f32_16x16x32_bf16 v[70:73], v[202:205], v[118:121], v[70:73]
	ds_read_b64_tr_b16 v[202:203], v242 offset:24576
	ds_read_b64_tr_b16 v[204:205], v242 offset:28672
	v_exp_f32_e32 v95, v95
	s_waitcnt lgkmcnt(10)
	v_mfma_f32_16x16x32_bf16 v[74:77], v[206:209], v[114:117], v[74:77]
	v_exp_f32_e32 v96, v96
	v_mfma_f32_16x16x32_bf16 v[78:81], v[206:209], v[118:121], v[78:81]
	ds_read_b64_tr_b16 v[206:207], v243 offset:24576
	ds_read_b64_tr_b16 v[208:209], v243 offset:28672
	v_exp_f32_e32 v97, v97
	s_waitcnt lgkmcnt(10)
	v_mfma_f32_16x16x32_bf16 v[18:21], v[210:213], v[130:133], v[18:21]
	v_exp_f32_e32 v98, v98
	v_mfma_f32_16x16x32_bf16 v[22:25], v[210:213], v[134:137], v[22:25]
	ds_read_b64_tr_b16 v[210:211], v244 offset:24576
	ds_read_b64_tr_b16 v[212:213], v244 offset:28672
	v_exp_f32_e32 v99, v99
	s_waitcnt lgkmcnt(10)
	v_mfma_f32_16x16x32_bf16 v[26:29], v[214:217], v[130:133], v[26:29]
	v_exp_f32_e32 v100, v100
	v_mfma_f32_16x16x32_bf16 v[30:33], v[214:217], v[134:137], v[30:33]
	ds_read_b64_tr_b16 v[214:215], v245 offset:24576
	ds_read_b64_tr_b16 v[216:217], v245 offset:28672
	v_exp_f32_e32 v101, v101
	s_waitcnt lgkmcnt(10)
	v_mfma_f32_16x16x32_bf16 v[34:37], v[218:221], v[130:133], v[34:37]
	v_exp_f32_e32 v102, v102
	v_mfma_f32_16x16x32_bf16 v[38:41], v[218:221], v[134:137], v[38:41]
	v_exp_f32_e32 v103, v103
	s_waitcnt lgkmcnt(8)
	v_mfma_f32_16x16x32_bf16 v[42:45], v[222:225], v[130:133], v[42:45]
	v_exp_f32_e32 v104, v104
	v_mfma_f32_16x16x32_bf16 v[46:49], v[222:225], v[134:137], v[46:49]
	v_exp_f32_e32 v105, v105
	s_waitcnt lgkmcnt(6)
	v_mfma_f32_16x16x32_bf16 v[50:53], v[202:205], v[130:133], v[50:53]
	v_exp_f32_e32 v106, v106
	ds_read_b128 v[178:181], v234 offset:49152
	v_mfma_f32_16x16x32_bf16 v[54:57], v[202:205], v[134:137], v[54:57]
	v_exp_f32_e32 v107, v107
	s_waitcnt lgkmcnt(5)
	v_mfma_f32_16x16x32_bf16 v[58:61], v[206:209], v[130:133], v[58:61]
	v_exp_f32_e32 v108, v108
	ds_read_b128 v[182:185], v234 offset:53248
	v_mfma_f32_16x16x32_bf16 v[62:65], v[206:209], v[134:137], v[62:65]
	v_exp_f32_e32 v109, v109
	s_waitcnt lgkmcnt(4)
	v_mfma_f32_16x16x32_bf16 v[66:69], v[210:213], v[130:133], v[66:69]
	v_exp_f32_e32 v110, v110
	ds_read_b128 v[186:189], v234 offset:57344
	v_mfma_f32_16x16x32_bf16 v[70:73], v[210:213], v[134:137], v[70:73]
	v_exp_f32_e32 v111, v111
	s_waitcnt lgkmcnt(3)
	v_mfma_f32_16x16x32_bf16 v[74:77], v[214:217], v[130:133], v[74:77]
	v_exp_f32_e32 v112, v112
	ds_read_b128 v[190:193], v234 offset:61440
	v_mfma_f32_16x16x32_bf16 v[78:81], v[214:217], v[134:137], v[78:81]
	v_exp_f32_e32 v113, v113
	s_waitcnt vmcnt(4)
	s_barrier
; #define SBAR() __builtin_amdgcn_sched_barrier(0)
; #define SLOAD(i, k0) do { sr_[i].vs0 = St::ld8(&Vh[(long)((k0) + sr) * LDK + sc]); sr_[i].vs1 = St::ld8(&Vh[(long)((k0) + 32 + sr) * LDK + sc]); \
;     sr_[i].ks0 = St::ld8(&Kh[(long)((k0) + sr) * LDK + sc]); sr_[i].ks1 = St::ld8(&Kh[(long)((k0) + 32 + sr) * LDK + sc]); } while (0)
; #define SWAIT() do { if constexpr (SDEPTH == 2) asm volatile("s_waitcnt vmcnt(4)" ::: "memory"); else asm volatile("s_waitcnt vmcnt(0)" ::: "memory"); } while (0)
; template <typename TQ> ...
;     ...
;   for (int j = 1; j + 1 < NT; j += 2) {
;     SBAR(); SLOAD(SO, (j + SDEPTH) * KVBLK); SBAR();
;     qkt(pB0, pB1, (bf16*)((char*)K_lds + SHM_K), qr, r32, hi, negm);
;     finishSM(pA0, pA1, l_reg, pa0, pa1, pa2, pa3); SBAR();
;     pv_d0(o, vb0, pa0, pa1, pa2, pa3); partialSM(pB0, pB1, mC);
;     __syncthreads(); SWAIT(); SWRITE(0, SE);
;     __syncthreads();
;     SBAR(); if (SDEPTH == 1 || j + 3 < NT) SLOAD(SE, (j + 1 + SDEPTH) * KVBLK); SBAR();
;     qkt(pA0, pA1, K_lds, qr, r32, hi, negm);
;     finishSM(pB0, pB1, l_reg, pa0, pa1, pa2, pa3); SBAR();
;     pv_d0(o, vb0 + (int)SHM_V, pa0, pa1, pa2, pa3); partialSM(pA0, pA1, mC);
	s_waitcnt lgkmcnt(3)
	v_mfma_f32_16x16x32_bf16 v[114:117], v[178:181], v[146:149], v[2:5]
	v_add_f32_e32 v250, v82, v250
	s_add_u32 s98, s98, 0x8000
	s_addc_u32 s99, s99, 0
	s_add_u32 s100, s100, 0x8000
	s_addc_u32 s101, s101, 0
	v_mfma_f32_16x16x32_bf16 v[118:121], v[178:181], v[162:165], v[2:5]
	ds_read_b128 v[178:181], v235 offset:49152
	v_add_f32_e32 v250, v83, v250
	v_add_f32_e32 v250, v84, v250
	s_waitcnt lgkmcnt(3)
	v_mfma_f32_16x16x32_bf16 v[122:125], v[182:185], v[146:149], v[2:5]
	v_add_f32_e32 v250, v85, v250
	s_add_u32 m0, s79, 32768
	s_nop 0
	global_load_lds_dwordx4 v246, s[98:99]
	v_mfma_f32_16x16x32_bf16 v[126:129], v[182:185], v[162:165], v[2:5]
	ds_read_b128 v[182:185], v235 offset:53248
	v_add_f32_e32 v250, v90, v250
	v_add_f32_e32 v250, v91, v250
	s_waitcnt lgkmcnt(3)
	v_mfma_f32_16x16x32_bf16 v[130:133], v[186:189], v[146:149], v[2:5]
	v_add_f32_e32 v250, v92, v250
	v_mfma_f32_16x16x32_bf16 v[134:137], v[186:189], v[162:165], v[2:5]
	ds_read_b128 v[186:189], v235 offset:57344
	v_add_f32_e32 v250, v93, v250
	v_cvt_pk_bf16_f32 v82, v82, v83
	s_waitcnt lgkmcnt(3)
	v_mfma_f32_16x16x32_bf16 v[138:141], v[190:193], v[146:149], v[2:5]
	v_cvt_pk_bf16_f32 v83, v84, v85
	s_add_u32 m0, s79, 33792
	s_nop 0
	global_load_lds_dwordx4 v247, s[98:99]
	v_mfma_f32_16x16x32_bf16 v[142:145], v[190:193], v[162:165], v[2:5]
	ds_read_b128 v[190:193], v235 offset:61440
	v_cvt_pk_bf16_f32 v84, v90, v91
	v_cvt_pk_bf16_f32 v85, v92, v93
	s_waitcnt lgkmcnt(3)
	v_mfma_f32_16x16x32_bf16 v[114:117], v[178:181], v[150:153], v[114:117]
	v_add_f32_e32 v251, v86, v251
	v_mfma_f32_16x16x32_bf16 v[118:121], v[178:181], v[166:169], v[118:121]
	ds_read_b128 v[178:181], v236 offset:49152
	v_add_f32_e32 v251, v87, v251
	v_add_f32_e32 v251, v88, v251
	s_waitcnt lgkmcnt(3)
	v_mfma_f32_16x16x32_bf16 v[122:125], v[182:185], v[150:153], v[122:125]
	v_add_f32_e32 v251, v89, v251
	s_add_u32 m0, s80, 16384
	s_nop 0
	global_load_lds_dwordx4 v248, s[100:101]
	v_mfma_f32_16x16x32_bf16 v[126:129], v[182:185], v[166:169], v[126:129]
	ds_read_b128 v[182:185], v236 offset:53248
	v_add_f32_e32 v251, v94, v251
	v_add_f32_e32 v251, v95, v251
	s_waitcnt lgkmcnt(3)
	v_mfma_f32_16x16x32_bf16 v[130:133], v[186:189], v[150:153], v[130:133]
	v_add_f32_e32 v251, v96, v251
	v_mfma_f32_16x16x32_bf16 v[134:137], v[186:189], v[166:169], v[134:137]
	ds_read_b128 v[186:189], v236 offset:57344
	v_add_f32_e32 v251, v97, v251
	v_cvt_pk_bf16_f32 v86, v86, v87
	s_waitcnt lgkmcnt(3)
	v_mfma_f32_16x16x32_bf16 v[138:141], v[190:193], v[150:153], v[138:141]
	v_cvt_pk_bf16_f32 v87, v88, v89
	s_add_u32 m0, s80, 17408
	s_nop 0
	global_load_lds_dwordx4 v249, s[100:101]
	v_mfma_f32_16x16x32_bf16 v[142:145], v[190:193], v[166:169], v[142:145]
	ds_read_b128 v[190:193], v236 offset:61440
	v_cvt_pk_bf16_f32 v88, v94, v95
	v_cvt_pk_bf16_f32 v89, v96, v97
	s_waitcnt lgkmcnt(3)
	v_mfma_f32_16x16x32_bf16 v[114:117], v[178:181], v[154:157], v[114:117]
	v_add_f32_e32 v250, v98, v250
	v_mfma_f32_16x16x32_bf16 v[118:121], v[178:181], v[170:173], v[118:121]
	ds_read_b128 v[178:181], v237 offset:49152
	v_add_f32_e32 v250, v99, v250
	v_add_f32_e32 v250, v100, v250
	s_waitcnt lgkmcnt(3)
	v_mfma_f32_16x16x32_bf16 v[122:125], v[182:185], v[154:157], v[122:125]
	v_add_f32_e32 v250, v101, v250
	v_mfma_f32_16x16x32_bf16 v[126:129], v[182:185], v[170:173], v[126:129]
	ds_read_b128 v[182:185], v237 offset:53248
	v_add_f32_e32 v250, v106, v250
	v_add_f32_e32 v250, v107, v250
	s_waitcnt lgkmcnt(3)
	v_mfma_f32_16x16x32_bf16 v[130:133], v[186:189], v[154:157], v[130:133]
	v_add_f32_e32 v250, v108, v250
	ds_read_b64_tr_b16 v[202:203], v238 offset:32768
	ds_read_b64_tr_b16 v[204:205], v238 offset:36864
	v_mfma_f32_16x16x32_bf16 v[134:137], v[186:189], v[170:173], v[134:137]
	ds_read_b128 v[186:189], v237 offset:57344
	v_add_f32_e32 v250, v109, v250
	v_cvt_pk_bf16_f32 v98, v98, v99
	s_waitcnt lgkmcnt(5)
	v_mfma_f32_16x16x32_bf16 v[138:141], v[190:193], v[154:157], v[138:141]
	v_cvt_pk_bf16_f32 v99, v100, v101
	ds_read_b64_tr_b16 v[206:207], v239 offset:32768
	ds_read_b64_tr_b16 v[208:209], v239 offset:36864
	v_mfma_f32_16x16x32_bf16 v[142:145], v[190:193], v[170:173], v[142:145]
	ds_read_b128 v[190:193], v237 offset:61440
	v_cvt_pk_bf16_f32 v100, v106, v107
	v_cvt_pk_bf16_f32 v101, v108, v109
	s_waitcnt lgkmcnt(7)
	v_mfma_f32_16x16x32_bf16 v[114:117], v[178:181], v[158:161], v[114:117]
	v_add_f32_e32 v251, v102, v251
	ds_read_b64_tr_b16 v[210:211], v240 offset:32768
	ds_read_b64_tr_b16 v[212:213], v240 offset:36864
	v_mfma_f32_16x16x32_bf16 v[118:121], v[178:181], v[174:177], v[118:121]
	v_add_f32_e32 v251, v103, v251
	v_add_f32_e32 v251, v104, v251
	s_waitcnt lgkmcnt(8)
	v_mfma_f32_16x16x32_bf16 v[122:125], v[182:185], v[158:161], v[122:125]
	v_add_f32_e32 v251, v105, v251
	ds_read_b64_tr_b16 v[214:215], v241 offset:32768
	ds_read_b64_tr_b16 v[216:217], v241 offset:36864
	v_mfma_f32_16x16x32_bf16 v[126:129], v[182:185], v[174:177], v[126:129]
	v_add_f32_e32 v251, v110, v251
	v_add_f32_e32 v251, v111, v251
	s_waitcnt lgkmcnt(7)
	v_mfma_f32_16x16x32_bf16 v[130:133], v[186:189], v[158:161], v[130:133]
	v_add_f32_e32 v251, v112, v251
	ds_read_b64_tr_b16 v[218:219], v242 offset:32768
	ds_read_b64_tr_b16 v[220:221], v242 offset:36864
	v_mfma_f32_16x16x32_bf16 v[134:137], v[186:189], v[174:177], v[134:137]
	v_add_f32_e32 v251, v113, v251
	v_cvt_pk_bf16_f32 v102, v102, v103
	s_waitcnt lgkmcnt(6)
; __device__ __forceinline__ void finishSM(f32x16& p0, f32x16& p1, float& l_reg, bf16x8& pa0, bf16x8& pa1, bf16x8& pa2, bf16x8& pa3) {
;   for (int r = 0; r < 16; ++r) p1[r] = __builtin_amdgcn_exp2f(p1[r]);
;   float ps = 0; for (int r = 0; r < 16; ++r) ps += p0[r]; for (int r = 0; r < 16; ++r) ps += p1[r];
;   { auto rr = __builtin_amdgcn_permlane32_swap(__float_as_uint(ps), __float_as_uint(ps), false, false);
;     ps = __uint_as_float(rr[0]) + __uint_as_float(rr[1]); }
;   l_reg += ps;
;     ...
;   PK4(p0, 0, pa0); PK4(p0, 8, pa1); PK4(p1, 0, pa2); PK4(p1, 8, pa3);
;     ...
; }
; __device__ __forceinline__ void qkt(f32x16& p0, f32x16& p1, const bf16* Ks, const bf16x8* qr, int r32, int hi, const f32x16& negm) {
; #pragma unroll
;   for (int d0 = 0; d0 < 8; ++d0) { int cb = (d0 * 16 + hi * 8) * 2;
;     bf16x8 b0 = *reinterpret_cast<const bf16x8*>((const char*)Ks + KSWZ(r32, cb));
;     bf16x8 b1 = *reinterpret_cast<const bf16x8*>((const char*)Ks + KSWZ(32 + r32, cb));
;     if (d0 == 0) { p0 = __builtin_amdgcn_mfma_f32_32x32x16_bf16(b0, qr[0], negm, 0, 0, 0); p1 = __builtin_amdgcn_mfma_f32_32x32x16_bf16(b1, qr[0], negm, 0, 0, 0); }
;     else { p0 = __builtin_amdgcn_mfma_f32_32x32x16_bf16(b0, qr[d0], p0, 0, 0, 0); p1 = __builtin_amdgcn_mfma_f32_32x32x16_bf16(b1, qr[d0], p1, 0, 0, 0); } }
; }
; __device__ __forceinline__ int v_st(int k, int c) { const int kk = (k & ~0xC) | ((k & 4) << 1) | ((k & 8) >> 1); return ((kk >> 3) * 4 + (c >> 5)) * 512 + ((kk & 7) * 32 + (c & 31)) * 2; }
; __device__ __forceinline__ int v_rd_base(int lane) { return ((lane & 3) << 3) | (((lane >> 2) & 3) << 6) | (((lane >> 4) & 1) << 5) | (((lane >> 5) & 1) << 8); }
; template <int OFF> __device__ __forceinline__ s16x4 tr_read(int vb) {
;   s16x4 r; asm volatile("ds_read_b64_tr_b16 %0, %1 offset:%2" : "=&v"(r) : "v"(vb), "i"(OFF) : "memory"); return r;
; }
; template <int D0> __device__ __forceinline__ void pv_one(f32x16& od, int vb, bf16x8 pa0, bf16x8 pa1, bf16x8 pa2, bf16x8 pa3) {
;   const s16x4 l0 = tr_read<v_rd_off(D0, 0, 0)>(vb), h0 = tr_read<v_rd_off(D0, 0, 1)>(vb), l1 = tr_read<v_rd_off(D0, 1, 0)>(vb), h1 = tr_read<v_rd_off(D0, 1, 1)>(vb);
;   const s16x4 l2 = tr_read<v_rd_off(D0, 2, 0)>(vb), h2 = tr_read<v_rd_off(D0, 2, 1)>(vb), l3 = tr_read<v_rd_off(D0, 3, 0)>(vb), h3 = tr_read<v_rd_off(D0, 3, 1)>(vb);
;   asm volatile("s_waitcnt lgkmcnt(0)" ::: "memory"); SBAR();
	v_mfma_f32_16x16x32_bf16 v[138:141], v[190:193], v[158:161], v[138:141]
	v_cvt_pk_bf16_f32 v103, v104, v105
	ds_read_b64_tr_b16 v[222:223], v243 offset:32768
	ds_read_b64_tr_b16 v[224:225], v243 offset:36864
	v_mfma_f32_16x16x32_bf16 v[142:145], v[190:193], v[174:177], v[142:145]
	v_cvt_pk_bf16_f32 v104, v110, v111
	v_cvt_pk_bf16_f32 v105, v112, v113
	v_mfma_f32_16x16x32_bf16 v[18:21], v[202:205], v[82:85], v[18:21]
	v_exp_f32_e32 v114, v114
	v_mfma_f32_16x16x32_bf16 v[22:25], v[202:205], v[86:89], v[22:25]
	ds_read_b64_tr_b16 v[202:203], v244 offset:32768
	ds_read_b64_tr_b16 v[204:205], v244 offset:36864
	v_exp_f32_e32 v115, v115
	v_mfma_f32_16x16x32_bf16 v[26:29], v[206:209], v[82:85], v[26:29]
	v_exp_f32_e32 v116, v116
	v_mfma_f32_16x16x32_bf16 v[30:33], v[206:209], v[86:89], v[30:33]
	ds_read_b64_tr_b16 v[206:207], v245 offset:32768
	ds_read_b64_tr_b16 v[208:209], v245 offset:36864
	v_exp_f32_e32 v117, v117
	s_waitcnt lgkmcnt(10)
	v_mfma_f32_16x16x32_bf16 v[34:37], v[210:213], v[82:85], v[34:37]
	v_exp_f32_e32 v118, v118
	v_mfma_f32_16x16x32_bf16 v[38:41], v[210:213], v[86:89], v[38:41]
	ds_read_b64_tr_b16 v[210:211], v238 offset:40960
	ds_read_b64_tr_b16 v[212:213], v238 offset:45056
	v_exp_f32_e32 v119, v119
	s_waitcnt lgkmcnt(10)
	v_mfma_f32_16x16x32_bf16 v[42:45], v[214:217], v[82:85], v[42:45]
	v_exp_f32_e32 v120, v120
	v_mfma_f32_16x16x32_bf16 v[46:49], v[214:217], v[86:89], v[46:49]
	ds_read_b64_tr_b16 v[214:215], v239 offset:40960
	ds_read_b64_tr_b16 v[216:217], v239 offset:45056
	v_exp_f32_e32 v121, v121
	s_waitcnt lgkmcnt(10)
	v_mfma_f32_16x16x32_bf16 v[50:53], v[218:221], v[82:85], v[50:53]
	v_exp_f32_e32 v122, v122
	v_mfma_f32_16x16x32_bf16 v[54:57], v[218:221], v[86:89], v[54:57]
	ds_read_b64_tr_b16 v[218:219], v240 offset:40960
	ds_read_b64_tr_b16 v[220:221], v240 offset:45056
	v_exp_f32_e32 v123, v123
	s_waitcnt lgkmcnt(10)
	v_mfma_f32_16x16x32_bf16 v[58:61], v[222:225], v[82:85], v[58:61]
	v_exp_f32_e32 v124, v124
	v_mfma_f32_16x16x32_bf16 v[62:65], v[222:225], v[86:89], v[62:65]
	ds_read_b64_tr_b16 v[222:223], v241 offset:40960
	ds_read_b64_tr_b16 v[224:225], v241 offset:45056
	v_exp_f32_e32 v125, v125
	s_waitcnt lgkmcnt(10)
	v_mfma_f32_16x16x32_bf16 v[66:69], v[202:205], v[82:85], v[66:69]
	v_exp_f32_e32 v126, v126
	v_mfma_f32_16x16x32_bf16 v[70:73], v[202:205], v[86:89], v[70:73]
	ds_read_b64_tr_b16 v[202:203], v242 offset:40960
	ds_read_b64_tr_b16 v[204:205], v242 offset:45056
	v_exp_f32_e32 v127, v127
	s_waitcnt lgkmcnt(10)
	v_mfma_f32_16x16x32_bf16 v[74:77], v[206:209], v[82:85], v[74:77]
	v_exp_f32_e32 v128, v128
	v_mfma_f32_16x16x32_bf16 v[78:81], v[206:209], v[86:89], v[78:81]
	ds_read_b64_tr_b16 v[206:207], v243 offset:40960
	ds_read_b64_tr_b16 v[208:209], v243 offset:45056
	v_exp_f32_e32 v129, v129
	s_waitcnt lgkmcnt(10)
	v_mfma_f32_16x16x32_bf16 v[18:21], v[210:213], v[98:101], v[18:21]
	v_exp_f32_e32 v130, v130
	v_mfma_f32_16x16x32_bf16 v[22:25], v[210:213], v[102:105], v[22:25]
	ds_read_b64_tr_b16 v[210:211], v244 offset:40960
	ds_read_b64_tr_b16 v[212:213], v244 offset:45056
	v_exp_f32_e32 v131, v131
	s_waitcnt lgkmcnt(10)
	v_mfma_f32_16x16x32_bf16 v[26:29], v[214:217], v[98:101], v[26:29]
	v_exp_f32_e32 v132, v132
	v_mfma_f32_16x16x32_bf16 v[30:33], v[214:217], v[102:105], v[30:33]
	ds_read_b64_tr_b16 v[214:215], v245 offset:40960
	ds_read_b64_tr_b16 v[216:217], v245 offset:45056
	v_exp_f32_e32 v133, v133
	s_waitcnt lgkmcnt(10)
	v_mfma_f32_16x16x32_bf16 v[34:37], v[218:221], v[98:101], v[34:37]
	v_exp_f32_e32 v134, v134
	v_mfma_f32_16x16x32_bf16 v[38:41], v[218:221], v[102:105], v[38:41]
	v_exp_f32_e32 v135, v135
	s_waitcnt lgkmcnt(8)
	v_mfma_f32_16x16x32_bf16 v[42:45], v[222:225], v[98:101], v[42:45]
	v_exp_f32_e32 v136, v136
	v_mfma_f32_16x16x32_bf16 v[46:49], v[222:225], v[102:105], v[46:49]
	v_exp_f32_e32 v137, v137
	s_waitcnt lgkmcnt(6)
	v_mfma_f32_16x16x32_bf16 v[50:53], v[202:205], v[98:101], v[50:53]
	v_exp_f32_e32 v138, v138
	ds_read_b128 v[178:181], v234 offset:0
	v_mfma_f32_16x16x32_bf16 v[54:57], v[202:205], v[102:105], v[54:57]
	v_exp_f32_e32 v139, v139
	s_waitcnt lgkmcnt(5)
	v_mfma_f32_16x16x32_bf16 v[58:61], v[206:209], v[98:101], v[58:61]
	v_exp_f32_e32 v140, v140
	ds_read_b128 v[182:185], v234 offset:4096
	v_mfma_f32_16x16x32_bf16 v[62:65], v[206:209], v[102:105], v[62:65]
	v_exp_f32_e32 v141, v141
	s_waitcnt lgkmcnt(4)
	v_mfma_f32_16x16x32_bf16 v[66:69], v[210:213], v[98:101], v[66:69]
	v_exp_f32_e32 v142, v142
	ds_read_b128 v[186:189], v234 offset:8192
	v_mfma_f32_16x16x32_bf16 v[70:73], v[210:213], v[102:105], v[70:73]
	v_exp_f32_e32 v143, v143
	s_waitcnt lgkmcnt(3)
	v_mfma_f32_16x16x32_bf16 v[74:77], v[214:217], v[98:101], v[74:77]
	v_exp_f32_e32 v144, v144
	ds_read_b128 v[190:193], v234 offset:12288
	v_mfma_f32_16x16x32_bf16 v[78:81], v[214:217], v[102:105], v[78:81]
	v_exp_f32_e32 v145, v145
	s_waitcnt vmcnt(4)
	s_barrier
; #define SBAR() __builtin_amdgcn_sched_barrier(0)
; #define SLOAD(i, k0) do { sr_[i].vs0 = St::ld8(&Vh[(long)((k0) + sr) * LDK + sc]); sr_[i].vs1 = St::ld8(&Vh[(long)((k0) + 32 + sr) * LDK + sc]); \
;     sr_[i].ks0 = St::ld8(&Kh[(long)((k0) + sr) * LDK + sc]); sr_[i].ks1 = St::ld8(&Kh[(long)((k0) + 32 + sr) * LDK + sc]); } while (0)
; #define SWAIT() do { if constexpr (SDEPTH == 2) asm volatile("s_waitcnt vmcnt(4)" ::: "memory"); else asm volatile("s_waitcnt vmcnt(0)" ::: "memory"); } while (0)
; template <typename TQ> ...
;     ...
;   for (int j = 1; j + 1 < NT; j += 2) {
;     SBAR(); SLOAD(SO, (j + SDEPTH) * KVBLK); SBAR();
;     qkt(pB0, pB1, (bf16*)((char*)K_lds + SHM_K), qr, r32, hi, negm);
;     finishSM(pA0, pA1, l_reg, pa0, pa1, pa2, pa3); SBAR();
;     pv_d0(o, vb0, pa0, pa1, pa2, pa3); partialSM(pB0, pB1, mC);
;     __syncthreads(); SWAIT(); SWRITE(0, SE);
;     __syncthreads();
;     SBAR(); if (SDEPTH == 1 || j + 3 < NT) SLOAD(SE, (j + 1 + SDEPTH) * KVBLK); SBAR();
;     qkt(pA0, pA1, K_lds, qr, r32, hi, negm);
;     finishSM(pB0, pB1, l_reg, pa0, pa1, pa2, pa3); SBAR();
;     pv_d0(o, vb0 + (int)SHM_V, pa0, pa1, pa2, pa3); partialSM(pA0, pA1, mC);
	s_waitcnt lgkmcnt(3)
	v_mfma_f32_16x16x32_bf16 v[82:85], v[178:181], v[146:149], v[2:5]
	v_add_f32_e32 v250, v114, v250
	s_add_u32 s98, s98, 0x8000
	s_addc_u32 s99, s99, 0
	s_add_u32 s100, s100, 0x8000
	s_addc_u32 s101, s101, 0
	v_mfma_f32_16x16x32_bf16 v[86:89], v[178:181], v[162:165], v[2:5]
	ds_read_b128 v[178:181], v235 offset:0
	v_add_f32_e32 v250, v115, v250
	v_add_f32_e32 v250, v116, v250
	s_waitcnt lgkmcnt(3)
	v_mfma_f32_16x16x32_bf16 v[90:93], v[182:185], v[146:149], v[2:5]
	v_add_f32_e32 v250, v117, v250
	s_add_u32 m0, s79, 49152
	s_nop 0
	global_load_lds_dwordx4 v246, s[98:99]
	v_mfma_f32_16x16x32_bf16 v[94:97], v[182:185], v[162:165], v[2:5]
	ds_read_b128 v[182:185], v235 offset:4096
	v_add_f32_e32 v250, v122, v250
	v_add_f32_e32 v250, v123, v250
	s_waitcnt lgkmcnt(3)
	v_mfma_f32_16x16x32_bf16 v[98:101], v[186:189], v[146:149], v[2:5]
	v_add_f32_e32 v250, v124, v250
	v_mfma_f32_16x16x32_bf16 v[102:105], v[186:189], v[162:165], v[2:5]
	ds_read_b128 v[186:189], v235 offset:8192
	v_add_f32_e32 v250, v125, v250
	v_cvt_pk_bf16_f32 v114, v114, v115
	s_waitcnt lgkmcnt(3)
	v_mfma_f32_16x16x32_bf16 v[106:109], v[190:193], v[146:149], v[2:5]
	v_cvt_pk_bf16_f32 v115, v116, v117
	s_add_u32 m0, s79, 50176
	s_nop 0
	global_load_lds_dwordx4 v247, s[98:99]
	v_mfma_f32_16x16x32_bf16 v[110:113], v[190:193], v[162:165], v[2:5]
	ds_read_b128 v[190:193], v235 offset:12288
	v_cvt_pk_bf16_f32 v116, v122, v123
	v_cvt_pk_bf16_f32 v117, v124, v125
	s_waitcnt lgkmcnt(3)
	v_mfma_f32_16x16x32_bf16 v[82:85], v[178:181], v[150:153], v[82:85]
	v_add_f32_e32 v251, v118, v251
	v_mfma_f32_16x16x32_bf16 v[86:89], v[178:181], v[166:169], v[86:89]
	ds_read_b128 v[178:181], v236 offset:0
	v_add_f32_e32 v251, v119, v251
	v_add_f32_e32 v251, v120, v251
	s_waitcnt lgkmcnt(3)
	v_mfma_f32_16x16x32_bf16 v[90:93], v[182:185], v[150:153], v[90:93]
	v_add_f32_e32 v251, v121, v251
	s_add_u32 m0, s80, 32768
	s_nop 0
	global_load_lds_dwordx4 v248, s[100:101]
	v_mfma_f32_16x16x32_bf16 v[94:97], v[182:185], v[166:169], v[94:97]
	ds_read_b128 v[182:185], v236 offset:4096
	v_add_f32_e32 v251, v126, v251
	v_add_f32_e32 v251, v127, v251
	s_waitcnt lgkmcnt(3)
	v_mfma_f32_16x16x32_bf16 v[98:101], v[186:189], v[150:153], v[98:101]
	v_add_f32_e32 v251, v128, v251
	v_mfma_f32_16x16x32_bf16 v[102:105], v[186:189], v[166:169], v[102:105]
	ds_read_b128 v[186:189], v236 offset:8192
	v_add_f32_e32 v251, v129, v251
	v_cvt_pk_bf16_f32 v118, v118, v119
	s_waitcnt lgkmcnt(3)
	v_mfma_f32_16x16x32_bf16 v[106:109], v[190:193], v[150:153], v[106:109]
	v_cvt_pk_bf16_f32 v119, v120, v121
	s_add_u32 m0, s80, 33792
	s_nop 0
	global_load_lds_dwordx4 v249, s[100:101]
	v_mfma_f32_16x16x32_bf16 v[110:113], v[190:193], v[166:169], v[110:113]
	ds_read_b128 v[190:193], v236 offset:12288
	v_cvt_pk_bf16_f32 v120, v126, v127
	v_cvt_pk_bf16_f32 v121, v128, v129
	s_waitcnt lgkmcnt(3)
	v_mfma_f32_16x16x32_bf16 v[82:85], v[178:181], v[154:157], v[82:85]
	v_add_f32_e32 v250, v130, v250
	v_mfma_f32_16x16x32_bf16 v[86:89], v[178:181], v[170:173], v[86:89]
	ds_read_b128 v[178:181], v237 offset:0
	v_add_f32_e32 v250, v131, v250
	v_add_f32_e32 v250, v132, v250
	s_waitcnt lgkmcnt(3)
	v_mfma_f32_16x16x32_bf16 v[90:93], v[182:185], v[154:157], v[90:93]
	v_add_f32_e32 v250, v133, v250
	v_mfma_f32_16x16x32_bf16 v[94:97], v[182:185], v[170:173], v[94:97]
	ds_read_b128 v[182:185], v237 offset:4096
	v_add_f32_e32 v250, v138, v250
	v_add_f32_e32 v250, v139, v250
	s_waitcnt lgkmcnt(3)
	v_mfma_f32_16x16x32_bf16 v[98:101], v[186:189], v[154:157], v[98:101]
	v_add_f32_e32 v250, v140, v250
	ds_read_b64_tr_b16 v[202:203], v238 offset:49152
	ds_read_b64_tr_b16 v[204:205], v238 offset:53248
	v_mfma_f32_16x16x32_bf16 v[102:105], v[186:189], v[170:173], v[102:105]
	ds_read_b128 v[186:189], v237 offset:8192
	v_add_f32_e32 v250, v141, v250
	v_cvt_pk_bf16_f32 v130, v130, v131
	s_waitcnt lgkmcnt(5)
	v_mfma_f32_16x16x32_bf16 v[106:109], v[190:193], v[154:157], v[106:109]
	v_cvt_pk_bf16_f32 v131, v132, v133
	ds_read_b64_tr_b16 v[206:207], v239 offset:49152
	ds_read_b64_tr_b16 v[208:209], v239 offset:53248
	v_mfma_f32_16x16x32_bf16 v[110:113], v[190:193], v[170:173], v[110:113]
	ds_read_b128 v[190:193], v237 offset:12288
	v_cvt_pk_bf16_f32 v132, v138, v139
	v_cvt_pk_bf16_f32 v133, v140, v141
	s_waitcnt lgkmcnt(7)
	v_mfma_f32_16x16x32_bf16 v[82:85], v[178:181], v[158:161], v[82:85]
	v_add_f32_e32 v251, v134, v251
	ds_read_b64_tr_b16 v[210:211], v240 offset:49152
	ds_read_b64_tr_b16 v[212:213], v240 offset:53248
	v_mfma_f32_16x16x32_bf16 v[86:89], v[178:181], v[174:177], v[86:89]
	v_add_f32_e32 v251, v135, v251
	v_add_f32_e32 v251, v136, v251
	s_waitcnt lgkmcnt(8)
	v_mfma_f32_16x16x32_bf16 v[90:93], v[182:185], v[158:161], v[90:93]
	v_add_f32_e32 v251, v137, v251
	ds_read_b64_tr_b16 v[214:215], v241 offset:49152
	ds_read_b64_tr_b16 v[216:217], v241 offset:53248
	v_mfma_f32_16x16x32_bf16 v[94:97], v[182:185], v[174:177], v[94:97]
	v_add_f32_e32 v251, v142, v251
	v_add_f32_e32 v251, v143, v251
	s_waitcnt lgkmcnt(7)
	v_mfma_f32_16x16x32_bf16 v[98:101], v[186:189], v[158:161], v[98:101]
	v_add_f32_e32 v251, v144, v251
	ds_read_b64_tr_b16 v[218:219], v242 offset:49152
	ds_read_b64_tr_b16 v[220:221], v242 offset:53248
	v_mfma_f32_16x16x32_bf16 v[102:105], v[186:189], v[174:177], v[102:105]
	v_add_f32_e32 v251, v145, v251
	v_cvt_pk_bf16_f32 v134, v134, v135
	s_waitcnt lgkmcnt(6)
; __device__ __forceinline__ void finishSM(f32x16& p0, f32x16& p1, float& l_reg, bf16x8& pa0, bf16x8& pa1, bf16x8& pa2, bf16x8& pa3) {
;   for (int r = 0; r < 16; ++r) p1[r] = __builtin_amdgcn_exp2f(p1[r]);
;   float ps = 0; for (int r = 0; r < 16; ++r) ps += p0[r]; for (int r = 0; r < 16; ++r) ps += p1[r];
;   { auto rr = __builtin_amdgcn_permlane32_swap(__float_as_uint(ps), __float_as_uint(ps), false, false);
;     ps = __uint_as_float(rr[0]) + __uint_as_float(rr[1]); }
;   l_reg += ps;
;     ...
;   PK4(p0, 0, pa0); PK4(p0, 8, pa1); PK4(p1, 0, pa2); PK4(p1, 8, pa3);
;     ...
; }
; __device__ __forceinline__ void qkt(f32x16& p0, f32x16& p1, const bf16* Ks, const bf16x8* qr, int r32, int hi, const f32x16& negm) {
; #pragma unroll
;   for (int d0 = 0; d0 < 8; ++d0) { int cb = (d0 * 16 + hi * 8) * 2;
;     bf16x8 b0 = *reinterpret_cast<const bf16x8*>((const char*)Ks + KSWZ(r32, cb));
;     bf16x8 b1 = *reinterpret_cast<const bf16x8*>((const char*)Ks + KSWZ(32 + r32, cb));
;     if (d0 == 0) { p0 = __builtin_amdgcn_mfma_f32_32x32x16_bf16(b0, qr[0], negm, 0, 0, 0); p1 = __builtin_amdgcn_mfma_f32_32x32x16_bf16(b1, qr[0], negm, 0, 0, 0); }
;     else { p0 = __builtin_amdgcn_mfma_f32_32x32x16_bf16(b0, qr[d0], p0, 0, 0, 0); p1 = __builtin_amdgcn_mfma_f32_32x32x16_bf16(b1, qr[d0], p1, 0, 0, 0); } }
; }
; __device__ __forceinline__ int v_st(int k, int c) { const int kk = (k & ~0xC) | ((k & 4) << 1) | ((k & 8) >> 1); return ((kk >> 3) * 4 + (c >> 5)) * 512 + ((kk & 7) * 32 + (c & 31)) * 2; }
; __device__ __forceinline__ int v_rd_base(int lane) { return ((lane & 3) << 3) | (((lane >> 2) & 3) << 6) | (((lane >> 4) & 1) << 5) | (((lane >> 5) & 1) << 8); }
; template <int OFF> __device__ __forceinline__ s16x4 tr_read(int vb) {
;   s16x4 r; asm volatile("ds_read_b64_tr_b16 %0, %1 offset:%2" : "=&v"(r) : "v"(vb), "i"(OFF) : "memory"); return r;
; }
; template <int D0> __device__ __forceinline__ void pv_one(f32x16& od, int vb, bf16x8 pa0, bf16x8 pa1, bf16x8 pa2, bf16x8 pa3) {
;   const s16x4 l0 = tr_read<v_rd_off(D0, 0, 0)>(vb), h0 = tr_read<v_rd_off(D0, 0, 1)>(vb), l1 = tr_read<v_rd_off(D0, 1, 0)>(vb), h1 = tr_read<v_rd_off(D0, 1, 1)>(vb);
;   const s16x4 l2 = tr_read<v_rd_off(D0, 2, 0)>(vb), h2 = tr_read<v_rd_off(D0, 2, 1)>(vb), l3 = tr_read<v_rd_off(D0, 3, 0)>(vb), h3 = tr_read<v_rd_off(D0, 3, 1)>(vb);
;   asm volatile("s_waitcnt lgkmcnt(0)" ::: "memory"); SBAR();
	v_mfma_f32_16x16x32_bf16 v[106:109], v[190:193], v[158:161], v[106:109]
	v_cvt_pk_bf16_f32 v135, v136, v137
	ds_read_b64_tr_b16 v[222:223], v243 offset:49152
	ds_read_b64_tr_b16 v[224:225], v243 offset:53248
	v_mfma_f32_16x16x32_bf16 v[110:113], v[190:193], v[174:177], v[110:113]
	v_cvt_pk_bf16_f32 v136, v142, v143
	v_cvt_pk_bf16_f32 v137, v144, v145
	v_mfma_f32_16x16x32_bf16 v[18:21], v[202:205], v[114:117], v[18:21]
	v_exp_f32_e32 v82, v82
	v_mfma_f32_16x16x32_bf16 v[22:25], v[202:205], v[118:121], v[22:25]
	ds_read_b64_tr_b16 v[202:203], v244 offset:49152
	ds_read_b64_tr_b16 v[204:205], v244 offset:53248
	v_exp_f32_e32 v83, v83
	v_mfma_f32_16x16x32_bf16 v[26:29], v[206:209], v[114:117], v[26:29]
	v_exp_f32_e32 v84, v84
	v_mfma_f32_16x16x32_bf16 v[30:33], v[206:209], v[118:121], v[30:33]
	ds_read_b64_tr_b16 v[206:207], v245 offset:49152
	ds_read_b64_tr_b16 v[208:209], v245 offset:53248
	v_exp_f32_e32 v85, v85
	s_waitcnt lgkmcnt(10)
	v_mfma_f32_16x16x32_bf16 v[34:37], v[210:213], v[114:117], v[34:37]
	v_exp_f32_e32 v86, v86
	v_mfma_f32_16x16x32_bf16 v[38:41], v[210:213], v[118:121], v[38:41]
	ds_read_b64_tr_b16 v[210:211], v238 offset:57344
	ds_read_b64_tr_b16 v[212:213], v238 offset:61440
	v_exp_f32_e32 v87, v87
	s_waitcnt lgkmcnt(10)
	v_mfma_f32_16x16x32_bf16 v[42:45], v[214:217], v[114:117], v[42:45]
	v_exp_f32_e32 v88, v88
	v_mfma_f32_16x16x32_bf16 v[46:49], v[214:217], v[118:121], v[46:49]
	ds_read_b64_tr_b16 v[214:215], v239 offset:57344
	ds_read_b64_tr_b16 v[216:217], v239 offset:61440
	v_exp_f32_e32 v89, v89
	s_waitcnt lgkmcnt(10)
	v_mfma_f32_16x16x32_bf16 v[50:53], v[218:221], v[114:117], v[50:53]
	v_exp_f32_e32 v90, v90
	v_mfma_f32_16x16x32_bf16 v[54:57], v[218:221], v[118:121], v[54:57]
	ds_read_b64_tr_b16 v[218:219], v240 offset:57344
	ds_read_b64_tr_b16 v[220:221], v240 offset:61440
	v_exp_f32_e32 v91, v91
	s_waitcnt lgkmcnt(10)
	v_mfma_f32_16x16x32_bf16 v[58:61], v[222:225], v[114:117], v[58:61]
	v_exp_f32_e32 v92, v92
	v_mfma_f32_16x16x32_bf16 v[62:65], v[222:225], v[118:121], v[62:65]
	ds_read_b64_tr_b16 v[222:223], v241 offset:57344
	ds_read_b64_tr_b16 v[224:225], v241 offset:61440
	v_exp_f32_e32 v93, v93
	s_waitcnt lgkmcnt(10)
	v_mfma_f32_16x16x32_bf16 v[66:69], v[202:205], v[114:117], v[66:69]
	v_exp_f32_e32 v94, v94
	v_mfma_f32_16x16x32_bf16 v[70:73], v[202:205], v[118:121], v[70:73]
	ds_read_b64_tr_b16 v[202:203], v242 offset:57344
	ds_read_b64_tr_b16 v[204:205], v242 offset:61440
	v_exp_f32_e32 v95, v95
	s_waitcnt lgkmcnt(10)
	v_mfma_f32_16x16x32_bf16 v[74:77], v[206:209], v[114:117], v[74:77]
	v_exp_f32_e32 v96, v96
	v_mfma_f32_16x16x32_bf16 v[78:81], v[206:209], v[118:121], v[78:81]
	ds_read_b64_tr_b16 v[206:207], v243 offset:57344
	ds_read_b64_tr_b16 v[208:209], v243 offset:61440
	v_exp_f32_e32 v97, v97
	s_waitcnt lgkmcnt(10)
	v_mfma_f32_16x16x32_bf16 v[18:21], v[210:213], v[130:133], v[18:21]
	v_exp_f32_e32 v98, v98
	v_mfma_f32_16x16x32_bf16 v[22:25], v[210:213], v[134:137], v[22:25]
	ds_read_b64_tr_b16 v[210:211], v244 offset:57344
	ds_read_b64_tr_b16 v[212:213], v244 offset:61440
	v_exp_f32_e32 v99, v99
	s_waitcnt lgkmcnt(10)
	v_mfma_f32_16x16x32_bf16 v[26:29], v[214:217], v[130:133], v[26:29]
	v_exp_f32_e32 v100, v100
	v_mfma_f32_16x16x32_bf16 v[30:33], v[214:217], v[134:137], v[30:33]
	ds_read_b64_tr_b16 v[214:215], v245 offset:57344
	ds_read_b64_tr_b16 v[216:217], v245 offset:61440
	v_exp_f32_e32 v101, v101
	s_waitcnt lgkmcnt(10)
	v_mfma_f32_16x16x32_bf16 v[34:37], v[218:221], v[130:133], v[34:37]
	v_exp_f32_e32 v102, v102
	v_mfma_f32_16x16x32_bf16 v[38:41], v[218:221], v[134:137], v[38:41]
	v_exp_f32_e32 v103, v103
	s_waitcnt lgkmcnt(8)
	v_mfma_f32_16x16x32_bf16 v[42:45], v[222:225], v[130:133], v[42:45]
	v_exp_f32_e32 v104, v104
	v_mfma_f32_16x16x32_bf16 v[46:49], v[222:225], v[134:137], v[46:49]
	v_exp_f32_e32 v105, v105
	s_waitcnt lgkmcnt(6)
	v_mfma_f32_16x16x32_bf16 v[50:53], v[202:205], v[130:133], v[50:53]
	v_exp_f32_e32 v106, v106
	ds_read_b128 v[178:181], v234 offset:16384
	v_mfma_f32_16x16x32_bf16 v[54:57], v[202:205], v[134:137], v[54:57]
	v_exp_f32_e32 v107, v107
	s_waitcnt lgkmcnt(5)
	v_mfma_f32_16x16x32_bf16 v[58:61], v[206:209], v[130:133], v[58:61]
	v_exp_f32_e32 v108, v108
	ds_read_b128 v[182:185], v234 offset:20480
	v_mfma_f32_16x16x32_bf16 v[62:65], v[206:209], v[134:137], v[62:65]
	v_exp_f32_e32 v109, v109
	s_waitcnt lgkmcnt(4)
	v_mfma_f32_16x16x32_bf16 v[66:69], v[210:213], v[130:133], v[66:69]
	v_exp_f32_e32 v110, v110
	ds_read_b128 v[186:189], v234 offset:24576
	v_mfma_f32_16x16x32_bf16 v[70:73], v[210:213], v[134:137], v[70:73]
	v_exp_f32_e32 v111, v111
	s_waitcnt lgkmcnt(3)
	v_mfma_f32_16x16x32_bf16 v[74:77], v[214:217], v[130:133], v[74:77]
	v_exp_f32_e32 v112, v112
	ds_read_b128 v[190:193], v234 offset:28672
	v_mfma_f32_16x16x32_bf16 v[78:81], v[214:217], v[134:137], v[78:81]
	v_exp_f32_e32 v113, v113
	s_waitcnt vmcnt(4)
	s_add_i32 s15, s15, 1
	s_cmp_lt_u32 s15, 32
	s_cbranch_scc1 .Lattn_loop
	s_barrier
; #define SBAR() __builtin_amdgcn_sched_barrier(0)
; template <typename TQ> ...
;     ...
;   SBAR(); qkt(pB0, pB1, (bf16*)((char*)K_lds + SHM_K), qr, r32, hi, negm);
;   finishSM(pA0, pA1, l_reg, pa0, pa1, pa2, pa3); SBAR();
;   pv_d0(o, vb0, pa0, pa1, pa2, pa3); partialSM(pB0, pB1, mC);
	s_waitcnt lgkmcnt(3)
	v_mfma_f32_16x16x32_bf16 v[114:117], v[178:181], v[146:149], v[2:5]
	v_add_f32_e32 v250, v82, v250
	s_add_u32 s98, s98, 0x8000
	s_addc_u32 s99, s99, 0
	s_add_u32 s100, s100, 0x8000
	s_addc_u32 s101, s101, 0
	v_mfma_f32_16x16x32_bf16 v[118:121], v[178:181], v[162:165], v[2:5]
	ds_read_b128 v[178:181], v235 offset:16384
	v_add_f32_e32 v250, v83, v250
	v_add_f32_e32 v250, v84, v250
	s_waitcnt lgkmcnt(3)
	v_mfma_f32_16x16x32_bf16 v[122:125], v[182:185], v[146:149], v[2:5]
	v_add_f32_e32 v250, v85, v250
	s_add_u32 m0, s80, 49152
	s_nop 0
	global_load_lds_dwordx4 v248, s[100:101]
	v_mfma_f32_16x16x32_bf16 v[126:129], v[182:185], v[162:165], v[2:5]
	ds_read_b128 v[182:185], v235 offset:20480
	v_add_f32_e32 v250, v90, v250
	v_add_f32_e32 v250, v91, v250
	s_waitcnt lgkmcnt(3)
	v_mfma_f32_16x16x32_bf16 v[130:133], v[186:189], v[146:149], v[2:5]
	v_add_f32_e32 v250, v92, v250
	v_mfma_f32_16x16x32_bf16 v[134:137], v[186:189], v[162:165], v[2:5]
	ds_read_b128 v[186:189], v235 offset:24576
	v_add_f32_e32 v250, v93, v250
	v_cvt_pk_bf16_f32 v82, v82, v83
	s_waitcnt lgkmcnt(3)
	v_mfma_f32_16x16x32_bf16 v[138:141], v[190:193], v[146:149], v[2:5]
	v_cvt_pk_bf16_f32 v83, v84, v85
	s_add_u32 m0, s80, 50176
	s_nop 0
	global_load_lds_dwordx4 v249, s[100:101]
	v_mfma_f32_16x16x32_bf16 v[142:145], v[190:193], v[162:165], v[2:5]
	ds_read_b128 v[190:193], v235 offset:28672
	v_cvt_pk_bf16_f32 v84, v90, v91
	v_cvt_pk_bf16_f32 v85, v92, v93
	s_waitcnt lgkmcnt(3)
	v_mfma_f32_16x16x32_bf16 v[114:117], v[178:181], v[150:153], v[114:117]
	v_add_f32_e32 v251, v86, v251
	v_mfma_f32_16x16x32_bf16 v[118:121], v[178:181], v[166:169], v[118:121]
	ds_read_b128 v[178:181], v236 offset:16384
	v_add_f32_e32 v251, v87, v251
	v_add_f32_e32 v251, v88, v251
	s_waitcnt lgkmcnt(3)
	v_mfma_f32_16x16x32_bf16 v[122:125], v[182:185], v[150:153], v[122:125]
	v_add_f32_e32 v251, v89, v251
	v_mfma_f32_16x16x32_bf16 v[126:129], v[182:185], v[166:169], v[126:129]
	ds_read_b128 v[182:185], v236 offset:20480
	v_add_f32_e32 v251, v94, v251
	v_add_f32_e32 v251, v95, v251
	s_waitcnt lgkmcnt(3)
	v_mfma_f32_16x16x32_bf16 v[130:133], v[186:189], v[150:153], v[130:133]
	v_add_f32_e32 v251, v96, v251
	v_mfma_f32_16x16x32_bf16 v[134:137], v[186:189], v[166:169], v[134:137]
	ds_read_b128 v[186:189], v236 offset:24576
	v_add_f32_e32 v251, v97, v251
	v_cvt_pk_bf16_f32 v86, v86, v87
	s_waitcnt lgkmcnt(3)
	v_mfma_f32_16x16x32_bf16 v[138:141], v[190:193], v[150:153], v[138:141]
	v_cvt_pk_bf16_f32 v87, v88, v89
	v_mfma_f32_16x16x32_bf16 v[142:145], v[190:193], v[166:169], v[142:145]
	ds_read_b128 v[190:193], v236 offset:28672
	v_cvt_pk_bf16_f32 v88, v94, v95
	v_cvt_pk_bf16_f32 v89, v96, v97
	s_waitcnt lgkmcnt(3)
	v_mfma_f32_16x16x32_bf16 v[114:117], v[178:181], v[154:157], v[114:117]
	v_add_f32_e32 v250, v98, v250
	v_mfma_f32_16x16x32_bf16 v[118:121], v[178:181], v[170:173], v[118:121]
	ds_read_b128 v[178:181], v237 offset:16384
	v_add_f32_e32 v250, v99, v250
	v_add_f32_e32 v250, v100, v250
	s_waitcnt lgkmcnt(3)
	v_mfma_f32_16x16x32_bf16 v[122:125], v[182:185], v[154:157], v[122:125]
	v_add_f32_e32 v250, v101, v250
	v_mfma_f32_16x16x32_bf16 v[126:129], v[182:185], v[170:173], v[126:129]
	ds_read_b128 v[182:185], v237 offset:20480
	v_add_f32_e32 v250, v106, v250
	v_add_f32_e32 v250, v107, v250
	s_waitcnt lgkmcnt(3)
	v_mfma_f32_16x16x32_bf16 v[130:133], v[186:189], v[154:157], v[130:133]
	v_add_f32_e32 v250, v108, v250
	ds_read_b64_tr_b16 v[202:203], v238 offset:0
	ds_read_b64_tr_b16 v[204:205], v238 offset:4096
	v_mfma_f32_16x16x32_bf16 v[134:137], v[186:189], v[170:173], v[134:137]
	ds_read_b128 v[186:189], v237 offset:24576
	v_add_f32_e32 v250, v109, v250
	v_cvt_pk_bf16_f32 v98, v98, v99
	s_waitcnt lgkmcnt(5)
	v_mfma_f32_16x16x32_bf16 v[138:141], v[190:193], v[154:157], v[138:141]
	v_cvt_pk_bf16_f32 v99, v100, v101
	ds_read_b64_tr_b16 v[206:207], v239 offset:0
	ds_read_b64_tr_b16 v[208:209], v239 offset:4096
	v_mfma_f32_16x16x32_bf16 v[142:145], v[190:193], v[170:173], v[142:145]
	ds_read_b128 v[190:193], v237 offset:28672
	v_cvt_pk_bf16_f32 v100, v106, v107
	v_cvt_pk_bf16_f32 v101, v108, v109
	s_waitcnt lgkmcnt(7)
	v_mfma_f32_16x16x32_bf16 v[114:117], v[178:181], v[158:161], v[114:117]
	v_add_f32_e32 v251, v102, v251
	ds_read_b64_tr_b16 v[210:211], v240 offset:0
	ds_read_b64_tr_b16 v[212:213], v240 offset:4096
	v_mfma_f32_16x16x32_bf16 v[118:121], v[178:181], v[174:177], v[118:121]
	v_add_f32_e32 v251, v103, v251
	v_add_f32_e32 v251, v104, v251
	s_waitcnt lgkmcnt(8)
	v_mfma_f32_16x16x32_bf16 v[122:125], v[182:185], v[158:161], v[122:125]
	v_add_f32_e32 v251, v105, v251
	ds_read_b64_tr_b16 v[214:215], v241 offset:0
	ds_read_b64_tr_b16 v[216:217], v241 offset:4096
	v_mfma_f32_16x16x32_bf16 v[126:129], v[182:185], v[174:177], v[126:129]
	v_add_f32_e32 v251, v110, v251
	v_add_f32_e32 v251, v111, v251
	s_waitcnt lgkmcnt(7)
	v_mfma_f32_16x16x32_bf16 v[130:133], v[186:189], v[158:161], v[130:133]
	v_add_f32_e32 v251, v112, v251
	ds_read_b64_tr_b16 v[218:219], v242 offset:0
	ds_read_b64_tr_b16 v[220:221], v242 offset:4096
	v_mfma_f32_16x16x32_bf16 v[134:137], v[186:189], v[174:177], v[134:137]
	v_add_f32_e32 v251, v113, v251
	v_cvt_pk_bf16_f32 v102, v102, v103
	s_waitcnt lgkmcnt(6)
; __device__ __forceinline__ void finishSM(f32x16& p0, f32x16& p1, float& l_reg, bf16x8& pa0, bf16x8& pa1, bf16x8& pa2, bf16x8& pa3) {
;   for (int r = 0; r < 16; ++r) p1[r] = __builtin_amdgcn_exp2f(p1[r]);
;   float ps = 0; for (int r = 0; r < 16; ++r) ps += p0[r]; for (int r = 0; r < 16; ++r) ps += p1[r];
;   { auto rr = __builtin_amdgcn_permlane32_swap(__float_as_uint(ps), __float_as_uint(ps), false, false);
;     ps = __uint_as_float(rr[0]) + __uint_as_float(rr[1]); }
;   l_reg += ps;
;     ...
;   PK4(p0, 0, pa0); PK4(p0, 8, pa1); PK4(p1, 0, pa2); PK4(p1, 8, pa3);
;     ...
; }
; __device__ __forceinline__ void qkt(f32x16& p0, f32x16& p1, const bf16* Ks, const bf16x8* qr, int r32, int hi, const f32x16& negm) {
; #pragma unroll
;   for (int d0 = 0; d0 < 8; ++d0) { int cb = (d0 * 16 + hi * 8) * 2;
;     bf16x8 b0 = *reinterpret_cast<const bf16x8*>((const char*)Ks + KSWZ(r32, cb));
;     bf16x8 b1 = *reinterpret_cast<const bf16x8*>((const char*)Ks + KSWZ(32 + r32, cb));
;     if (d0 == 0) { p0 = __builtin_amdgcn_mfma_f32_32x32x16_bf16(b0, qr[0], negm, 0, 0, 0); p1 = __builtin_amdgcn_mfma_f32_32x32x16_bf16(b1, qr[0], negm, 0, 0, 0); }
;     else { p0 = __builtin_amdgcn_mfma_f32_32x32x16_bf16(b0, qr[d0], p0, 0, 0, 0); p1 = __builtin_amdgcn_mfma_f32_32x32x16_bf16(b1, qr[d0], p1, 0, 0, 0); } }
; }
; __device__ __forceinline__ int v_st(int k, int c) { const int kk = (k & ~0xC) | ((k & 4) << 1) | ((k & 8) >> 1); return ((kk >> 3) * 4 + (c >> 5)) * 512 + ((kk & 7) * 32 + (c & 31)) * 2; }
; __device__ __forceinline__ int v_rd_base(int lane) { return ((lane & 3) << 3) | (((lane >> 2) & 3) << 6) | (((lane >> 4) & 1) << 5) | (((lane >> 5) & 1) << 8); }
; template <int OFF> __device__ __forceinline__ s16x4 tr_read(int vb) {
;   s16x4 r; asm volatile("ds_read_b64_tr_b16 %0, %1 offset:%2" : "=&v"(r) : "v"(vb), "i"(OFF) : "memory"); return r;
; }
; template <int D0> __device__ __forceinline__ void pv_one(f32x16& od, int vb, bf16x8 pa0, bf16x8 pa1, bf16x8 pa2, bf16x8 pa3) {
;   const s16x4 l0 = tr_read<v_rd_off(D0, 0, 0)>(vb), h0 = tr_read<v_rd_off(D0, 0, 1)>(vb), l1 = tr_read<v_rd_off(D0, 1, 0)>(vb), h1 = tr_read<v_rd_off(D0, 1, 1)>(vb);
;   const s16x4 l2 = tr_read<v_rd_off(D0, 2, 0)>(vb), h2 = tr_read<v_rd_off(D0, 2, 1)>(vb), l3 = tr_read<v_rd_off(D0, 3, 0)>(vb), h3 = tr_read<v_rd_off(D0, 3, 1)>(vb);
;   asm volatile("s_waitcnt lgkmcnt(0)" ::: "memory"); SBAR();
	v_mfma_f32_16x16x32_bf16 v[138:141], v[190:193], v[158:161], v[138:141]
	v_cvt_pk_bf16_f32 v103, v104, v105
	ds_read_b64_tr_b16 v[222:223], v243 offset:0
	ds_read_b64_tr_b16 v[224:225], v243 offset:4096
	v_mfma_f32_16x16x32_bf16 v[142:145], v[190:193], v[174:177], v[142:145]
	v_cvt_pk_bf16_f32 v104, v110, v111
	v_cvt_pk_bf16_f32 v105, v112, v113
	v_mfma_f32_16x16x32_bf16 v[18:21], v[202:205], v[82:85], v[18:21]
	v_exp_f32_e32 v114, v114
	v_mfma_f32_16x16x32_bf16 v[22:25], v[202:205], v[86:89], v[22:25]
	ds_read_b64_tr_b16 v[202:203], v244 offset:0
	ds_read_b64_tr_b16 v[204:205], v244 offset:4096
	v_exp_f32_e32 v115, v115
	v_mfma_f32_16x16x32_bf16 v[26:29], v[206:209], v[82:85], v[26:29]
	v_exp_f32_e32 v116, v116
	v_mfma_f32_16x16x32_bf16 v[30:33], v[206:209], v[86:89], v[30:33]
	ds_read_b64_tr_b16 v[206:207], v245 offset:0
	ds_read_b64_tr_b16 v[208:209], v245 offset:4096
	v_exp_f32_e32 v117, v117
	s_waitcnt lgkmcnt(10)
	v_mfma_f32_16x16x32_bf16 v[34:37], v[210:213], v[82:85], v[34:37]
	v_exp_f32_e32 v118, v118
	v_mfma_f32_16x16x32_bf16 v[38:41], v[210:213], v[86:89], v[38:41]
	ds_read_b64_tr_b16 v[210:211], v238 offset:8192
	ds_read_b64_tr_b16 v[212:213], v238 offset:12288
	v_exp_f32_e32 v119, v119
	s_waitcnt lgkmcnt(10)
	v_mfma_f32_16x16x32_bf16 v[42:45], v[214:217], v[82:85], v[42:45]
	v_exp_f32_e32 v120, v120
	v_mfma_f32_16x16x32_bf16 v[46:49], v[214:217], v[86:89], v[46:49]
	ds_read_b64_tr_b16 v[214:215], v239 offset:8192
	ds_read_b64_tr_b16 v[216:217], v239 offset:12288
	v_exp_f32_e32 v121, v121
	s_waitcnt lgkmcnt(10)
	v_mfma_f32_16x16x32_bf16 v[50:53], v[218:221], v[82:85], v[50:53]
	v_exp_f32_e32 v122, v122
	v_mfma_f32_16x16x32_bf16 v[54:57], v[218:221], v[86:89], v[54:57]
	ds_read_b64_tr_b16 v[218:219], v240 offset:8192
	ds_read_b64_tr_b16 v[220:221], v240 offset:12288
	v_exp_f32_e32 v123, v123
	s_waitcnt lgkmcnt(10)
	v_mfma_f32_16x16x32_bf16 v[58:61], v[222:225], v[82:85], v[58:61]
	v_exp_f32_e32 v124, v124
	v_mfma_f32_16x16x32_bf16 v[62:65], v[222:225], v[86:89], v[62:65]
	ds_read_b64_tr_b16 v[222:223], v241 offset:8192
	ds_read_b64_tr_b16 v[224:225], v241 offset:12288
	v_exp_f32_e32 v125, v125
	s_waitcnt lgkmcnt(10)
	v_mfma_f32_16x16x32_bf16 v[66:69], v[202:205], v[82:85], v[66:69]
	v_exp_f32_e32 v126, v126
	v_mfma_f32_16x16x32_bf16 v[70:73], v[202:205], v[86:89], v[70:73]
	ds_read_b64_tr_b16 v[202:203], v242 offset:8192
	ds_read_b64_tr_b16 v[204:205], v242 offset:12288
	v_exp_f32_e32 v127, v127
	s_waitcnt lgkmcnt(10)
	v_mfma_f32_16x16x32_bf16 v[74:77], v[206:209], v[82:85], v[74:77]
	v_exp_f32_e32 v128, v128
	v_mfma_f32_16x16x32_bf16 v[78:81], v[206:209], v[86:89], v[78:81]
	ds_read_b64_tr_b16 v[206:207], v243 offset:8192
	ds_read_b64_tr_b16 v[208:209], v243 offset:12288
	v_exp_f32_e32 v129, v129
	s_waitcnt lgkmcnt(10)
	v_mfma_f32_16x16x32_bf16 v[18:21], v[210:213], v[98:101], v[18:21]
	v_exp_f32_e32 v130, v130
	v_mfma_f32_16x16x32_bf16 v[22:25], v[210:213], v[102:105], v[22:25]
	ds_read_b64_tr_b16 v[210:211], v244 offset:8192
	ds_read_b64_tr_b16 v[212:213], v244 offset:12288
	v_exp_f32_e32 v131, v131
	s_waitcnt lgkmcnt(10)
	v_mfma_f32_16x16x32_bf16 v[26:29], v[214:217], v[98:101], v[26:29]
	v_exp_f32_e32 v132, v132
	v_mfma_f32_16x16x32_bf16 v[30:33], v[214:217], v[102:105], v[30:33]
	ds_read_b64_tr_b16 v[214:215], v245 offset:8192
	ds_read_b64_tr_b16 v[216:217], v245 offset:12288
	v_exp_f32_e32 v133, v133
	s_waitcnt lgkmcnt(10)
	v_mfma_f32_16x16x32_bf16 v[34:37], v[218:221], v[98:101], v[34:37]
	v_exp_f32_e32 v134, v134
	v_mfma_f32_16x16x32_bf16 v[38:41], v[218:221], v[102:105], v[38:41]
	v_exp_f32_e32 v135, v135
	s_waitcnt lgkmcnt(8)
	v_mfma_f32_16x16x32_bf16 v[42:45], v[222:225], v[98:101], v[42:45]
	v_exp_f32_e32 v136, v136
	v_mfma_f32_16x16x32_bf16 v[46:49], v[222:225], v[102:105], v[46:49]
	v_exp_f32_e32 v137, v137
	s_waitcnt lgkmcnt(6)
	v_mfma_f32_16x16x32_bf16 v[50:53], v[202:205], v[98:101], v[50:53]
	v_exp_f32_e32 v138, v138
	ds_read_b128 v[178:181], v234 offset:32768
	v_mfma_f32_16x16x32_bf16 v[54:57], v[202:205], v[102:105], v[54:57]
	v_exp_f32_e32 v139, v139
	s_waitcnt lgkmcnt(5)
	v_mfma_f32_16x16x32_bf16 v[58:61], v[206:209], v[98:101], v[58:61]
	v_exp_f32_e32 v140, v140
	ds_read_b128 v[182:185], v234 offset:36864
	v_mfma_f32_16x16x32_bf16 v[62:65], v[206:209], v[102:105], v[62:65]
	v_exp_f32_e32 v141, v141
	s_waitcnt lgkmcnt(4)
	v_mfma_f32_16x16x32_bf16 v[66:69], v[210:213], v[98:101], v[66:69]
	v_exp_f32_e32 v142, v142
	ds_read_b128 v[186:189], v234 offset:40960
	v_mfma_f32_16x16x32_bf16 v[70:73], v[210:213], v[102:105], v[70:73]
	v_exp_f32_e32 v143, v143
	s_waitcnt lgkmcnt(3)
	v_mfma_f32_16x16x32_bf16 v[74:77], v[214:217], v[98:101], v[74:77]
	v_exp_f32_e32 v144, v144
	ds_read_b128 v[190:193], v234 offset:45056
	v_mfma_f32_16x16x32_bf16 v[78:81], v[214:217], v[102:105], v[78:81]
	v_exp_f32_e32 v145, v145
	s_waitcnt vmcnt(2)
	s_barrier
; #define SBAR() __builtin_amdgcn_sched_barrier(0)
; template <typename TQ> ...
;     ...
;   pv_d0(o, vb0, pa0, pa1, pa2, pa3); partialSM(pB0, pB1, mC);
;   __syncthreads();
;   finishSM(pB0, pB1, l_reg, pa0, pa1, pa2, pa3); SBAR();
;   pv_d0(o, vb0 + (int)SHM_V, pa0, pa1, pa2, pa3);
	s_waitcnt lgkmcnt(3)
	v_mfma_f32_16x16x32_bf16 v[82:85], v[178:181], v[146:149], v[2:5]
	v_add_f32_e32 v250, v114, v250
	v_mfma_f32_16x16x32_bf16 v[86:89], v[178:181], v[162:165], v[2:5]
	ds_read_b128 v[178:181], v235 offset:32768
	v_add_f32_e32 v250, v115, v250
	v_add_f32_e32 v250, v116, v250
	s_waitcnt lgkmcnt(3)
	v_mfma_f32_16x16x32_bf16 v[90:93], v[182:185], v[146:149], v[2:5]
	v_add_f32_e32 v250, v117, v250
	v_mfma_f32_16x16x32_bf16 v[94:97], v[182:185], v[162:165], v[2:5]
	ds_read_b128 v[182:185], v235 offset:36864
	v_add_f32_e32 v250, v122, v250
	v_add_f32_e32 v250, v123, v250
	s_waitcnt lgkmcnt(3)
	v_mfma_f32_16x16x32_bf16 v[98:101], v[186:189], v[146:149], v[2:5]
	v_add_f32_e32 v250, v124, v250
	v_mfma_f32_16x16x32_bf16 v[102:105], v[186:189], v[162:165], v[2:5]
	ds_read_b128 v[186:189], v235 offset:40960
	v_add_f32_e32 v250, v125, v250
	v_cvt_pk_bf16_f32 v114, v114, v115
	s_waitcnt lgkmcnt(3)
	v_mfma_f32_16x16x32_bf16 v[106:109], v[190:193], v[146:149], v[2:5]
	v_cvt_pk_bf16_f32 v115, v116, v117
	v_mfma_f32_16x16x32_bf16 v[110:113], v[190:193], v[162:165], v[2:5]
	ds_read_b128 v[190:193], v235 offset:45056
	v_cvt_pk_bf16_f32 v116, v122, v123
	v_cvt_pk_bf16_f32 v117, v124, v125
	s_waitcnt lgkmcnt(3)
	v_mfma_f32_16x16x32_bf16 v[82:85], v[178:181], v[150:153], v[82:85]
	v_add_f32_e32 v251, v118, v251
	v_mfma_f32_16x16x32_bf16 v[86:89], v[178:181], v[166:169], v[86:89]
	ds_read_b128 v[178:181], v236 offset:32768
	v_add_f32_e32 v251, v119, v251
	v_add_f32_e32 v251, v120, v251
	s_waitcnt lgkmcnt(3)
	v_mfma_f32_16x16x32_bf16 v[90:93], v[182:185], v[150:153], v[90:93]
	v_add_f32_e32 v251, v121, v251
	v_mfma_f32_16x16x32_bf16 v[94:97], v[182:185], v[166:169], v[94:97]
	ds_read_b128 v[182:185], v236 offset:36864
	v_add_f32_e32 v251, v126, v251
	v_add_f32_e32 v251, v127, v251
	s_waitcnt lgkmcnt(3)
	v_mfma_f32_16x16x32_bf16 v[98:101], v[186:189], v[150:153], v[98:101]
	v_add_f32_e32 v251, v128, v251
	v_mfma_f32_16x16x32_bf16 v[102:105], v[186:189], v[166:169], v[102:105]
	ds_read_b128 v[186:189], v236 offset:40960
	v_add_f32_e32 v251, v129, v251
	v_cvt_pk_bf16_f32 v118, v118, v119
	s_waitcnt lgkmcnt(3)
	v_mfma_f32_16x16x32_bf16 v[106:109], v[190:193], v[150:153], v[106:109]
	v_cvt_pk_bf16_f32 v119, v120, v121
	v_mfma_f32_16x16x32_bf16 v[110:113], v[190:193], v[166:169], v[110:113]
	ds_read_b128 v[190:193], v236 offset:45056
	v_cvt_pk_bf16_f32 v120, v126, v127
	v_cvt_pk_bf16_f32 v121, v128, v129
	s_waitcnt lgkmcnt(3)
	v_mfma_f32_16x16x32_bf16 v[82:85], v[178:181], v[154:157], v[82:85]
	v_add_f32_e32 v250, v130, v250
	v_mfma_f32_16x16x32_bf16 v[86:89], v[178:181], v[170:173], v[86:89]
	ds_read_b128 v[178:181], v237 offset:32768
	v_add_f32_e32 v250, v131, v250
	v_add_f32_e32 v250, v132, v250
	s_waitcnt lgkmcnt(3)
	v_mfma_f32_16x16x32_bf16 v[90:93], v[182:185], v[154:157], v[90:93]
	v_add_f32_e32 v250, v133, v250
	v_mfma_f32_16x16x32_bf16 v[94:97], v[182:185], v[170:173], v[94:97]
	ds_read_b128 v[182:185], v237 offset:36864
	v_add_f32_e32 v250, v138, v250
	v_add_f32_e32 v250, v139, v250
	s_waitcnt lgkmcnt(3)
	v_mfma_f32_16x16x32_bf16 v[98:101], v[186:189], v[154:157], v[98:101]
	v_add_f32_e32 v250, v140, v250
	ds_read_b64_tr_b16 v[202:203], v238 offset:16384
	ds_read_b64_tr_b16 v[204:205], v238 offset:20480
	v_mfma_f32_16x16x32_bf16 v[102:105], v[186:189], v[170:173], v[102:105]
	ds_read_b128 v[186:189], v237 offset:40960
	v_add_f32_e32 v250, v141, v250
	v_cvt_pk_bf16_f32 v130, v130, v131
	s_waitcnt lgkmcnt(5)
	v_mfma_f32_16x16x32_bf16 v[106:109], v[190:193], v[154:157], v[106:109]
	v_cvt_pk_bf16_f32 v131, v132, v133
	ds_read_b64_tr_b16 v[206:207], v239 offset:16384
	ds_read_b64_tr_b16 v[208:209], v239 offset:20480
	v_mfma_f32_16x16x32_bf16 v[110:113], v[190:193], v[170:173], v[110:113]
	ds_read_b128 v[190:193], v237 offset:45056
	v_cvt_pk_bf16_f32 v132, v138, v139
	v_cvt_pk_bf16_f32 v133, v140, v141
	s_waitcnt lgkmcnt(7)
	v_mfma_f32_16x16x32_bf16 v[82:85], v[178:181], v[158:161], v[82:85]
	v_add_f32_e32 v251, v134, v251
	ds_read_b64_tr_b16 v[210:211], v240 offset:16384
	ds_read_b64_tr_b16 v[212:213], v240 offset:20480
	v_mfma_f32_16x16x32_bf16 v[86:89], v[178:181], v[174:177], v[86:89]
	v_add_f32_e32 v251, v135, v251
	v_add_f32_e32 v251, v136, v251
	s_waitcnt lgkmcnt(8)
	v_mfma_f32_16x16x32_bf16 v[90:93], v[182:185], v[158:161], v[90:93]
	v_add_f32_e32 v251, v137, v251
	ds_read_b64_tr_b16 v[214:215], v241 offset:16384
	ds_read_b64_tr_b16 v[216:217], v241 offset:20480
	v_mfma_f32_16x16x32_bf16 v[94:97], v[182:185], v[174:177], v[94:97]
	v_add_f32_e32 v251, v142, v251
	v_add_f32_e32 v251, v143, v251
	s_waitcnt lgkmcnt(7)
	v_mfma_f32_16x16x32_bf16 v[98:101], v[186:189], v[158:161], v[98:101]
	v_add_f32_e32 v251, v144, v251
	ds_read_b64_tr_b16 v[218:219], v242 offset:16384
	ds_read_b64_tr_b16 v[220:221], v242 offset:20480
	v_mfma_f32_16x16x32_bf16 v[102:105], v[186:189], v[174:177], v[102:105]
	v_add_f32_e32 v251, v145, v251
	v_cvt_pk_bf16_f32 v134, v134, v135
	s_waitcnt lgkmcnt(6)
	v_mfma_f32_16x16x32_bf16 v[106:109], v[190:193], v[158:161], v[106:109]
	v_cvt_pk_bf16_f32 v135, v136, v137
	ds_read_b64_tr_b16 v[222:223], v243 offset:16384
	ds_read_b64_tr_b16 v[224:225], v243 offset:20480
	v_mfma_f32_16x16x32_bf16 v[110:113], v[190:193], v[174:177], v[110:113]
	v_cvt_pk_bf16_f32 v136, v142, v143
	v_cvt_pk_bf16_f32 v137, v144, v145
	v_mfma_f32_16x16x32_bf16 v[18:21], v[202:205], v[114:117], v[18:21]
	v_exp_f32_e32 v82, v82
	v_mfma_f32_16x16x32_bf16 v[22:25], v[202:205], v[118:121], v[22:25]
	ds_read_b64_tr_b16 v[202:203], v244 offset:16384
	ds_read_b64_tr_b16 v[204:205], v244 offset:20480
	v_exp_f32_e32 v83, v83
	v_mfma_f32_16x16x32_bf16 v[26:29], v[206:209], v[114:117], v[26:29]
	v_exp_f32_e32 v84, v84
	v_mfma_f32_16x16x32_bf16 v[30:33], v[206:209], v[118:121], v[30:33]
	ds_read_b64_tr_b16 v[206:207], v245 offset:16384
	ds_read_b64_tr_b16 v[208:209], v245 offset:20480
	v_exp_f32_e32 v85, v85
	s_waitcnt lgkmcnt(10)
; #define SBAR() __builtin_amdgcn_sched_barrier(0)
; template <typename TQ> ...
;     ...
;   SBAR(); qkt(pB0, pB1, (bf16*)((char*)K_lds + SHM_K), qr, r32, hi, negm);
;   finishSM(pA0, pA1, l_reg, pa0, pa1, pa2, pa3); SBAR();
;   pv_d0(o, vb0, pa0, pa1, pa2, pa3); partialSM(pB0, pB1, mC);
;   __syncthreads();
;   finishSM(pB0, pB1, l_reg, pa0, pa1, pa2, pa3); SBAR();
;   pv_d0(o, vb0 + (int)SHM_V, pa0, pa1, pa2, pa3);
	v_mfma_f32_16x16x32_bf16 v[34:37], v[210:213], v[114:117], v[34:37]
	v_exp_f32_e32 v86, v86
	v_mfma_f32_16x16x32_bf16 v[38:41], v[210:213], v[118:121], v[38:41]
	ds_read_b64_tr_b16 v[210:211], v238 offset:24576
	ds_read_b64_tr_b16 v[212:213], v238 offset:28672
	v_exp_f32_e32 v87, v87
	s_waitcnt lgkmcnt(10)
	v_mfma_f32_16x16x32_bf16 v[42:45], v[214:217], v[114:117], v[42:45]
	v_exp_f32_e32 v88, v88
	v_mfma_f32_16x16x32_bf16 v[46:49], v[214:217], v[118:121], v[46:49]
	ds_read_b64_tr_b16 v[214:215], v239 offset:24576
	ds_read_b64_tr_b16 v[216:217], v239 offset:28672
	v_exp_f32_e32 v89, v89
	s_waitcnt lgkmcnt(10)
	v_mfma_f32_16x16x32_bf16 v[50:53], v[218:221], v[114:117], v[50:53]
	v_exp_f32_e32 v90, v90
	v_mfma_f32_16x16x32_bf16 v[54:57], v[218:221], v[118:121], v[54:57]
	ds_read_b64_tr_b16 v[218:219], v240 offset:24576
	ds_read_b64_tr_b16 v[220:221], v240 offset:28672
	v_exp_f32_e32 v91, v91
	s_waitcnt lgkmcnt(10)
	v_mfma_f32_16x16x32_bf16 v[58:61], v[222:225], v[114:117], v[58:61]
	v_exp_f32_e32 v92, v92
	v_mfma_f32_16x16x32_bf16 v[62:65], v[222:225], v[118:121], v[62:65]
	ds_read_b64_tr_b16 v[222:223], v241 offset:24576
	ds_read_b64_tr_b16 v[224:225], v241 offset:28672
	v_exp_f32_e32 v93, v93
	s_waitcnt lgkmcnt(10)
	v_mfma_f32_16x16x32_bf16 v[66:69], v[202:205], v[114:117], v[66:69]
	v_exp_f32_e32 v94, v94
	v_mfma_f32_16x16x32_bf16 v[70:73], v[202:205], v[118:121], v[70:73]
	ds_read_b64_tr_b16 v[202:203], v242 offset:24576
	ds_read_b64_tr_b16 v[204:205], v242 offset:28672
	v_exp_f32_e32 v95, v95
	s_waitcnt lgkmcnt(10)
	v_mfma_f32_16x16x32_bf16 v[74:77], v[206:209], v[114:117], v[74:77]
	v_exp_f32_e32 v96, v96
	v_mfma_f32_16x16x32_bf16 v[78:81], v[206:209], v[118:121], v[78:81]
	ds_read_b64_tr_b16 v[206:207], v243 offset:24576
	ds_read_b64_tr_b16 v[208:209], v243 offset:28672
	v_exp_f32_e32 v97, v97
	s_waitcnt lgkmcnt(10)
	v_mfma_f32_16x16x32_bf16 v[18:21], v[210:213], v[130:133], v[18:21]
	v_exp_f32_e32 v98, v98
	v_mfma_f32_16x16x32_bf16 v[22:25], v[210:213], v[134:137], v[22:25]
	ds_read_b64_tr_b16 v[210:211], v244 offset:24576
	ds_read_b64_tr_b16 v[212:213], v244 offset:28672
	v_exp_f32_e32 v99, v99
	s_waitcnt lgkmcnt(10)
	v_mfma_f32_16x16x32_bf16 v[26:29], v[214:217], v[130:133], v[26:29]
	v_exp_f32_e32 v100, v100
	v_mfma_f32_16x16x32_bf16 v[30:33], v[214:217], v[134:137], v[30:33]
	ds_read_b64_tr_b16 v[214:215], v245 offset:24576
	ds_read_b64_tr_b16 v[216:217], v245 offset:28672
	v_exp_f32_e32 v101, v101
	s_waitcnt lgkmcnt(10)
	v_mfma_f32_16x16x32_bf16 v[34:37], v[218:221], v[130:133], v[34:37]
	v_exp_f32_e32 v102, v102
	v_mfma_f32_16x16x32_bf16 v[38:41], v[218:221], v[134:137], v[38:41]
	v_exp_f32_e32 v103, v103
	s_waitcnt lgkmcnt(8)
	v_mfma_f32_16x16x32_bf16 v[42:45], v[222:225], v[130:133], v[42:45]
	v_exp_f32_e32 v104, v104
	v_mfma_f32_16x16x32_bf16 v[46:49], v[222:225], v[134:137], v[46:49]
	v_exp_f32_e32 v105, v105
	s_waitcnt lgkmcnt(6)
	v_mfma_f32_16x16x32_bf16 v[50:53], v[202:205], v[130:133], v[50:53]
	v_exp_f32_e32 v106, v106
	ds_read_b128 v[178:181], v234 offset:49152
	v_mfma_f32_16x16x32_bf16 v[54:57], v[202:205], v[134:137], v[54:57]
	v_exp_f32_e32 v107, v107
	s_waitcnt lgkmcnt(5)
	v_mfma_f32_16x16x32_bf16 v[58:61], v[206:209], v[130:133], v[58:61]
	v_exp_f32_e32 v108, v108
	ds_read_b128 v[182:185], v234 offset:53248
	v_mfma_f32_16x16x32_bf16 v[62:65], v[206:209], v[134:137], v[62:65]
	v_exp_f32_e32 v109, v109
	s_waitcnt lgkmcnt(4)
	v_mfma_f32_16x16x32_bf16 v[66:69], v[210:213], v[130:133], v[66:69]
	v_exp_f32_e32 v110, v110
	ds_read_b128 v[186:189], v234 offset:57344
	v_mfma_f32_16x16x32_bf16 v[70:73], v[210:213], v[134:137], v[70:73]
	v_exp_f32_e32 v111, v111
	s_waitcnt lgkmcnt(3)
	v_mfma_f32_16x16x32_bf16 v[74:77], v[214:217], v[130:133], v[74:77]
	v_exp_f32_e32 v112, v112
	ds_read_b128 v[190:193], v234 offset:61440
	v_mfma_f32_16x16x32_bf16 v[78:81], v[214:217], v[134:137], v[78:81]
	v_exp_f32_e32 v113, v113
	s_waitcnt vmcnt(0)
	s_barrier
	s_waitcnt lgkmcnt(3)
	v_mfma_f32_16x16x32_bf16 v[114:117], v[178:181], v[146:149], v[2:5]
	v_add_f32_e32 v250, v82, v250
	v_mfma_f32_16x16x32_bf16 v[118:121], v[178:181], v[162:165], v[2:5]
	ds_read_b128 v[178:181], v235 offset:49152
	v_add_f32_e32 v250, v83, v250
	v_add_f32_e32 v250, v84, v250
	s_waitcnt lgkmcnt(3)
	v_mfma_f32_16x16x32_bf16 v[122:125], v[182:185], v[146:149], v[2:5]
	v_add_f32_e32 v250, v85, v250
	v_mfma_f32_16x16x32_bf16 v[126:129], v[182:185], v[162:165], v[2:5]
	ds_read_b128 v[182:185], v235 offset:53248
	v_add_f32_e32 v250, v90, v250
	v_add_f32_e32 v250, v91, v250
	s_waitcnt lgkmcnt(3)
	v_mfma_f32_16x16x32_bf16 v[130:133], v[186:189], v[146:149], v[2:5]
	v_add_f32_e32 v250, v92, v250
	v_mfma_f32_16x16x32_bf16 v[134:137], v[186:189], v[162:165], v[2:5]
	ds_read_b128 v[186:189], v235 offset:57344
	v_add_f32_e32 v250, v93, v250
	v_cvt_pk_bf16_f32 v82, v82, v83
	s_waitcnt lgkmcnt(3)
	v_mfma_f32_16x16x32_bf16 v[138:141], v[190:193], v[146:149], v[2:5]
	v_cvt_pk_bf16_f32 v83, v84, v85
	v_mfma_f32_16x16x32_bf16 v[142:145], v[190:193], v[162:165], v[2:5]
	ds_read_b128 v[190:193], v235 offset:61440
	v_cvt_pk_bf16_f32 v84, v90, v91
	v_cvt_pk_bf16_f32 v85, v92, v93
	s_waitcnt lgkmcnt(3)
	v_mfma_f32_16x16x32_bf16 v[114:117], v[178:181], v[150:153], v[114:117]
	v_add_f32_e32 v251, v86, v251
	v_mfma_f32_16x16x32_bf16 v[118:121], v[178:181], v[166:169], v[118:121]
	ds_read_b128 v[178:181], v236 offset:49152
	v_add_f32_e32 v251, v87, v251
	v_add_f32_e32 v251, v88, v251
	s_waitcnt lgkmcnt(3)
	v_mfma_f32_16x16x32_bf16 v[122:125], v[182:185], v[150:153], v[122:125]
	v_add_f32_e32 v251, v89, v251
	v_mfma_f32_16x16x32_bf16 v[126:129], v[182:185], v[166:169], v[126:129]
	ds_read_b128 v[182:185], v236 offset:53248
	v_add_f32_e32 v251, v94, v251
	v_add_f32_e32 v251, v95, v251
	s_waitcnt lgkmcnt(3)
; #define SBAR() __builtin_amdgcn_sched_barrier(0)
; __device__ __forceinline__ void finishSM(f32x16& p0, f32x16& p1, float& l_reg, bf16x8& pa0, bf16x8& pa1, bf16x8& pa2, bf16x8& pa3) {
;   for (int r = 0; r < 16; ++r) p1[r] = __builtin_amdgcn_exp2f(p1[r]);
;   float ps = 0; for (int r = 0; r < 16; ++r) ps += p0[r]; for (int r = 0; r < 16; ++r) ps += p1[r];
;   { auto rr = __builtin_amdgcn_permlane32_swap(__float_as_uint(ps), __float_as_uint(ps), false, false);
;     ps = __uint_as_float(rr[0]) + __uint_as_float(rr[1]); }
;   l_reg += ps;
;     ...
;   PK4(p0, 0, pa0); PK4(p0, 8, pa1); PK4(p1, 0, pa2); PK4(p1, 8, pa3);
;     ...
; }
; __device__ __forceinline__ void qkt(f32x16& p0, f32x16& p1, const bf16* Ks, const bf16x8* qr, int r32, int hi, const f32x16& negm) {
; #pragma unroll
;   for (int d0 = 0; d0 < 8; ++d0) { int cb = (d0 * 16 + hi * 8) * 2;
;     bf16x8 b0 = *reinterpret_cast<const bf16x8*>((const char*)Ks + KSWZ(r32, cb));
;     bf16x8 b1 = *reinterpret_cast<const bf16x8*>((const char*)Ks + KSWZ(32 + r32, cb));
;     if (d0 == 0) { p0 = __builtin_amdgcn_mfma_f32_32x32x16_bf16(b0, qr[0], negm, 0, 0, 0); p1 = __builtin_amdgcn_mfma_f32_32x32x16_bf16(b1, qr[0], negm, 0, 0, 0); }
;     else { p0 = __builtin_amdgcn_mfma_f32_32x32x16_bf16(b0, qr[d0], p0, 0, 0, 0); p1 = __builtin_amdgcn_mfma_f32_32x32x16_bf16(b1, qr[d0], p1, 0, 0, 0); } }
; template <typename TQ> ...
;     ...
;   SBAR(); qkt(pB0, pB1, (bf16*)((char*)K_lds + SHM_K), qr, r32, hi, negm);
;   finishSM(pA0, pA1, l_reg, pa0, pa1, pa2, pa3); SBAR();
;   pv_d0(o, vb0, pa0, pa1, pa2, pa3); partialSM(pB0, pB1, mC);
	v_mfma_f32_16x16x32_bf16 v[130:133], v[186:189], v[150:153], v[130:133]
	v_add_f32_e32 v251, v96, v251
	v_mfma_f32_16x16x32_bf16 v[134:137], v[186:189], v[166:169], v[134:137]
	ds_read_b128 v[186:189], v236 offset:57344
	v_add_f32_e32 v251, v97, v251
	v_cvt_pk_bf16_f32 v86, v86, v87
	s_waitcnt lgkmcnt(3)
	v_mfma_f32_16x16x32_bf16 v[138:141], v[190:193], v[150:153], v[138:141]
	v_cvt_pk_bf16_f32 v87, v88, v89
	v_mfma_f32_16x16x32_bf16 v[142:145], v[190:193], v[166:169], v[142:145]
	ds_read_b128 v[190:193], v236 offset:61440
	v_cvt_pk_bf16_f32 v88, v94, v95
	v_cvt_pk_bf16_f32 v89, v96, v97
	s_waitcnt lgkmcnt(3)
	v_mfma_f32_16x16x32_bf16 v[114:117], v[178:181], v[154:157], v[114:117]
	v_add_f32_e32 v250, v98, v250
	v_mfma_f32_16x16x32_bf16 v[118:121], v[178:181], v[170:173], v[118:121]
	ds_read_b128 v[178:181], v237 offset:49152
	v_add_f32_e32 v250, v99, v250
	v_add_f32_e32 v250, v100, v250
	s_waitcnt lgkmcnt(3)
	v_mfma_f32_16x16x32_bf16 v[122:125], v[182:185], v[154:157], v[122:125]
	v_add_f32_e32 v250, v101, v250
	v_mfma_f32_16x16x32_bf16 v[126:129], v[182:185], v[170:173], v[126:129]
	ds_read_b128 v[182:185], v237 offset:53248
	v_add_f32_e32 v250, v106, v250
	v_add_f32_e32 v250, v107, v250
	s_waitcnt lgkmcnt(3)
	v_mfma_f32_16x16x32_bf16 v[130:133], v[186:189], v[154:157], v[130:133]
	v_add_f32_e32 v250, v108, v250
	ds_read_b64_tr_b16 v[202:203], v238 offset:32768
	ds_read_b64_tr_b16 v[204:205], v238 offset:36864
	v_mfma_f32_16x16x32_bf16 v[134:137], v[186:189], v[170:173], v[134:137]
	ds_read_b128 v[186:189], v237 offset:57344
	v_add_f32_e32 v250, v109, v250
	v_cvt_pk_bf16_f32 v98, v98, v99
	s_waitcnt lgkmcnt(5)
	v_mfma_f32_16x16x32_bf16 v[138:141], v[190:193], v[154:157], v[138:141]
	v_cvt_pk_bf16_f32 v99, v100, v101
	ds_read_b64_tr_b16 v[206:207], v239 offset:32768
	ds_read_b64_tr_b16 v[208:209], v239 offset:36864
	v_mfma_f32_16x16x32_bf16 v[142:145], v[190:193], v[170:173], v[142:145]
	ds_read_b128 v[190:193], v237 offset:61440
	v_cvt_pk_bf16_f32 v100, v106, v107
	v_cvt_pk_bf16_f32 v101, v108, v109
	s_waitcnt lgkmcnt(7)
	v_mfma_f32_16x16x32_bf16 v[114:117], v[178:181], v[158:161], v[114:117]
	v_add_f32_e32 v251, v102, v251
	ds_read_b64_tr_b16 v[210:211], v240 offset:32768
	ds_read_b64_tr_b16 v[212:213], v240 offset:36864
	v_mfma_f32_16x16x32_bf16 v[118:121], v[178:181], v[174:177], v[118:121]
	v_add_f32_e32 v251, v103, v251
	v_add_f32_e32 v251, v104, v251
	s_waitcnt lgkmcnt(8)
	v_mfma_f32_16x16x32_bf16 v[122:125], v[182:185], v[158:161], v[122:125]
	v_add_f32_e32 v251, v105, v251
	ds_read_b64_tr_b16 v[214:215], v241 offset:32768
	ds_read_b64_tr_b16 v[216:217], v241 offset:36864
	v_mfma_f32_16x16x32_bf16 v[126:129], v[182:185], v[174:177], v[126:129]
	v_add_f32_e32 v251, v110, v251
	v_add_f32_e32 v251, v111, v251
	s_waitcnt lgkmcnt(7)
	v_mfma_f32_16x16x32_bf16 v[130:133], v[186:189], v[158:161], v[130:133]
	v_add_f32_e32 v251, v112, v251
	ds_read_b64_tr_b16 v[218:219], v242 offset:32768
	ds_read_b64_tr_b16 v[220:221], v242 offset:36864
	v_mfma_f32_16x16x32_bf16 v[134:137], v[186:189], v[174:177], v[134:137]
	v_add_f32_e32 v251, v113, v251
	v_cvt_pk_bf16_f32 v102, v102, v103
	s_waitcnt lgkmcnt(6)
	v_mfma_f32_16x16x32_bf16 v[138:141], v[190:193], v[158:161], v[138:141]
	v_cvt_pk_bf16_f32 v103, v104, v105
	ds_read_b64_tr_b16 v[222:223], v243 offset:32768
	ds_read_b64_tr_b16 v[224:225], v243 offset:36864
	v_mfma_f32_16x16x32_bf16 v[142:145], v[190:193], v[174:177], v[142:145]
	v_cvt_pk_bf16_f32 v104, v110, v111
	v_cvt_pk_bf16_f32 v105, v112, v113
	v_mfma_f32_16x16x32_bf16 v[18:21], v[202:205], v[82:85], v[18:21]
	v_exp_f32_e32 v114, v114
	v_mfma_f32_16x16x32_bf16 v[22:25], v[202:205], v[86:89], v[22:25]
	ds_read_b64_tr_b16 v[202:203], v244 offset:32768
	ds_read_b64_tr_b16 v[204:205], v244 offset:36864
	v_exp_f32_e32 v115, v115
	v_mfma_f32_16x16x32_bf16 v[26:29], v[206:209], v[82:85], v[26:29]
	v_exp_f32_e32 v116, v116
	v_mfma_f32_16x16x32_bf16 v[30:33], v[206:209], v[86:89], v[30:33]
	ds_read_b64_tr_b16 v[206:207], v245 offset:32768
	ds_read_b64_tr_b16 v[208:209], v245 offset:36864
	v_exp_f32_e32 v117, v117
	s_waitcnt lgkmcnt(10)
	v_mfma_f32_16x16x32_bf16 v[34:37], v[210:213], v[82:85], v[34:37]
	v_exp_f32_e32 v118, v118
	v_mfma_f32_16x16x32_bf16 v[38:41], v[210:213], v[86:89], v[38:41]
	ds_read_b64_tr_b16 v[210:211], v238 offset:40960
	ds_read_b64_tr_b16 v[212:213], v238 offset:45056
	v_exp_f32_e32 v119, v119
	s_waitcnt lgkmcnt(10)
	v_mfma_f32_16x16x32_bf16 v[42:45], v[214:217], v[82:85], v[42:45]
	v_exp_f32_e32 v120, v120
	v_mfma_f32_16x16x32_bf16 v[46:49], v[214:217], v[86:89], v[46:49]
	ds_read_b64_tr_b16 v[214:215], v239 offset:40960
	ds_read_b64_tr_b16 v[216:217], v239 offset:45056
	v_exp_f32_e32 v121, v121
	s_waitcnt lgkmcnt(10)
	v_mfma_f32_16x16x32_bf16 v[50:53], v[218:221], v[82:85], v[50:53]
	v_exp_f32_e32 v122, v122
	v_mfma_f32_16x16x32_bf16 v[54:57], v[218:221], v[86:89], v[54:57]
	ds_read_b64_tr_b16 v[218:219], v240 offset:40960
	ds_read_b64_tr_b16 v[220:221], v240 offset:45056
	v_exp_f32_e32 v123, v123
	s_waitcnt lgkmcnt(10)
	v_mfma_f32_16x16x32_bf16 v[58:61], v[222:225], v[82:85], v[58:61]
	v_exp_f32_e32 v124, v124
	v_mfma_f32_16x16x32_bf16 v[62:65], v[222:225], v[86:89], v[62:65]
	ds_read_b64_tr_b16 v[222:223], v241 offset:40960
	ds_read_b64_tr_b16 v[224:225], v241 offset:45056
	v_exp_f32_e32 v125, v125
	s_waitcnt lgkmcnt(10)
	v_mfma_f32_16x16x32_bf16 v[66:69], v[202:205], v[82:85], v[66:69]
	v_exp_f32_e32 v126, v126
	v_mfma_f32_16x16x32_bf16 v[70:73], v[202:205], v[86:89], v[70:73]
	ds_read_b64_tr_b16 v[202:203], v242 offset:40960
	ds_read_b64_tr_b16 v[204:205], v242 offset:45056
	v_exp_f32_e32 v127, v127
	s_waitcnt lgkmcnt(10)
; #define SBAR() __builtin_amdgcn_sched_barrier(0)
; __device__ __forceinline__ void finishSM(f32x16& p0, f32x16& p1, float& l_reg, bf16x8& pa0, bf16x8& pa1, bf16x8& pa2, bf16x8& pa3) {
;   for (int r = 0; r < 16; ++r) p1[r] = __builtin_amdgcn_exp2f(p1[r]);
;   float ps = 0; for (int r = 0; r < 16; ++r) ps += p0[r]; for (int r = 0; r < 16; ++r) ps += p1[r];
;   { auto rr = __builtin_amdgcn_permlane32_swap(__float_as_uint(ps), __float_as_uint(ps), false, false);
;     ps = __uint_as_float(rr[0]) + __uint_as_float(rr[1]); }
;   l_reg += ps;
;     ...
;   PK4(p0, 0, pa0); PK4(p0, 8, pa1); PK4(p1, 0, pa2); PK4(p1, 8, pa3);
;     ...
; }
; template <typename TQ> ...
;     ...
;   pv_d0(o, vb0, pa0, pa1, pa2, pa3); partialSM(pB0, pB1, mC);
;   __syncthreads();
;   finishSM(pB0, pB1, l_reg, pa0, pa1, pa2, pa3); SBAR();
;   pv_d0(o, vb0 + (int)SHM_V, pa0, pa1, pa2, pa3);
	v_mfma_f32_16x16x32_bf16 v[74:77], v[206:209], v[82:85], v[74:77]
	v_exp_f32_e32 v128, v128
	v_mfma_f32_16x16x32_bf16 v[78:81], v[206:209], v[86:89], v[78:81]
	ds_read_b64_tr_b16 v[206:207], v243 offset:40960
	ds_read_b64_tr_b16 v[208:209], v243 offset:45056
	v_exp_f32_e32 v129, v129
	s_waitcnt lgkmcnt(10)
	v_mfma_f32_16x16x32_bf16 v[18:21], v[210:213], v[98:101], v[18:21]
	v_exp_f32_e32 v130, v130
	v_mfma_f32_16x16x32_bf16 v[22:25], v[210:213], v[102:105], v[22:25]
	ds_read_b64_tr_b16 v[210:211], v244 offset:40960
	ds_read_b64_tr_b16 v[212:213], v244 offset:45056
	v_exp_f32_e32 v131, v131
	s_waitcnt lgkmcnt(10)
	v_mfma_f32_16x16x32_bf16 v[26:29], v[214:217], v[98:101], v[26:29]
	v_exp_f32_e32 v132, v132
	v_mfma_f32_16x16x32_bf16 v[30:33], v[214:217], v[102:105], v[30:33]
	ds_read_b64_tr_b16 v[214:215], v245 offset:40960
	ds_read_b64_tr_b16 v[216:217], v245 offset:45056
	v_exp_f32_e32 v133, v133
	s_waitcnt lgkmcnt(10)
	v_mfma_f32_16x16x32_bf16 v[34:37], v[218:221], v[98:101], v[34:37]
	v_exp_f32_e32 v134, v134
	v_mfma_f32_16x16x32_bf16 v[38:41], v[218:221], v[102:105], v[38:41]
	v_exp_f32_e32 v135, v135
	s_waitcnt lgkmcnt(8)
	v_mfma_f32_16x16x32_bf16 v[42:45], v[222:225], v[98:101], v[42:45]
	v_exp_f32_e32 v136, v136
	v_mfma_f32_16x16x32_bf16 v[46:49], v[222:225], v[102:105], v[46:49]
	v_exp_f32_e32 v137, v137
	s_waitcnt lgkmcnt(6)
	v_mfma_f32_16x16x32_bf16 v[50:53], v[202:205], v[98:101], v[50:53]
	v_exp_f32_e32 v138, v138
	v_mfma_f32_16x16x32_bf16 v[54:57], v[202:205], v[102:105], v[54:57]
	v_exp_f32_e32 v139, v139
	s_waitcnt lgkmcnt(4)
	v_mfma_f32_16x16x32_bf16 v[58:61], v[206:209], v[98:101], v[58:61]
	v_exp_f32_e32 v140, v140
	v_mfma_f32_16x16x32_bf16 v[62:65], v[206:209], v[102:105], v[62:65]
	v_exp_f32_e32 v141, v141
	s_waitcnt lgkmcnt(2)
	v_mfma_f32_16x16x32_bf16 v[66:69], v[210:213], v[98:101], v[66:69]
	v_exp_f32_e32 v142, v142
	v_mfma_f32_16x16x32_bf16 v[70:73], v[210:213], v[102:105], v[70:73]
	v_exp_f32_e32 v143, v143
	s_waitcnt lgkmcnt(0)
	v_mfma_f32_16x16x32_bf16 v[74:77], v[214:217], v[98:101], v[74:77]
	v_exp_f32_e32 v144, v144
	v_mfma_f32_16x16x32_bf16 v[78:81], v[214:217], v[102:105], v[78:81]
	v_exp_f32_e32 v145, v145
	s_waitcnt vmcnt(0)
	v_add_f32_e32 v250, v114, v250
	v_add_f32_e32 v250, v115, v250
	v_add_f32_e32 v250, v116, v250
	v_add_f32_e32 v250, v117, v250
	v_add_f32_e32 v250, v122, v250
	v_add_f32_e32 v250, v123, v250
	v_add_f32_e32 v250, v124, v250
	v_add_f32_e32 v250, v125, v250
	v_cvt_pk_bf16_f32 v114, v114, v115
	v_cvt_pk_bf16_f32 v115, v116, v117
	v_cvt_pk_bf16_f32 v116, v122, v123
	v_cvt_pk_bf16_f32 v117, v124, v125
	v_add_f32_e32 v251, v118, v251
	v_add_f32_e32 v251, v119, v251
	v_add_f32_e32 v251, v120, v251
	v_add_f32_e32 v251, v121, v251
	v_add_f32_e32 v251, v126, v251
	v_add_f32_e32 v251, v127, v251
	v_add_f32_e32 v251, v128, v251
	v_add_f32_e32 v251, v129, v251
	v_cvt_pk_bf16_f32 v118, v118, v119
	v_cvt_pk_bf16_f32 v119, v120, v121
	v_cvt_pk_bf16_f32 v120, v126, v127
	v_cvt_pk_bf16_f32 v121, v128, v129
	v_add_f32_e32 v250, v130, v250
	v_add_f32_e32 v250, v131, v250
	v_add_f32_e32 v250, v132, v250
	v_add_f32_e32 v250, v133, v250
	v_add_f32_e32 v250, v138, v250
	v_add_f32_e32 v250, v139, v250
	v_add_f32_e32 v250, v140, v250
	v_add_f32_e32 v250, v141, v250
	v_cvt_pk_bf16_f32 v130, v130, v131
	v_cvt_pk_bf16_f32 v131, v132, v133
	v_cvt_pk_bf16_f32 v132, v138, v139
	v_cvt_pk_bf16_f32 v133, v140, v141
	v_add_f32_e32 v251, v134, v251
	v_add_f32_e32 v251, v135, v251
	v_add_f32_e32 v251, v136, v251
	v_add_f32_e32 v251, v137, v251
	v_add_f32_e32 v251, v142, v251
	v_add_f32_e32 v251, v143, v251
	v_add_f32_e32 v251, v144, v251
	v_add_f32_e32 v251, v145, v251
	v_cvt_pk_bf16_f32 v134, v134, v135
	v_cvt_pk_bf16_f32 v135, v136, v137
	v_cvt_pk_bf16_f32 v136, v142, v143
	v_cvt_pk_bf16_f32 v137, v144, v145
	ds_read_b64_tr_b16 v[202:203], v238 offset:49152
	ds_read_b64_tr_b16 v[204:205], v238 offset:53248
	ds_read_b64_tr_b16 v[206:207], v239 offset:49152
	ds_read_b64_tr_b16 v[208:209], v239 offset:53248
	ds_read_b64_tr_b16 v[210:211], v240 offset:49152
	ds_read_b64_tr_b16 v[212:213], v240 offset:53248
	ds_read_b64_tr_b16 v[214:215], v241 offset:49152
	ds_read_b64_tr_b16 v[216:217], v241 offset:53248
	ds_read_b64_tr_b16 v[218:219], v242 offset:49152
	ds_read_b64_tr_b16 v[220:221], v242 offset:53248
	ds_read_b64_tr_b16 v[222:223], v243 offset:49152
	ds_read_b64_tr_b16 v[224:225], v243 offset:53248
	s_waitcnt lgkmcnt(10)
	v_mfma_f32_16x16x32_bf16 v[18:21], v[202:205], v[114:117], v[18:21]
	v_mfma_f32_16x16x32_bf16 v[22:25], v[202:205], v[118:121], v[22:25]
	ds_read_b64_tr_b16 v[202:203], v244 offset:49152
	ds_read_b64_tr_b16 v[204:205], v244 offset:53248
	s_waitcnt lgkmcnt(10)
	v_mfma_f32_16x16x32_bf16 v[26:29], v[206:209], v[114:117], v[26:29]
	v_mfma_f32_16x16x32_bf16 v[30:33], v[206:209], v[118:121], v[30:33]
	ds_read_b64_tr_b16 v[206:207], v245 offset:49152
	ds_read_b64_tr_b16 v[208:209], v245 offset:53248
	s_waitcnt lgkmcnt(10)
	v_mfma_f32_16x16x32_bf16 v[34:37], v[210:213], v[114:117], v[34:37]
	v_mfma_f32_16x16x32_bf16 v[38:41], v[210:213], v[118:121], v[38:41]
	ds_read_b64_tr_b16 v[210:211], v238 offset:57344
	ds_read_b64_tr_b16 v[212:213], v238 offset:61440
	s_waitcnt lgkmcnt(10)
	v_mfma_f32_16x16x32_bf16 v[42:45], v[214:217], v[114:117], v[42:45]
	v_mfma_f32_16x16x32_bf16 v[46:49], v[214:217], v[118:121], v[46:49]
	ds_read_b64_tr_b16 v[214:215], v239 offset:57344
	ds_read_b64_tr_b16 v[216:217], v239 offset:61440
	s_waitcnt lgkmcnt(10)
	v_mfma_f32_16x16x32_bf16 v[50:53], v[218:221], v[114:117], v[50:53]
	v_mfma_f32_16x16x32_bf16 v[54:57], v[218:221], v[118:121], v[54:57]
	ds_read_b64_tr_b16 v[218:219], v240 offset:57344
	ds_read_b64_tr_b16 v[220:221], v240 offset:61440
	s_waitcnt lgkmcnt(10)
; #define SBAR() __builtin_amdgcn_sched_barrier(0)
; __device__ __forceinline__ int crow(int r, int hi) { return (r & 3) + 8 * (r >> 2) + 4 * hi; }
; template <int D0> __device__ __forceinline__ void pv_one(f32x16& od, int vb, bf16x8 pa0, bf16x8 pa1, bf16x8 pa2, bf16x8 pa3) {
;   const s16x4 l0 = tr_read<v_rd_off(D0, 0, 0)>(vb), h0 = tr_read<v_rd_off(D0, 0, 1)>(vb), l1 = tr_read<v_rd_off(D0, 1, 0)>(vb), h1 = tr_read<v_rd_off(D0, 1, 1)>(vb);
;   const s16x4 l2 = tr_read<v_rd_off(D0, 2, 0)>(vb), h2 = tr_read<v_rd_off(D0, 2, 1)>(vb), l3 = tr_read<v_rd_off(D0, 3, 0)>(vb), h3 = tr_read<v_rd_off(D0, 3, 1)>(vb);
;   asm volatile("s_waitcnt lgkmcnt(0)" ::: "memory"); SBAR();
;     ...
;   od = __builtin_amdgcn_mfma_f32_32x32x16_bf16(pa0, PK(l0, h0), od, 0, 0, 0);
;   od = __builtin_amdgcn_mfma_f32_32x32x16_bf16(pa1, PK(l1, h1), od, 0, 0, 0);
;   od = __builtin_amdgcn_mfma_f32_32x32x16_bf16(pa2, PK(l2, h2), od, 0, 0, 0);
;   od = __builtin_amdgcn_mfma_f32_32x32x16_bf16(pa3, PK(l3, h3), od, 0, 0, 0);
;     ...
; }
; __device__ __forceinline__ void pv_d0(f32x16* o, int vb, bf16x8 pa0, bf16x8 pa1, bf16x8 pa2, bf16x8 pa3) {
;   pv_one<0>(o[0], vb, pa0, pa1, pa2, pa3); pv_one<1>(o[1], vb, pa0, pa1, pa2, pa3); pv_one<2>(o[2], vb, pa0, pa1, pa2, pa3); pv_one<3>(o[3], vb, pa0, pa1, pa2, pa3);
; template <typename TQ> ...
;     ...
;   pv_d0(o, vb0 + (int)SHM_V, pa0, pa1, pa2, pa3);
;   if (hi == 0) li_l[r32] = l_reg; asm volatile("s_waitcnt lgkmcnt(0)" ::: "memory");
;   float rli[16];
; #pragma unroll
;   for (int r = 0; r < 16; ++r) rli[r] = __builtin_amdgcn_rcpf(li_l[crow(r, hi)]);
;   int le = (int)(threadIdx.x & 63u); asm volatile("" : "+v"(le));
;   const int r32e = le & 31, hie = le >> 5;
;   bf16* Ow = Ob + (long)(wid * QBLK) * LDO;
; #pragma unroll
;   for (int r = 0; r < 16; ++r) { int orow = crow(r, hie);
;     for (int d0 = 0; d0 < 4; ++d0) Ow[(long)orow * LDO + d0 * 32 + r32e] = __float2bfloat16(o[d0][r] * rli[r]); }
	v_mfma_f32_16x16x32_bf16 v[58:61], v[222:225], v[114:117], v[58:61]
	v_mfma_f32_16x16x32_bf16 v[62:65], v[222:225], v[118:121], v[62:65]
	ds_read_b64_tr_b16 v[222:223], v241 offset:57344
	ds_read_b64_tr_b16 v[224:225], v241 offset:61440
	s_waitcnt lgkmcnt(10)
	v_mfma_f32_16x16x32_bf16 v[66:69], v[202:205], v[114:117], v[66:69]
	v_mfma_f32_16x16x32_bf16 v[70:73], v[202:205], v[118:121], v[70:73]
	ds_read_b64_tr_b16 v[202:203], v242 offset:57344
	ds_read_b64_tr_b16 v[204:205], v242 offset:61440
	s_waitcnt lgkmcnt(10)
	v_mfma_f32_16x16x32_bf16 v[74:77], v[206:209], v[114:117], v[74:77]
	v_mfma_f32_16x16x32_bf16 v[78:81], v[206:209], v[118:121], v[78:81]
	ds_read_b64_tr_b16 v[206:207], v243 offset:57344
	ds_read_b64_tr_b16 v[208:209], v243 offset:61440
	s_waitcnt lgkmcnt(10)
	v_mfma_f32_16x16x32_bf16 v[18:21], v[210:213], v[130:133], v[18:21]
	v_mfma_f32_16x16x32_bf16 v[22:25], v[210:213], v[134:137], v[22:25]
	ds_read_b64_tr_b16 v[210:211], v244 offset:57344
	ds_read_b64_tr_b16 v[212:213], v244 offset:61440
	s_waitcnt lgkmcnt(10)
	v_mfma_f32_16x16x32_bf16 v[26:29], v[214:217], v[130:133], v[26:29]
	v_mfma_f32_16x16x32_bf16 v[30:33], v[214:217], v[134:137], v[30:33]
	ds_read_b64_tr_b16 v[214:215], v245 offset:57344
	ds_read_b64_tr_b16 v[216:217], v245 offset:61440
	s_waitcnt lgkmcnt(10)
	v_mfma_f32_16x16x32_bf16 v[34:37], v[218:221], v[130:133], v[34:37]
	v_mfma_f32_16x16x32_bf16 v[38:41], v[218:221], v[134:137], v[38:41]
	s_waitcnt lgkmcnt(8)
	v_mfma_f32_16x16x32_bf16 v[42:45], v[222:225], v[130:133], v[42:45]
	v_mfma_f32_16x16x32_bf16 v[46:49], v[222:225], v[134:137], v[46:49]
	s_waitcnt lgkmcnt(6)
	v_mfma_f32_16x16x32_bf16 v[50:53], v[202:205], v[130:133], v[50:53]
	v_mfma_f32_16x16x32_bf16 v[54:57], v[202:205], v[134:137], v[54:57]
	s_waitcnt lgkmcnt(4)
	v_mfma_f32_16x16x32_bf16 v[58:61], v[206:209], v[130:133], v[58:61]
	v_mfma_f32_16x16x32_bf16 v[62:65], v[206:209], v[134:137], v[62:65]
	s_waitcnt lgkmcnt(2)
	v_mfma_f32_16x16x32_bf16 v[66:69], v[210:213], v[130:133], v[66:69]
	v_mfma_f32_16x16x32_bf16 v[70:73], v[210:213], v[134:137], v[70:73]
	s_waitcnt lgkmcnt(0)
	v_mfma_f32_16x16x32_bf16 v[74:77], v[214:217], v[130:133], v[74:77]
	v_mfma_f32_16x16x32_bf16 v[78:81], v[214:217], v[134:137], v[78:81]
	ds_swizzle_b32 v6, v250 offset:swizzle(SWAP,16)
	s_waitcnt lgkmcnt(0)
	v_add_f32_e32 v250, v250, v6
	v_mov_b32_e32 v6, v250
	s_nop 1
	v_permlane32_swap_b32_e32 v250, v6
	v_add_f32_e32 v250, v250, v6
	v_rcp_f32_e32 v250, v250
	ds_swizzle_b32 v6, v251 offset:swizzle(SWAP,16)
	s_waitcnt lgkmcnt(0)
	v_add_f32_e32 v251, v251, v6
	v_mov_b32_e32 v6, v251
	s_nop 1
	v_permlane32_swap_b32_e32 v251, v6
	v_add_f32_e32 v251, v251, v6
	v_rcp_f32_e32 v251, v251
	s_add_u32 s12, s71, s48
	s_addc_u32 s13, s72, s49
	v_add_u32_e32 v13, s52, v16
	v_lshlrev_b32_e32 v13, 11, v13
	v_lshl_or_b32 v7, v17, 3, v13
	v_add_u32_e32 v12, 0x8000, v7
	v_mul_f32_e32 v18, v18, v250
	v_mul_f32_e32 v19, v19, v250
	v_mul_f32_e32 v20, v20, v250
	v_mul_f32_e32 v21, v21, v250
	v_cvt_pk_bf16_f32 v18, v18, v19
	v_cvt_pk_bf16_f32 v19, v20, v21
	global_store_dwordx2 v7, v[18:19], s[12:13] offset:0
	v_mul_f32_e32 v22, v22, v251
	v_mul_f32_e32 v23, v23, v251
	v_mul_f32_e32 v24, v24, v251
	v_mul_f32_e32 v25, v25, v251
	v_cvt_pk_bf16_f32 v22, v22, v23
	v_cvt_pk_bf16_f32 v23, v24, v25
	global_store_dwordx2 v12, v[22:23], s[12:13] offset:0
	v_mul_f32_e32 v26, v26, v250
	v_mul_f32_e32 v27, v27, v250
	v_mul_f32_e32 v28, v28, v250
	v_mul_f32_e32 v29, v29, v250
	v_cvt_pk_bf16_f32 v26, v26, v27
	v_cvt_pk_bf16_f32 v27, v28, v29
	global_store_dwordx2 v7, v[26:27], s[12:13] offset:32
	v_mul_f32_e32 v30, v30, v251
	v_mul_f32_e32 v31, v31, v251
	v_mul_f32_e32 v32, v32, v251
	v_mul_f32_e32 v33, v33, v251
	v_cvt_pk_bf16_f32 v30, v30, v31
	v_cvt_pk_bf16_f32 v31, v32, v33
	global_store_dwordx2 v12, v[30:31], s[12:13] offset:32
	v_mul_f32_e32 v34, v34, v250
	v_mul_f32_e32 v35, v35, v250
	v_mul_f32_e32 v36, v36, v250
	v_mul_f32_e32 v37, v37, v250
	v_cvt_pk_bf16_f32 v34, v34, v35
	v_cvt_pk_bf16_f32 v35, v36, v37
	global_store_dwordx2 v7, v[34:35], s[12:13] offset:64
	v_mul_f32_e32 v38, v38, v251
	v_mul_f32_e32 v39, v39, v251
	v_mul_f32_e32 v40, v40, v251
	v_mul_f32_e32 v41, v41, v251
	v_cvt_pk_bf16_f32 v38, v38, v39
	v_cvt_pk_bf16_f32 v39, v40, v41
	global_store_dwordx2 v12, v[38:39], s[12:13] offset:64
	v_mul_f32_e32 v42, v42, v250
	v_mul_f32_e32 v43, v43, v250
	v_mul_f32_e32 v44, v44, v250
	v_mul_f32_e32 v45, v45, v250
	v_cvt_pk_bf16_f32 v42, v42, v43
	v_cvt_pk_bf16_f32 v43, v44, v45
	global_store_dwordx2 v7, v[42:43], s[12:13] offset:96
	v_mul_f32_e32 v46, v46, v251
	v_mul_f32_e32 v47, v47, v251
	v_mul_f32_e32 v48, v48, v251
	v_mul_f32_e32 v49, v49, v251
	v_cvt_pk_bf16_f32 v46, v46, v47
	v_cvt_pk_bf16_f32 v47, v48, v49
	global_store_dwordx2 v12, v[46:47], s[12:13] offset:96
	v_mul_f32_e32 v50, v50, v250
	v_mul_f32_e32 v51, v51, v250
	v_mul_f32_e32 v52, v52, v250
	v_mul_f32_e32 v53, v53, v250
	v_cvt_pk_bf16_f32 v50, v50, v51
	v_cvt_pk_bf16_f32 v51, v52, v53
	global_store_dwordx2 v7, v[50:51], s[12:13] offset:128
	v_mul_f32_e32 v54, v54, v251
	v_mul_f32_e32 v55, v55, v251
	v_mul_f32_e32 v56, v56, v251
	v_mul_f32_e32 v57, v57, v251
	v_cvt_pk_bf16_f32 v54, v54, v55
	v_cvt_pk_bf16_f32 v55, v56, v57
	global_store_dwordx2 v12, v[54:55], s[12:13] offset:128
	v_mul_f32_e32 v58, v58, v250
	v_mul_f32_e32 v59, v59, v250
	v_mul_f32_e32 v60, v60, v250
	v_mul_f32_e32 v61, v61, v250
	v_cvt_pk_bf16_f32 v58, v58, v59
	v_cvt_pk_bf16_f32 v59, v60, v61
	global_store_dwordx2 v7, v[58:59], s[12:13] offset:160
	v_mul_f32_e32 v62, v62, v251
	v_mul_f32_e32 v63, v63, v251
	v_mul_f32_e32 v64, v64, v251
	v_mul_f32_e32 v65, v65, v251
	v_cvt_pk_bf16_f32 v62, v62, v63
	v_cvt_pk_bf16_f32 v63, v64, v65
	global_store_dwordx2 v12, v[62:63], s[12:13] offset:160
	v_mul_f32_e32 v66, v66, v250
	v_mul_f32_e32 v67, v67, v250
	v_mul_f32_e32 v68, v68, v250
	v_mul_f32_e32 v69, v69, v250
	v_cvt_pk_bf16_f32 v66, v66, v67
	v_cvt_pk_bf16_f32 v67, v68, v69
	global_store_dwordx2 v7, v[66:67], s[12:13] offset:192
	v_mul_f32_e32 v70, v70, v251
	v_mul_f32_e32 v71, v71, v251
	v_mul_f32_e32 v72, v72, v251
	v_mul_f32_e32 v73, v73, v251
	v_cvt_pk_bf16_f32 v70, v70, v71
	v_cvt_pk_bf16_f32 v71, v72, v73
	global_store_dwordx2 v12, v[70:71], s[12:13] offset:192
	v_mul_f32_e32 v74, v74, v250
	v_mul_f32_e32 v75, v75, v250
	v_mul_f32_e32 v76, v76, v250
	v_mul_f32_e32 v77, v77, v250
	v_cvt_pk_bf16_f32 v74, v74, v75
	v_cvt_pk_bf16_f32 v75, v76, v77
	global_store_dwordx2 v7, v[74:75], s[12:13] offset:224
	v_mul_f32_e32 v78, v78, v251
	v_mul_f32_e32 v79, v79, v251
	v_mul_f32_e32 v80, v80, v251
	v_mul_f32_e32 v81, v81, v251
	v_cvt_pk_bf16_f32 v78, v78, v79
	v_cvt_pk_bf16_f32 v79, v80, v81
	global_store_dwordx2 v12, v[78:79], s[12:13] offset:224
	s_add_i32 s74, s74, 1
	s_add_i32 s94, s94, 1
	s_cmp_eq_u32 s74, s66
	s_cselect_b64 s[0:1], -1, 0
	s_barrier
	s_branch .LBB0_818
